# 4-phase GEMM loops with a uniform vmcnt(8) wait at the end of every load segment so each LDS-DMA gets a 4-slot lead
# baseline (speedup 1.0000x reference)
; #define PG8_STAGE(bufoff, gbase, voff) do { _Pragma("unroll") for (int _i = 0; _i < 2; ++_i) \
;         __builtin_amdgcn_global_load_lds((const unsigned*)((const char*)(gbase) + (voff)[_i]), (LAS unsigned*)(lds + (bufoff) + ldsw + _i * 8192), 16, 0, 0); } while (0)
; #define PG8_LDA(dst, b, h) do { _Pragma("unroll") for (int m = 0; m < 4; ++m) _Pragma("unroll") for (int k = 0; k < 2; ++k) dst[m][k] = *(const LAS h16x8*)(lds + PG8_SA(b, h) + aoff + m * 2048 + k * 1024); } while (0)
; #define PG8_LDB(dst, b, h) do { _Pragma("unroll") for (int n = 0; n < 2; ++n) _Pragma("unroll") for (int k = 0; k < 2; ++k) dst[n][k] = *(const LAS h16x8*)(lds + PG8_SB(b, h) + boff + n * 2048 + k * 1024); } while (0)
; #define PG8_MMA(ai, bj, At, Bt_) do { __builtin_amdgcn_s_setprio(1); _Pragma("unroll") for (int m = 0; m < 4; ++m) _Pragma("unroll") for (int n = 0; n < 2; ++n) _Pragma("unroll") for (int k = 0; k < 2; ++k) \
;         acc[ai][bj][m][n] = __builtin_amdgcn_mfma_f32_16x16x32_f16(Bt_[n][k], At[m][k], acc[ai][bj][m][n], 0, 0, 0); __builtin_amdgcn_s_setprio(0); } while (0)
; #define PG8_WAIT_V(n) asm volatile("s_waitcnt vmcnt(" #n ")" ::: "memory")
; template <class Epi, class AMap>
; __device__ __forceinline__ void gemm_phase(LAS unsigned char* lds, const AMap am, const int lda, const h16* Bt, const int ldb, const int M, const int N, const int K, const Epi& E) {
;     ...
;         for (int t = 0; t < nt; t += 2) {
;             const bool last = (t == nt - 2);
;             const char* a1 = cA + (size_t)(t + 1) * kstep;
;             const char* a2 = last ? nA : cA + (size_t)(t + 2) * kstep; const char* b2 = last ? nB : cB + (size_t)(t + 2) * kstep;
;             const char* a3 = a2 + kstep; const char* b3 = b2 + kstep;
;             PG8_LDB(B0, 0, 0); PG8_SCHED; PG8_LDA(At, 0, 0); PG8_STAGE(PG8_SA(1, 1), a1 + hstepA, voffA);
;             PG8_WAIT_L(8); PG8_BAR; PG8_WAIT_L(0); PG8_MMA(0, 0, At, B0); PG8_BAR; PG8_SCHED;
;             PG8_LDB(B1, 0, 1); PG8_STAGE(PG8_SB(0, 0), b2, voffB);
;             PG8_BAR; PG8_WAIT_L(0); PG8_MMA(0, 1, At, B1); PG8_BAR;
;             PG8_LDA(At, 0, 1); PG8_STAGE(PG8_SA(0, 0), a2, voffA);
;             PG8_BAR; PG8_WAIT_L(0); PG8_MMA(1, 0, At, B0); PG8_BAR; PG8_SCHED;
;             PG8_STAGE(PG8_SB(0, 1), b2 + hstepB, voffB);
;             PG8_WAIT_V(6); PG8_BAR; PG8_MMA(1, 1, At, B1); PG8_BAR;
.LBB0_61:
	s_add_u32 s26, s22, 0x100
	s_addc_u32 s27, s23, 0
	s_add_i32 s51, 0, 0x10000
	v_add_u32_e32 v144, s51, v147
	ds_read_b128 v[140:143], v144
	ds_read_b128 v[150:153], v144 offset:1024
	ds_read_b128 v[154:157], v144 offset:2048
	ds_read_b128 v[158:161], v144 offset:3072
	s_cmpk_eq_i32 s29, 0x52
	s_cselect_b32 s45, s1, s27
	s_cselect_b32 s44, s0, s26
	s_cselect_b32 s43, s41, s21
	s_cselect_b32 s42, s40, s20
	v_lshl_add_u64 v[144:145], s[22:23], 0, v[136:137]
	s_add_i32 m0, s63, 0xc000
	ds_read_b128 v[162:165], v149
	ds_read_b128 v[166:169], v149 offset:1024
	ds_read_b128 v[170:173], v149 offset:2048
	ds_read_b128 v[174:177], v149 offset:3072
	ds_read_b128 v[178:181], v149 offset:4096
	ds_read_b128 v[182:185], v149 offset:5120
	ds_read_b128 v[186:189], v149 offset:6144
	ds_read_b128 v[190:193], v149 offset:7168
	global_load_lds_dwordx4 v[144:145], off
	v_lshl_add_u64 v[144:145], s[22:23], 0, v[138:139]
	s_add_i32 m0, s63, 0xe000
	s_nop 0
	global_load_lds_dwordx4 v[144:145], off
	s_waitcnt lgkmcnt(11)
	s_add_i32 s60, 0, 0x14000
	v_add_u32_e32 v144, s60, v147
	s_add_i32 s22, s51, s48
	ds_read_b128 v[194:197], v144
	ds_read_b128 v[198:201], v144 offset:1024
	ds_read_b128 v[202:205], v144 offset:2048
	ds_read_b128 v[220:223], v144 offset:3072
	s_waitcnt vmcnt(8) lgkmcnt(0)
	s_barrier
	v_mfma_f32_16x16x32_f16 v[126:129], v[140:143], v[162:165], v[126:129]
	v_mfma_f32_16x16x32_f16 v[122:125], v[154:157], v[162:165], v[122:125]
	v_mfma_f32_16x16x32_f16 v[110:113], v[140:143], v[170:173], v[110:113]
	v_mfma_f32_16x16x32_f16 v[106:109], v[154:157], v[170:173], v[106:109]
	v_mfma_f32_16x16x32_f16 v[94:97], v[140:143], v[178:181], v[94:97]
	v_mfma_f32_16x16x32_f16 v[90:93], v[154:157], v[178:181], v[90:93]
	v_mfma_f32_16x16x32_f16 v[78:81], v[140:143], v[186:189], v[78:81]
	v_mfma_f32_16x16x32_f16 v[74:77], v[154:157], v[186:189], v[74:77]
	v_mfma_f32_16x16x32_f16 v[126:129], v[150:153], v[166:169], v[126:129]
	v_mfma_f32_16x16x32_f16 v[122:125], v[158:161], v[166:169], v[122:125]
	v_mfma_f32_16x16x32_f16 v[110:113], v[150:153], v[174:177], v[110:113]
	v_mfma_f32_16x16x32_f16 v[106:109], v[158:161], v[174:177], v[106:109]
	v_mfma_f32_16x16x32_f16 v[94:97], v[150:153], v[182:185], v[94:97]
	v_mfma_f32_16x16x32_f16 v[90:93], v[158:161], v[182:185], v[90:93]
	v_mfma_f32_16x16x32_f16 v[78:81], v[150:153], v[190:193], v[78:81]
	v_mfma_f32_16x16x32_f16 v[74:77], v[158:161], v[190:193], v[74:77]
	v_mfma_f32_16x16x32_f16 v[118:121], v[194:197], v[162:165], v[118:121]
	v_mfma_f32_16x16x32_f16 v[114:117], v[202:205], v[162:165], v[114:117]
	v_mfma_f32_16x16x32_f16 v[102:105], v[194:197], v[170:173], v[102:105]
	v_mfma_f32_16x16x32_f16 v[98:101], v[202:205], v[170:173], v[98:101]
	v_mfma_f32_16x16x32_f16 v[86:89], v[194:197], v[178:181], v[86:89]
	v_mfma_f32_16x16x32_f16 v[82:85], v[202:205], v[178:181], v[82:85]
	v_mfma_f32_16x16x32_f16 v[70:73], v[194:197], v[186:189], v[70:73]
	v_mfma_f32_16x16x32_f16 v[66:69], v[202:205], v[186:189], v[66:69]
	v_mfma_f32_16x16x32_f16 v[118:121], v[198:201], v[166:169], v[118:121]
	v_mfma_f32_16x16x32_f16 v[114:117], v[220:223], v[166:169], v[114:117]
	v_mfma_f32_16x16x32_f16 v[102:105], v[198:201], v[174:177], v[102:105]
	v_mfma_f32_16x16x32_f16 v[98:101], v[220:223], v[174:177], v[98:101]
	v_mfma_f32_16x16x32_f16 v[86:89], v[198:201], v[182:185], v[86:89]
	v_mfma_f32_16x16x32_f16 v[82:85], v[220:223], v[182:185], v[82:85]
	v_mfma_f32_16x16x32_f16 v[70:73], v[198:201], v[190:193], v[70:73]
	v_mfma_f32_16x16x32_f16 v[66:69], v[220:223], v[190:193], v[66:69]
	s_barrier
	v_lshl_add_u64 v[144:145], s[42:43], 0, v[0:1]
	s_mov_b32 m0, s22
	v_lshl_add_u64 v[206:207], s[42:43], 0, v[134:135]
	global_load_lds_dwordx4 v[144:145], off
	s_add_i32 m0, s22, 0x2000
	s_nop 0
	global_load_lds_dwordx4 v[206:207], off
	s_mov_b32 m0, s63
	v_lshl_add_u64 v[212:213], s[44:45], 0, v[130:131]
	ds_read_b128 v[162:165], v149 offset:16384
	ds_read_b128 v[166:169], v149 offset:17408
	ds_read_b128 v[170:173], v149 offset:18432
	ds_read_b128 v[174:177], v149 offset:19456
	ds_read_b128 v[178:181], v149 offset:20480
	ds_read_b128 v[182:185], v149 offset:21504
	ds_read_b128 v[186:189], v149 offset:22528
	ds_read_b128 v[190:193], v149 offset:23552
	global_load_lds_dwordx4 v[212:213], off
	v_lshl_add_u64 v[214:215], s[44:45], 0, v[132:133]
	s_mov_b32 m0, s64
	s_nop 0
	global_load_lds_dwordx4 v[214:215], off
	s_add_u32 s22, s42, 0x158000
	s_addc_u32 s23, s43, 0
	s_add_i32 s51, s60, s48
	v_lshl_add_u64 v[232:233], s[22:23], 0, v[0:1]
	s_mov_b32 m0, s51
	s_nop 0
	global_load_lds_dwordx4 v[232:233], off
	v_lshl_add_u64 v[232:233], s[22:23], 0, v[134:135]
	s_add_i32 m0, s51, 0x2000
	s_nop 0
	global_load_lds_dwordx4 v[232:233], off
	s_waitcnt vmcnt(8) lgkmcnt(0)
	s_barrier
; #define PG8_STAGE(bufoff, gbase, voff) do { _Pragma("unroll") for (int _i = 0; _i < 2; ++_i) \
;         __builtin_amdgcn_global_load_lds((const unsigned*)((const char*)(gbase) + (voff)[_i]), (LAS unsigned*)(lds + (bufoff) + ldsw + _i * 8192), 16, 0, 0); } while (0)
; #define PG8_LDA(dst, b, h) do { _Pragma("unroll") for (int m = 0; m < 4; ++m) _Pragma("unroll") for (int k = 0; k < 2; ++k) dst[m][k] = *(const LAS h16x8*)(lds + PG8_SA(b, h) + aoff + m * 2048 + k * 1024); } while (0)
; #define PG8_LDB(dst, b, h) do { _Pragma("unroll") for (int n = 0; n < 2; ++n) _Pragma("unroll") for (int k = 0; k < 2; ++k) dst[n][k] = *(const LAS h16x8*)(lds + PG8_SB(b, h) + boff + n * 2048 + k * 1024); } while (0)
; #define PG8_MMA(ai, bj, At, Bt_) do { __builtin_amdgcn_s_setprio(1); _Pragma("unroll") for (int m = 0; m < 4; ++m) _Pragma("unroll") for (int n = 0; n < 2; ++n) _Pragma("unroll") for (int k = 0; k < 2; ++k) \
;         acc[ai][bj][m][n] = __builtin_amdgcn_mfma_f32_16x16x32_f16(Bt_[n][k], At[m][k], acc[ai][bj][m][n], 0, 0, 0); __builtin_amdgcn_s_setprio(0); } while (0)
; #define PG8_WAIT_V(n) asm volatile("s_waitcnt vmcnt(" #n ")" ::: "memory")
; #define PG8_WAIT_L(n) asm volatile("s_waitcnt lgkmcnt(" #n ")" ::: "memory")
; #define PG8_BAR __builtin_amdgcn_s_barrier()
; #define PG8_SCHED __builtin_amdgcn_sched_barrier(0)
; template <class Epi, class AMap>
; __device__ __forceinline__ void gemm_phase(LAS unsigned char* lds, const AMap am, const int lda, const h16* Bt, const int ldb, const int M, const int N, const int K, const Epi& E) {
;     ...
;             PG8_BAR; PG8_WAIT_L(0); PG8_MMA(1, 0, At, B0); PG8_BAR; PG8_SCHED;
;             PG8_STAGE(PG8_SB(0, 1), b2 + hstepB, voffB);
;             PG8_WAIT_V(6); PG8_BAR; PG8_MMA(1, 1, At, B1); PG8_BAR;
;             PG8_LDB(B0, 1, 0); PG8_SCHED; PG8_LDA(At, 1, 0); PG8_STAGE(PG8_SA(0, 1), a2 + hstepA, voffA);
;             PG8_WAIT_L(8); PG8_BAR; PG8_WAIT_L(0); PG8_MMA(0, 0, At, B0); PG8_BAR; PG8_SCHED;
;             PG8_LDB(B1, 1, 1); PG8_STAGE(PG8_SB(1, 0), b3, voffB);
;             PG8_BAR; PG8_WAIT_L(0); PG8_MMA(0, 1, At, B1); PG8_BAR;
;             PG8_LDA(At, 1, 1); PG8_STAGE(PG8_SA(1, 0), a3, voffA);
;             PG8_BAR; PG8_WAIT_L(0); PG8_MMA(1, 0, At, B0); PG8_BAR; PG8_SCHED;
	v_mfma_f32_16x16x32_f16 v[62:65], v[140:143], v[162:165], v[62:65]
	v_mfma_f32_16x16x32_f16 v[58:61], v[154:157], v[162:165], v[58:61]
	v_mfma_f32_16x16x32_f16 v[46:49], v[140:143], v[170:173], v[46:49]
	v_mfma_f32_16x16x32_f16 v[42:45], v[154:157], v[170:173], v[42:45]
	v_mfma_f32_16x16x32_f16 v[30:33], v[140:143], v[178:181], v[30:33]
	v_mfma_f32_16x16x32_f16 v[26:29], v[154:157], v[178:181], v[26:29]
	v_mfma_f32_16x16x32_f16 v[14:17], v[140:143], v[186:189], v[14:17]
	v_mfma_f32_16x16x32_f16 v[10:13], v[154:157], v[186:189], v[10:13]
	v_mfma_f32_16x16x32_f16 v[62:65], v[150:153], v[166:169], v[62:65]
	v_mfma_f32_16x16x32_f16 v[58:61], v[158:161], v[166:169], v[58:61]
	v_mfma_f32_16x16x32_f16 v[46:49], v[150:153], v[174:177], v[46:49]
	v_mfma_f32_16x16x32_f16 v[42:45], v[158:161], v[174:177], v[42:45]
	v_mfma_f32_16x16x32_f16 v[30:33], v[150:153], v[182:185], v[30:33]
	v_mfma_f32_16x16x32_f16 v[26:29], v[158:161], v[182:185], v[26:29]
	v_mfma_f32_16x16x32_f16 v[14:17], v[150:153], v[190:193], v[14:17]
	v_mfma_f32_16x16x32_f16 v[10:13], v[158:161], v[190:193], v[10:13]
	v_mfma_f32_16x16x32_f16 v[54:57], v[194:197], v[162:165], v[54:57]
	v_mfma_f32_16x16x32_f16 v[50:53], v[202:205], v[162:165], v[50:53]
	v_mfma_f32_16x16x32_f16 v[38:41], v[194:197], v[170:173], v[38:41]
	v_mfma_f32_16x16x32_f16 v[34:37], v[202:205], v[170:173], v[34:37]
	v_mfma_f32_16x16x32_f16 v[22:25], v[194:197], v[178:181], v[22:25]
	v_mfma_f32_16x16x32_f16 v[18:21], v[202:205], v[178:181], v[18:21]
	v_mfma_f32_16x16x32_f16 v[6:9], v[194:197], v[186:189], v[6:9]
	v_mfma_f32_16x16x32_f16 v[2:5], v[202:205], v[186:189], v[2:5]
	v_mfma_f32_16x16x32_f16 v[54:57], v[198:201], v[166:169], v[54:57]
	v_mfma_f32_16x16x32_f16 v[50:53], v[220:223], v[166:169], v[50:53]
	v_mfma_f32_16x16x32_f16 v[38:41], v[198:201], v[174:177], v[38:41]
	v_mfma_f32_16x16x32_f16 v[34:37], v[220:223], v[174:177], v[34:37]
	v_mfma_f32_16x16x32_f16 v[22:25], v[198:201], v[182:185], v[22:25]
	v_mfma_f32_16x16x32_f16 v[18:21], v[220:223], v[182:185], v[18:21]
	v_mfma_f32_16x16x32_f16 v[6:9], v[198:201], v[190:193], v[6:9]
	v_mfma_f32_16x16x32_f16 v[2:5], v[220:223], v[190:193], v[2:5]
	s_barrier
	s_add_i32 s51, 0, 0x18000
	v_add_u32_e32 v234, s51, v147
	ds_read_b128 v[140:143], v234
	ds_read_b128 v[150:153], v234 offset:1024
	ds_read_b128 v[154:157], v234 offset:2048
	ds_read_b128 v[158:161], v234 offset:3072
	s_add_u32 s22, s44, 0x158000
	s_addc_u32 s23, s45, 0
	s_mov_b32 m0, s65
	v_lshl_add_u64 v[232:233], s[22:23], 0, v[130:131]
	ds_read_b128 v[162:165], v149 offset:32768
	ds_read_b128 v[166:169], v149 offset:33792
	ds_read_b128 v[170:173], v149 offset:34816
	ds_read_b128 v[174:177], v149 offset:35840
	ds_read_b128 v[178:181], v149 offset:36864
	ds_read_b128 v[182:185], v149 offset:37888
	ds_read_b128 v[186:189], v149 offset:38912
	ds_read_b128 v[190:193], v149 offset:39936
	global_load_lds_dwordx4 v[232:233], off
	v_lshl_add_u64 v[232:233], s[22:23], 0, v[132:133]
	s_mov_b32 m0, s68
	s_nop 0
	global_load_lds_dwordx4 v[232:233], off
	s_waitcnt lgkmcnt(11)
	s_add_i32 s44, 0, 0x1c000
	s_add_i32 s22, s51, s48
	v_add_u32_e32 v216, s44, v147
	v_lshl_add_u64 v[144:145], v[144:145], 0, s[92:93]
	s_mov_b32 m0, s22
	ds_read_b128 v[194:197], v216
	ds_read_b128 v[198:201], v216 offset:1024
	ds_read_b128 v[202:205], v216 offset:2048
	ds_read_b128 v[220:223], v216 offset:3072
	s_waitcnt vmcnt(8) lgkmcnt(0)
	s_barrier
	v_mfma_f32_16x16x32_f16 v[126:129], v[140:143], v[162:165], v[126:129]
	v_mfma_f32_16x16x32_f16 v[122:125], v[154:157], v[162:165], v[122:125]
	v_mfma_f32_16x16x32_f16 v[110:113], v[140:143], v[170:173], v[110:113]
	v_mfma_f32_16x16x32_f16 v[106:109], v[154:157], v[170:173], v[106:109]
	v_mfma_f32_16x16x32_f16 v[94:97], v[140:143], v[178:181], v[94:97]
	v_mfma_f32_16x16x32_f16 v[90:93], v[154:157], v[178:181], v[90:93]
	v_mfma_f32_16x16x32_f16 v[78:81], v[140:143], v[186:189], v[78:81]
	v_mfma_f32_16x16x32_f16 v[74:77], v[154:157], v[186:189], v[74:77]
	v_mfma_f32_16x16x32_f16 v[126:129], v[150:153], v[166:169], v[126:129]
	v_mfma_f32_16x16x32_f16 v[122:125], v[158:161], v[166:169], v[122:125]
	v_mfma_f32_16x16x32_f16 v[110:113], v[150:153], v[174:177], v[110:113]
	v_mfma_f32_16x16x32_f16 v[106:109], v[158:161], v[174:177], v[106:109]
	v_mfma_f32_16x16x32_f16 v[94:97], v[150:153], v[182:185], v[94:97]
	v_mfma_f32_16x16x32_f16 v[90:93], v[158:161], v[182:185], v[90:93]
	v_mfma_f32_16x16x32_f16 v[78:81], v[150:153], v[190:193], v[78:81]
	v_mfma_f32_16x16x32_f16 v[74:77], v[158:161], v[190:193], v[74:77]
	v_mfma_f32_16x16x32_f16 v[118:121], v[194:197], v[162:165], v[118:121]
	v_mfma_f32_16x16x32_f16 v[114:117], v[202:205], v[162:165], v[114:117]
	v_mfma_f32_16x16x32_f16 v[102:105], v[194:197], v[170:173], v[102:105]
	v_mfma_f32_16x16x32_f16 v[98:101], v[202:205], v[170:173], v[98:101]
	v_mfma_f32_16x16x32_f16 v[86:89], v[194:197], v[178:181], v[86:89]
	v_mfma_f32_16x16x32_f16 v[82:85], v[202:205], v[178:181], v[82:85]
	v_mfma_f32_16x16x32_f16 v[70:73], v[194:197], v[186:189], v[70:73]
	v_mfma_f32_16x16x32_f16 v[66:69], v[202:205], v[186:189], v[66:69]
	v_mfma_f32_16x16x32_f16 v[118:121], v[198:201], v[166:169], v[118:121]
	v_mfma_f32_16x16x32_f16 v[114:117], v[220:223], v[166:169], v[114:117]
	v_mfma_f32_16x16x32_f16 v[102:105], v[198:201], v[174:177], v[102:105]
	v_mfma_f32_16x16x32_f16 v[98:101], v[220:223], v[174:177], v[98:101]
	v_mfma_f32_16x16x32_f16 v[86:89], v[198:201], v[182:185], v[86:89]
	v_mfma_f32_16x16x32_f16 v[82:85], v[220:223], v[182:185], v[82:85]
	v_mfma_f32_16x16x32_f16 v[70:73], v[198:201], v[190:193], v[70:73]
	v_mfma_f32_16x16x32_f16 v[66:69], v[220:223], v[190:193], v[66:69]
	s_barrier
; #define PG8_STAGE(bufoff, gbase, voff) do { _Pragma("unroll") for (int _i = 0; _i < 2; ++_i) \
;         __builtin_amdgcn_global_load_lds((const unsigned*)((const char*)(gbase) + (voff)[_i]), (LAS unsigned*)(lds + (bufoff) + ldsw + _i * 8192), 16, 0, 0); } while (0)
; #define PG8_LDA(dst, b, h) do { _Pragma("unroll") for (int m = 0; m < 4; ++m) _Pragma("unroll") for (int k = 0; k < 2; ++k) dst[m][k] = *(const LAS h16x8*)(lds + PG8_SA(b, h) + aoff + m * 2048 + k * 1024); } while (0)
; #define PG8_MMA(ai, bj, At, Bt_) do { __builtin_amdgcn_s_setprio(1); _Pragma("unroll") for (int m = 0; m < 4; ++m) _Pragma("unroll") for (int n = 0; n < 2; ++n) _Pragma("unroll") for (int k = 0; k < 2; ++k) \
;         acc[ai][bj][m][n] = __builtin_amdgcn_mfma_f32_16x16x32_f16(Bt_[n][k], At[m][k], acc[ai][bj][m][n], 0, 0, 0); __builtin_amdgcn_s_setprio(0); } while (0)
; #define PG8_WAIT_V(n) asm volatile("s_waitcnt vmcnt(" #n ")" ::: "memory")
; #define PG8_WAIT_L(n) asm volatile("s_waitcnt lgkmcnt(" #n ")" ::: "memory")
; #define PG8_BAR __builtin_amdgcn_s_barrier()
; #define PG8_SCHED __builtin_amdgcn_sched_barrier(0)
; template <class Epi, class AMap>
; __device__ __forceinline__ void gemm_phase(LAS unsigned char* lds, const AMap am, const int lda, const h16* Bt, const int ldb, const int M, const int N, const int K, const Epi& E) {
;     ...
;             PG8_LDA(At, 1, 1); PG8_STAGE(PG8_SA(1, 0), a3, voffA);
;             PG8_BAR; PG8_WAIT_L(0); PG8_MMA(1, 0, At, B0); PG8_BAR; PG8_SCHED;
;             PG8_STAGE(PG8_SB(1, 1), b3 + hstepB, voffB);
;             PG8_WAIT_V(6); PG8_BAR; PG8_MMA(1, 1, At, B1); PG8_BAR;
;         }
;     __device__ __forceinline__ void operator()(const f32x4 (&acc)[2][2][4][2], const Unit& u, int wr, int wc, int fr, int fq) const {
;     ...
;             for (int m = 0; m < 4; ++m) { const size_t off = (size_t)(row0 + ai * 128 + m * 16) * DM + colt;
; #pragma unroll
;                 for (int bj = 0; bj < 2; ++bj) {
;                     const h16x8 x = *(const h16x8*)(X + off + bj * 128);
	global_load_lds_dwordx4 v[144:145], off
	v_lshl_add_u64 v[144:145], v[206:207], 0, s[92:93]
	s_add_i32 m0, s22, 0x2000
	s_nop 0
	global_load_lds_dwordx4 v[144:145], off
	s_mov_b32 m0, s69
	v_lshl_add_u64 v[144:145], v[212:213], 0, s[92:93]
	ds_read_b128 v[162:165], v149 offset:49152
	ds_read_b128 v[166:169], v149 offset:50176
	ds_read_b128 v[170:173], v149 offset:51200
	ds_read_b128 v[174:177], v149 offset:52224
	ds_read_b128 v[178:181], v149 offset:53248
	ds_read_b128 v[182:185], v149 offset:54272
	ds_read_b128 v[186:189], v149 offset:55296
	ds_read_b128 v[190:193], v149 offset:56320
	global_load_lds_dwordx4 v[144:145], off
	v_lshl_add_u64 v[144:145], v[214:215], 0, s[92:93]
	s_mov_b32 m0, s70
	s_nop 0
	global_load_lds_dwordx4 v[144:145], off
	s_add_u32 s22, s42, 0x158080
	s_addc_u32 s23, s43, 0
	s_add_i32 s42, s44, s48
	v_lshl_add_u64 v[232:233], s[22:23], 0, v[0:1]
	s_mov_b32 m0, s42
	s_nop 0
	global_load_lds_dwordx4 v[232:233], off
	v_lshl_add_u64 v[232:233], s[22:23], 0, v[134:135]
	s_add_i32 m0, s42, 0x2000
	s_nop 0
	global_load_lds_dwordx4 v[232:233], off
	s_waitcnt vmcnt(8) lgkmcnt(0)
	s_barrier
	v_mfma_f32_16x16x32_f16 v[62:65], v[140:143], v[162:165], v[62:65]
	v_mfma_f32_16x16x32_f16 v[58:61], v[154:157], v[162:165], v[58:61]
	v_mfma_f32_16x16x32_f16 v[46:49], v[140:143], v[170:173], v[46:49]
	v_mfma_f32_16x16x32_f16 v[42:45], v[154:157], v[170:173], v[42:45]
	v_mfma_f32_16x16x32_f16 v[30:33], v[140:143], v[178:181], v[30:33]
	v_mfma_f32_16x16x32_f16 v[26:29], v[154:157], v[178:181], v[26:29]
	v_mfma_f32_16x16x32_f16 v[14:17], v[140:143], v[186:189], v[14:17]
	v_mfma_f32_16x16x32_f16 v[10:13], v[154:157], v[186:189], v[10:13]
	v_mfma_f32_16x16x32_f16 v[62:65], v[150:153], v[166:169], v[62:65]
	v_mfma_f32_16x16x32_f16 v[58:61], v[158:161], v[166:169], v[58:61]
	v_mfma_f32_16x16x32_f16 v[46:49], v[150:153], v[174:177], v[46:49]
	v_mfma_f32_16x16x32_f16 v[42:45], v[158:161], v[174:177], v[42:45]
	v_mfma_f32_16x16x32_f16 v[30:33], v[150:153], v[182:185], v[30:33]
	v_mfma_f32_16x16x32_f16 v[26:29], v[158:161], v[182:185], v[26:29]
	v_mfma_f32_16x16x32_f16 v[14:17], v[150:153], v[190:193], v[14:17]
	v_mfma_f32_16x16x32_f16 v[10:13], v[158:161], v[190:193], v[10:13]
	v_mfma_f32_16x16x32_f16 v[54:57], v[194:197], v[162:165], v[54:57]
	v_mfma_f32_16x16x32_f16 v[50:53], v[202:205], v[162:165], v[50:53]
	v_mfma_f32_16x16x32_f16 v[38:41], v[194:197], v[170:173], v[38:41]
	v_mfma_f32_16x16x32_f16 v[34:37], v[202:205], v[170:173], v[34:37]
	v_mfma_f32_16x16x32_f16 v[22:25], v[194:197], v[178:181], v[22:25]
	v_mfma_f32_16x16x32_f16 v[18:21], v[202:205], v[178:181], v[18:21]
	v_mfma_f32_16x16x32_f16 v[6:9], v[194:197], v[186:189], v[6:9]
	v_mfma_f32_16x16x32_f16 v[2:5], v[202:205], v[186:189], v[2:5]
	v_mfma_f32_16x16x32_f16 v[54:57], v[198:201], v[166:169], v[54:57]
	v_mfma_f32_16x16x32_f16 v[50:53], v[220:223], v[166:169], v[50:53]
	v_mfma_f32_16x16x32_f16 v[38:41], v[198:201], v[174:177], v[38:41]
	v_mfma_f32_16x16x32_f16 v[34:37], v[220:223], v[174:177], v[34:37]
	v_mfma_f32_16x16x32_f16 v[22:25], v[198:201], v[182:185], v[22:25]
	v_mfma_f32_16x16x32_f16 v[18:21], v[220:223], v[182:185], v[18:21]
	v_mfma_f32_16x16x32_f16 v[6:9], v[198:201], v[190:193], v[6:9]
	v_mfma_f32_16x16x32_f16 v[2:5], v[220:223], v[190:193], v[2:5]
	s_add_i32 s29, s29, 2
	s_add_u32 s20, s20, 0x100
	s_addc_u32 s21, s21, 0
	s_cmpk_gt_u32 s29, 0x53
	s_mov_b64 s[22:23], s[26:27]
	s_barrier
	s_cbranch_scc0 .LBB0_61
	v_lshl_add_u32 v144, s35, 8, v146
	v_lshl_or_b32 v142, s50, 8, v148
	v_ashrrev_i32_e32 v145, 31, v144
	v_ashrrev_i32_e32 v143, 31, v142
	v_lshlrev_b64 v[140:141], 11, v[144:145]
	v_lshl_add_u64 v[140:141], v[140:141], 0, v[142:143]
	v_lshlrev_b64 v[140:141], 1, v[140:141]
	v_lshl_add_u64 v[154:155], s[94:95], 0, v[140:141]
	s_mov_b32 s101, 0
	global_load_dwordx4 v[158:161], v[154:155], off
	global_load_dwordx4 v[162:165], v[154:155], off offset:256
	s_mov_b32 s100, 0x10000
	v_lshl_add_u64 v[232:233], v[154:155], 0, s[100:101]
	global_load_dwordx4 v[166:169], v[232:233], off
	global_load_dwordx4 v[170:173], v[232:233], off offset:256
	s_mov_b32 s100, 0x20000
	v_lshl_add_u64 v[232:233], v[154:155], 0, s[100:101]
	global_load_dwordx4 v[174:177], v[232:233], off
	global_load_dwordx4 v[178:181], v[232:233], off offset:256
	s_mov_b32 s100, 0x30000
	v_lshl_add_u64 v[232:233], v[154:155], 0, s[100:101]
	global_load_dwordx4 v[182:185], v[232:233], off
	global_load_dwordx4 v[186:189], v[232:233], off offset:256
	s_mov_b32 s100, 0x80000
	v_lshl_add_u64 v[232:233], v[154:155], 0, s[100:101]
	global_load_dwordx4 v[190:193], v[232:233], off
	global_load_dwordx4 v[194:197], v[232:233], off offset:256
	s_mov_b32 s100, 0x90000
	v_lshl_add_u64 v[232:233], v[154:155], 0, s[100:101]
	global_load_dwordx4 v[198:201], v[232:233], off
	global_load_dwordx4 v[202:205], v[232:233], off offset:256
	s_mov_b32 s100, 0xa0000
	v_lshl_add_u64 v[232:233], v[154:155], 0, s[100:101]
	global_load_dwordx4 v[212:215], v[232:233], off
	global_load_dwordx4 v[220:223], v[232:233], off offset:256
	s_mov_b32 s100, 0xb0000
	v_lshl_add_u64 v[232:233], v[154:155], 0, s[100:101]
	global_load_dwordx4 v[224:227], v[232:233], off
	global_load_dwordx4 v[228:231], v[232:233], off offset:256
	s_mov_b64 s[4:5], 0xb0000
	s_and_b64 vcc, exec, s[38:39]
	s_mov_b32 s50, s72
	s_mov_b64 s[26:27], s[40:41]
	s_mov_b64 s[22:23], s[0:1]
	s_waitcnt vmcnt(15)
;     __device__ __forceinline__ void operator()(const f32x4 (&acc)[2][2][4][2], const Unit& u, int wr, int wc, int fr, int fq) const {
;         EPI_ROWS_PERM
; #pragma unroll
;         for (int ai = 0; ai < 2; ++ai)
; #pragma unroll
;             for (int m = 0; m < 4; ++m) { const size_t off = (size_t)(row0 + ai * 128 + m * 16) * DM + colt;
; #pragma unroll
;                 for (int bj = 0; bj < 2; ++bj) {
;                     const h16x8 x = *(const h16x8*)(X + off + bj * 128);
;                     f32x4 o0, o1;
; #pragma unroll
;                     for (int e = 0; e < 4; ++e) { o0[e] = (float)x[e] * ALPHA + acc[ai][bj][m][0][e]; o1[e] = (float)x[4 + e] * ALPHA + acc[ai][bj][m][1][e]; }
;                     *(u32x4*)(PRE + off + bj * 128) = pack8(o0, o1); } }
	v_mov_b64_e32 v[150:151], v[158:159]
	v_mov_b64_e32 v[152:153], v[160:161]
	v_cvt_f32_f16_e32 v156, v150
	v_cvt_f32_f16_sdwa v157, v150 dst_sel:DWORD dst_unused:UNUSED_PAD src0_sel:WORD_1
	v_cvt_f32_f16_e32 v150, v151
	v_cvt_f32_f16_sdwa v151, v151 dst_sel:DWORD dst_unused:UNUSED_PAD src0_sel:WORD_1
	v_pk_fma_f32 v[126:127], v[156:157], s[34:35], v[126:127] op_sel_hi:[1,0,1]
	s_nop 0
	v_cvt_pk_f16_f32 v126, v126, v127
	v_pk_fma_f32 v[128:129], v[150:151], s[34:35], v[128:129] op_sel_hi:[1,0,1]
	v_lshl_add_u64 v[150:151], s[8:9], 0, v[140:141]
	v_cvt_pk_f16_f32 v127, v128, v129
	v_cvt_f32_f16_e32 v128, v152
	v_cvt_f32_f16_sdwa v129, v152 dst_sel:DWORD dst_unused:UNUSED_PAD src0_sel:WORD_1
	v_pk_fma_f32 v[122:123], v[128:129], s[34:35], v[122:123] op_sel_hi:[1,0,1]
	s_nop 0
	v_cvt_pk_f16_f32 v128, v122, v123
	v_cvt_f32_f16_e32 v122, v153
	v_cvt_f32_f16_sdwa v123, v153 dst_sel:DWORD dst_unused:UNUSED_PAD src0_sel:WORD_1
	v_pk_fma_f32 v[122:123], v[122:123], s[34:35], v[124:125] op_sel_hi:[1,0,1]
	s_nop 0
	v_cvt_pk_f16_f32 v129, v122, v123
	s_nop 0
	global_store_dwordx4 v[150:151], v[126:129], off
	s_waitcnt vmcnt(15)
	v_mov_b64_e32 v[122:123], v[162:163]
	v_mov_b64_e32 v[124:125], v[164:165]
	s_nop 0
	v_cvt_f32_f16_e32 v126, v122
	v_cvt_f32_f16_sdwa v127, v122 dst_sel:DWORD dst_unused:UNUSED_PAD src0_sel:WORD_1
	v_cvt_f32_f16_e32 v122, v123
	v_cvt_f32_f16_sdwa v123, v123 dst_sel:DWORD dst_unused:UNUSED_PAD src0_sel:WORD_1
	v_pk_fma_f32 v[118:119], v[126:127], s[34:35], v[118:119] op_sel_hi:[1,0,1]
	s_nop 0
	v_cvt_pk_f16_f32 v118, v118, v119
	v_pk_fma_f32 v[120:121], v[122:123], s[34:35], v[120:121] op_sel_hi:[1,0,1]
	s_nop 0
	v_cvt_pk_f16_f32 v119, v120, v121
	v_cvt_f32_f16_e32 v120, v124
	v_cvt_f32_f16_sdwa v121, v124 dst_sel:DWORD dst_unused:UNUSED_PAD src0_sel:WORD_1
	v_pk_fma_f32 v[114:115], v[120:121], s[34:35], v[114:115] op_sel_hi:[1,0,1]
	s_nop 0
	v_cvt_pk_f16_f32 v120, v114, v115
	v_cvt_f32_f16_e32 v114, v125
	v_cvt_f32_f16_sdwa v115, v125 dst_sel:DWORD dst_unused:UNUSED_PAD src0_sel:WORD_1
	v_pk_fma_f32 v[114:115], v[114:115], s[34:35], v[116:117] op_sel_hi:[1,0,1]
	s_nop 0
	v_cvt_pk_f16_f32 v121, v114, v115
	v_or_b32_e32 v114, 16, v144
	v_ashrrev_i32_e32 v115, 31, v114
	v_lshlrev_b64 v[114:115], 11, v[114:115]
	v_lshl_add_u64 v[114:115], v[114:115], 0, v[142:143]
	global_store_dwordx4 v[150:151], v[118:121], off offset:256
	s_nop 1
	v_lshlrev_b64 v[118:119], 1, v[114:115]
	v_lshl_add_u64 v[120:121], s[94:95], 0, v[118:119]
	s_waitcnt vmcnt(15)
	v_mov_b64_e32 v[114:115], v[166:167]
	v_mov_b64_e32 v[116:117], v[168:169]
	v_cvt_f32_f16_e32 v122, v114
	v_cvt_f32_f16_sdwa v123, v114 dst_sel:DWORD dst_unused:UNUSED_PAD src0_sel:WORD_1
	v_cvt_f32_f16_e32 v114, v115
	v_cvt_f32_f16_sdwa v115, v115 dst_sel:DWORD dst_unused:UNUSED_PAD src0_sel:WORD_1
	v_pk_fma_f32 v[110:111], v[122:123], s[34:35], v[110:111] op_sel_hi:[1,0,1]
	s_nop 0
	v_cvt_pk_f16_f32 v110, v110, v111
	v_pk_fma_f32 v[112:113], v[114:115], s[34:35], v[112:113] op_sel_hi:[1,0,1]
	v_lshl_add_u64 v[114:115], s[8:9], 0, v[118:119]
	v_cvt_pk_f16_f32 v111, v112, v113
	v_cvt_f32_f16_e32 v112, v116
	v_cvt_f32_f16_sdwa v113, v116 dst_sel:DWORD dst_unused:UNUSED_PAD src0_sel:WORD_1
	v_pk_fma_f32 v[106:107], v[112:113], s[34:35], v[106:107] op_sel_hi:[1,0,1]
	s_nop 0
	v_cvt_pk_f16_f32 v112, v106, v107
	v_cvt_f32_f16_e32 v106, v117
	v_cvt_f32_f16_sdwa v107, v117 dst_sel:DWORD dst_unused:UNUSED_PAD src0_sel:WORD_1
	v_pk_fma_f32 v[106:107], v[106:107], s[34:35], v[108:109] op_sel_hi:[1,0,1]
	s_nop 0
	v_cvt_pk_f16_f32 v113, v106, v107
	s_nop 0
	global_store_dwordx4 v[114:115], v[110:113], off
	s_waitcnt vmcnt(15)
	v_mov_b64_e32 v[106:107], v[170:171]
	v_mov_b64_e32 v[108:109], v[172:173]
	s_nop 0
	v_cvt_f32_f16_e32 v110, v106
	v_cvt_f32_f16_sdwa v111, v106 dst_sel:DWORD dst_unused:UNUSED_PAD src0_sel:WORD_1
	v_cvt_f32_f16_e32 v106, v107
	v_cvt_f32_f16_sdwa v107, v107 dst_sel:DWORD dst_unused:UNUSED_PAD src0_sel:WORD_1
	v_pk_fma_f32 v[102:103], v[110:111], s[34:35], v[102:103] op_sel_hi:[1,0,1]
	s_nop 0
	v_cvt_pk_f16_f32 v102, v102, v103
	v_pk_fma_f32 v[104:105], v[106:107], s[34:35], v[104:105] op_sel_hi:[1,0,1]
	s_nop 0
	v_cvt_pk_f16_f32 v103, v104, v105
	v_cvt_f32_f16_e32 v104, v108
	v_cvt_f32_f16_sdwa v105, v108 dst_sel:DWORD dst_unused:UNUSED_PAD src0_sel:WORD_1
	v_pk_fma_f32 v[98:99], v[104:105], s[34:35], v[98:99] op_sel_hi:[1,0,1]
	s_nop 0
	v_cvt_pk_f16_f32 v104, v98, v99
	v_cvt_f32_f16_e32 v98, v109
	v_cvt_f32_f16_sdwa v99, v109 dst_sel:DWORD dst_unused:UNUSED_PAD src0_sel:WORD_1
	v_pk_fma_f32 v[98:99], v[98:99], s[34:35], v[100:101] op_sel_hi:[1,0,1]
	s_nop 0
	v_cvt_pk_f16_f32 v105, v98, v99
	v_or_b32_e32 v98, 32, v144
	v_ashrrev_i32_e32 v99, 31, v98
	v_lshlrev_b64 v[98:99], 11, v[98:99]
	v_lshl_add_u64 v[98:99], v[98:99], 0, v[142:143]
	global_store_dwordx4 v[114:115], v[102:105], off offset:256
	s_nop 1
	v_lshlrev_b64 v[102:103], 1, v[98:99]
	v_lshl_add_u64 v[104:105], s[94:95], 0, v[102:103]
	s_waitcnt vmcnt(15)
	v_mov_b64_e32 v[98:99], v[174:175]
	v_mov_b64_e32 v[100:101], v[176:177]
	v_cvt_f32_f16_e32 v106, v98
	v_cvt_f32_f16_sdwa v107, v98 dst_sel:DWORD dst_unused:UNUSED_PAD src0_sel:WORD_1
	v_cvt_f32_f16_e32 v98, v99
	v_cvt_f32_f16_sdwa v99, v99 dst_sel:DWORD dst_unused:UNUSED_PAD src0_sel:WORD_1
	v_pk_fma_f32 v[94:95], v[106:107], s[34:35], v[94:95] op_sel_hi:[1,0,1]
	s_nop 0
	v_cvt_pk_f16_f32 v94, v94, v95
	v_pk_fma_f32 v[96:97], v[98:99], s[34:35], v[96:97] op_sel_hi:[1,0,1]
	v_lshl_add_u64 v[98:99], s[8:9], 0, v[102:103]
	v_cvt_pk_f16_f32 v95, v96, v97
	v_cvt_f32_f16_e32 v96, v100
	v_cvt_f32_f16_sdwa v97, v100 dst_sel:DWORD dst_unused:UNUSED_PAD src0_sel:WORD_1
	v_pk_fma_f32 v[90:91], v[96:97], s[34:35], v[90:91] op_sel_hi:[1,0,1]
	s_nop 0
	v_cvt_pk_f16_f32 v96, v90, v91
	v_cvt_f32_f16_e32 v90, v101
	v_cvt_f32_f16_sdwa v91, v101 dst_sel:DWORD dst_unused:UNUSED_PAD src0_sel:WORD_1
	v_pk_fma_f32 v[90:91], v[90:91], s[34:35], v[92:93] op_sel_hi:[1,0,1]
	s_nop 0
	v_cvt_pk_f16_f32 v97, v90, v91
	s_nop 0
	global_store_dwordx4 v[98:99], v[94:97], off
	s_waitcnt vmcnt(15)
;     __device__ __forceinline__ void operator()(const f32x4 (&acc)[2][2][4][2], const Unit& u, int wr, int wc, int fr, int fq) const {
;         EPI_ROWS_PERM
; #pragma unroll
;         for (int ai = 0; ai < 2; ++ai)
; #pragma unroll
;             for (int m = 0; m < 4; ++m) { const size_t off = (size_t)(row0 + ai * 128 + m * 16) * DM + colt;
; #pragma unroll
;                 for (int bj = 0; bj < 2; ++bj) {
;                     const h16x8 x = *(const h16x8*)(X + off + bj * 128);
;                     f32x4 o0, o1;
; #pragma unroll
;                     for (int e = 0; e < 4; ++e) { o0[e] = (float)x[e] * ALPHA + acc[ai][bj][m][0][e]; o1[e] = (float)x[4 + e] * ALPHA + acc[ai][bj][m][1][e]; }
;                     *(u32x4*)(PRE + off + bj * 128) = pack8(o0, o1); } }
	v_mov_b64_e32 v[90:91], v[178:179]
	v_mov_b64_e32 v[92:93], v[180:181]
	s_nop 0
	v_cvt_f32_f16_e32 v94, v90
	v_cvt_f32_f16_sdwa v95, v90 dst_sel:DWORD dst_unused:UNUSED_PAD src0_sel:WORD_1
	v_cvt_f32_f16_e32 v90, v91
	v_cvt_f32_f16_sdwa v91, v91 dst_sel:DWORD dst_unused:UNUSED_PAD src0_sel:WORD_1
	v_pk_fma_f32 v[86:87], v[94:95], s[34:35], v[86:87] op_sel_hi:[1,0,1]
	s_nop 0
	v_cvt_pk_f16_f32 v86, v86, v87
	v_pk_fma_f32 v[88:89], v[90:91], s[34:35], v[88:89] op_sel_hi:[1,0,1]
	s_nop 0
	v_cvt_pk_f16_f32 v87, v88, v89
	v_cvt_f32_f16_e32 v88, v92
	v_cvt_f32_f16_sdwa v89, v92 dst_sel:DWORD dst_unused:UNUSED_PAD src0_sel:WORD_1
	v_pk_fma_f32 v[82:83], v[88:89], s[34:35], v[82:83] op_sel_hi:[1,0,1]
	s_nop 0
	v_cvt_pk_f16_f32 v88, v82, v83
	v_cvt_f32_f16_e32 v82, v93
	v_cvt_f32_f16_sdwa v83, v93 dst_sel:DWORD dst_unused:UNUSED_PAD src0_sel:WORD_1
	v_pk_fma_f32 v[82:83], v[82:83], s[34:35], v[84:85] op_sel_hi:[1,0,1]
	s_nop 0
	v_cvt_pk_f16_f32 v89, v82, v83
	v_or_b32_e32 v82, 48, v144
	v_ashrrev_i32_e32 v83, 31, v82
	v_lshlrev_b64 v[82:83], 11, v[82:83]
	v_lshl_add_u64 v[82:83], v[82:83], 0, v[142:143]
	global_store_dwordx4 v[98:99], v[86:89], off offset:256
	s_nop 1
	v_lshlrev_b64 v[86:87], 1, v[82:83]
	v_lshl_add_u64 v[88:89], s[94:95], 0, v[86:87]
	s_waitcnt vmcnt(15)
	v_mov_b64_e32 v[82:83], v[182:183]
	v_mov_b64_e32 v[84:85], v[184:185]
	v_cvt_f32_f16_e32 v90, v82
	v_cvt_f32_f16_sdwa v91, v82 dst_sel:DWORD dst_unused:UNUSED_PAD src0_sel:WORD_1
	v_cvt_f32_f16_e32 v82, v83
	v_cvt_f32_f16_sdwa v83, v83 dst_sel:DWORD dst_unused:UNUSED_PAD src0_sel:WORD_1
	v_pk_fma_f32 v[78:79], v[90:91], s[34:35], v[78:79] op_sel_hi:[1,0,1]
	s_nop 0
	v_cvt_pk_f16_f32 v78, v78, v79
	v_pk_fma_f32 v[80:81], v[82:83], s[34:35], v[80:81] op_sel_hi:[1,0,1]
	v_lshl_add_u64 v[82:83], s[8:9], 0, v[86:87]
	v_cvt_pk_f16_f32 v79, v80, v81
	v_cvt_f32_f16_e32 v80, v84
	v_cvt_f32_f16_sdwa v81, v84 dst_sel:DWORD dst_unused:UNUSED_PAD src0_sel:WORD_1
	v_pk_fma_f32 v[74:75], v[80:81], s[34:35], v[74:75] op_sel_hi:[1,0,1]
	s_nop 0
	v_cvt_pk_f16_f32 v80, v74, v75
	v_cvt_f32_f16_e32 v74, v85
	v_cvt_f32_f16_sdwa v75, v85 dst_sel:DWORD dst_unused:UNUSED_PAD src0_sel:WORD_1
	v_pk_fma_f32 v[74:75], v[74:75], s[34:35], v[76:77] op_sel_hi:[1,0,1]
	s_nop 0
	v_cvt_pk_f16_f32 v81, v74, v75
	s_nop 0
	global_store_dwordx4 v[82:83], v[78:81], off
	s_waitcnt vmcnt(15)
	v_mov_b64_e32 v[74:75], v[186:187]
	v_mov_b64_e32 v[76:77], v[188:189]
	s_nop 0
	v_cvt_f32_f16_e32 v78, v74
	v_cvt_f32_f16_sdwa v79, v74 dst_sel:DWORD dst_unused:UNUSED_PAD src0_sel:WORD_1
	v_cvt_f32_f16_e32 v74, v75
	v_cvt_f32_f16_sdwa v75, v75 dst_sel:DWORD dst_unused:UNUSED_PAD src0_sel:WORD_1
	v_pk_fma_f32 v[70:71], v[78:79], s[34:35], v[70:71] op_sel_hi:[1,0,1]
	s_nop 0
	v_cvt_pk_f16_f32 v70, v70, v71
	v_pk_fma_f32 v[72:73], v[74:75], s[34:35], v[72:73] op_sel_hi:[1,0,1]
	s_nop 0
	v_cvt_pk_f16_f32 v71, v72, v73
	v_cvt_f32_f16_e32 v72, v76
	v_cvt_f32_f16_sdwa v73, v76 dst_sel:DWORD dst_unused:UNUSED_PAD src0_sel:WORD_1
	v_pk_fma_f32 v[66:67], v[72:73], s[34:35], v[66:67] op_sel_hi:[1,0,1]
	s_nop 0
	v_cvt_pk_f16_f32 v72, v66, v67
	v_cvt_f32_f16_e32 v66, v77
	v_cvt_f32_f16_sdwa v67, v77 dst_sel:DWORD dst_unused:UNUSED_PAD src0_sel:WORD_1
	v_pk_fma_f32 v[66:67], v[66:67], s[34:35], v[68:69] op_sel_hi:[1,0,1]
	s_nop 0
	v_cvt_pk_f16_f32 v73, v66, v67
	global_store_dwordx4 v[82:83], v[70:73], off offset:256
	s_nop 1
	v_lshl_add_u64 v[70:71], v[140:141], 0, s[16:17]
	v_lshl_add_u64 v[72:73], s[94:95], 0, v[70:71]
	s_waitcnt vmcnt(15)
	v_mov_b64_e32 v[66:67], v[190:191]
	v_mov_b64_e32 v[68:69], v[192:193]
	v_cvt_f32_f16_e32 v74, v66
	v_cvt_f32_f16_sdwa v75, v66 dst_sel:DWORD dst_unused:UNUSED_PAD src0_sel:WORD_1
	v_cvt_f32_f16_e32 v66, v67
	v_cvt_f32_f16_sdwa v67, v67 dst_sel:DWORD dst_unused:UNUSED_PAD src0_sel:WORD_1
	v_pk_fma_f32 v[62:63], v[74:75], s[34:35], v[62:63] op_sel_hi:[1,0,1]
	s_nop 0
	v_cvt_pk_f16_f32 v62, v62, v63
	v_pk_fma_f32 v[64:65], v[66:67], s[34:35], v[64:65] op_sel_hi:[1,0,1]
	v_lshl_add_u64 v[66:67], s[8:9], 0, v[70:71]
	v_cvt_pk_f16_f32 v63, v64, v65
	v_cvt_f32_f16_e32 v64, v68
	v_cvt_f32_f16_sdwa v65, v68 dst_sel:DWORD dst_unused:UNUSED_PAD src0_sel:WORD_1
	v_pk_fma_f32 v[58:59], v[64:65], s[34:35], v[58:59] op_sel_hi:[1,0,1]
	s_nop 0
	v_cvt_pk_f16_f32 v64, v58, v59
	v_cvt_f32_f16_e32 v58, v69
	v_cvt_f32_f16_sdwa v59, v69 dst_sel:DWORD dst_unused:UNUSED_PAD src0_sel:WORD_1
	v_pk_fma_f32 v[58:59], v[58:59], s[34:35], v[60:61] op_sel_hi:[1,0,1]
	s_nop 0
	v_cvt_pk_f16_f32 v65, v58, v59
	s_nop 0
	global_store_dwordx4 v[66:67], v[62:65], off
	s_waitcnt vmcnt(15)
	v_mov_b64_e32 v[58:59], v[194:195]
	v_mov_b64_e32 v[60:61], v[196:197]
	s_nop 0
	v_cvt_f32_f16_e32 v62, v58
	v_cvt_f32_f16_sdwa v63, v58 dst_sel:DWORD dst_unused:UNUSED_PAD src0_sel:WORD_1
	v_cvt_f32_f16_e32 v58, v59
	v_cvt_f32_f16_sdwa v59, v59 dst_sel:DWORD dst_unused:UNUSED_PAD src0_sel:WORD_1
	v_pk_fma_f32 v[54:55], v[62:63], s[34:35], v[54:55] op_sel_hi:[1,0,1]
	s_nop 0
	v_cvt_pk_f16_f32 v54, v54, v55
	v_pk_fma_f32 v[56:57], v[58:59], s[34:35], v[56:57] op_sel_hi:[1,0,1]
	s_nop 0
	v_cvt_pk_f16_f32 v55, v56, v57
	v_cvt_f32_f16_e32 v56, v60
	v_cvt_f32_f16_sdwa v57, v60 dst_sel:DWORD dst_unused:UNUSED_PAD src0_sel:WORD_1
	v_pk_fma_f32 v[50:51], v[56:57], s[34:35], v[50:51] op_sel_hi:[1,0,1]
	s_nop 0
	v_cvt_pk_f16_f32 v56, v50, v51
	v_cvt_f32_f16_e32 v50, v61
	v_cvt_f32_f16_sdwa v51, v61 dst_sel:DWORD dst_unused:UNUSED_PAD src0_sel:WORD_1
	v_pk_fma_f32 v[50:51], v[50:51], s[34:35], v[52:53] op_sel_hi:[1,0,1]
	s_nop 0
	v_cvt_pk_f16_f32 v57, v50, v51
	global_store_dwordx4 v[66:67], v[54:57], off offset:256
	s_nop 1
	v_lshl_add_u64 v[54:55], v[140:141], 0, s[18:19]
	v_lshl_add_u64 v[56:57], s[94:95], 0, v[54:55]
	s_waitcnt vmcnt(15)
; #define PG8_WAIT_V(n) asm volatile("s_waitcnt vmcnt(" #n ")" ::: "memory")
; #define PG8_BAR __builtin_amdgcn_s_barrier()
; template <class Epi, class AMap>
; __device__ __forceinline__ void gemm_phase(LAS unsigned char* lds, const AMap am, const int lda, const h16* Bt, const int ldb, const int M, const int N, const int K, const Epi& E) {
;     ...
;         if (!has_next) break;
; #pragma unroll
;         for (int a = 0; a < 2; ++a)
; #pragma unroll
;             for (int b = 0; b < 2; ++b)
; #pragma unroll
;                 for (int m = 0; m < 4; ++m)
; #pragma unroll
;                     for (int n = 0; n < 2; ++n) acc[a][b][m][n] = (f32x4){0.f, 0.f, 0.f, 0.f};
;         cur = nxt; cA = nA; cB = nB; ++ui;
;     }
;     PG8_WAIT_V(0);
;     if (wr == 0) PG8_BAR;
;     PG8_BAR;
;     __device__ __forceinline__ void operator()(const f32x4 (&acc)[2][2][4][2], const Unit& u, int wr, int wc, int fr, int fq) const {
;     ...
;             for (int m = 0; m < 4; ++m) { const size_t off = (size_t)(row0 + ai * 128 + m * 16) * DM + colt;
; #pragma unroll
;                 for (int bj = 0; bj < 2; ++bj) {
;                     const h16x8 x = *(const h16x8*)(X + off + bj * 128);
;                     f32x4 o0, o1;
; #pragma unroll
;                     for (int e = 0; e < 4; ++e) { o0[e] = (float)x[e] * ALPHA + acc[ai][bj][m][0][e]; o1[e] = (float)x[4 + e] * ALPHA + acc[ai][bj][m][1][e]; }
;                     *(u32x4*)(PRE + off + bj * 128) = pack8(o0, o1); } }
	v_mov_b64_e32 v[50:51], v[198:199]
	v_mov_b64_e32 v[52:53], v[200:201]
	v_cvt_f32_f16_e32 v58, v50
	v_cvt_f32_f16_sdwa v59, v50 dst_sel:DWORD dst_unused:UNUSED_PAD src0_sel:WORD_1
	v_cvt_f32_f16_e32 v50, v51
	v_cvt_f32_f16_sdwa v51, v51 dst_sel:DWORD dst_unused:UNUSED_PAD src0_sel:WORD_1
	v_pk_fma_f32 v[46:47], v[58:59], s[34:35], v[46:47] op_sel_hi:[1,0,1]
	s_nop 0
	v_cvt_pk_f16_f32 v46, v46, v47
	v_pk_fma_f32 v[48:49], v[50:51], s[34:35], v[48:49] op_sel_hi:[1,0,1]
	v_lshl_add_u64 v[50:51], s[8:9], 0, v[54:55]
	v_cvt_pk_f16_f32 v47, v48, v49
	v_cvt_f32_f16_e32 v48, v52
	v_cvt_f32_f16_sdwa v49, v52 dst_sel:DWORD dst_unused:UNUSED_PAD src0_sel:WORD_1
	v_pk_fma_f32 v[42:43], v[48:49], s[34:35], v[42:43] op_sel_hi:[1,0,1]
	s_nop 0
	v_cvt_pk_f16_f32 v48, v42, v43
	v_cvt_f32_f16_e32 v42, v53
	v_cvt_f32_f16_sdwa v43, v53 dst_sel:DWORD dst_unused:UNUSED_PAD src0_sel:WORD_1
	v_pk_fma_f32 v[42:43], v[42:43], s[34:35], v[44:45] op_sel_hi:[1,0,1]
	s_nop 0
	v_cvt_pk_f16_f32 v49, v42, v43
	s_nop 0
	global_store_dwordx4 v[50:51], v[46:49], off
	s_waitcnt vmcnt(15)
	v_mov_b64_e32 v[42:43], v[202:203]
	v_mov_b64_e32 v[44:45], v[204:205]
	s_nop 0
	v_cvt_f32_f16_e32 v46, v42
	v_cvt_f32_f16_sdwa v47, v42 dst_sel:DWORD dst_unused:UNUSED_PAD src0_sel:WORD_1
	v_cvt_f32_f16_e32 v42, v43
	v_cvt_f32_f16_sdwa v43, v43 dst_sel:DWORD dst_unused:UNUSED_PAD src0_sel:WORD_1
	v_pk_fma_f32 v[38:39], v[46:47], s[34:35], v[38:39] op_sel_hi:[1,0,1]
	s_nop 0
	v_cvt_pk_f16_f32 v38, v38, v39
	v_pk_fma_f32 v[40:41], v[42:43], s[34:35], v[40:41] op_sel_hi:[1,0,1]
	s_nop 0
	v_cvt_pk_f16_f32 v39, v40, v41
	v_cvt_f32_f16_e32 v40, v44
	v_cvt_f32_f16_sdwa v41, v44 dst_sel:DWORD dst_unused:UNUSED_PAD src0_sel:WORD_1
	v_pk_fma_f32 v[34:35], v[40:41], s[34:35], v[34:35] op_sel_hi:[1,0,1]
	s_nop 0
	v_cvt_pk_f16_f32 v40, v34, v35
	v_cvt_f32_f16_e32 v34, v45
	v_cvt_f32_f16_sdwa v35, v45 dst_sel:DWORD dst_unused:UNUSED_PAD src0_sel:WORD_1
	v_pk_fma_f32 v[34:35], v[34:35], s[34:35], v[36:37] op_sel_hi:[1,0,1]
	s_nop 0
	v_cvt_pk_f16_f32 v41, v34, v35
	global_store_dwordx4 v[50:51], v[38:41], off offset:256
	s_nop 1
	v_lshl_add_u64 v[38:39], v[140:141], 0, s[14:15]
	v_lshl_add_u64 v[40:41], s[94:95], 0, v[38:39]
	s_waitcnt vmcnt(15)
	v_mov_b64_e32 v[34:35], v[212:213]
	v_mov_b64_e32 v[36:37], v[214:215]
	v_cvt_f32_f16_e32 v42, v34
	v_cvt_f32_f16_sdwa v43, v34 dst_sel:DWORD dst_unused:UNUSED_PAD src0_sel:WORD_1
	v_cvt_f32_f16_e32 v34, v35
	v_cvt_f32_f16_sdwa v35, v35 dst_sel:DWORD dst_unused:UNUSED_PAD src0_sel:WORD_1
	v_pk_fma_f32 v[30:31], v[42:43], s[34:35], v[30:31] op_sel_hi:[1,0,1]
	s_nop 0
	v_cvt_pk_f16_f32 v30, v30, v31
	v_pk_fma_f32 v[32:33], v[34:35], s[34:35], v[32:33] op_sel_hi:[1,0,1]
	v_lshl_add_u64 v[34:35], s[8:9], 0, v[38:39]
	v_cvt_pk_f16_f32 v31, v32, v33
	v_cvt_f32_f16_e32 v32, v36
	v_cvt_f32_f16_sdwa v33, v36 dst_sel:DWORD dst_unused:UNUSED_PAD src0_sel:WORD_1
	v_pk_fma_f32 v[26:27], v[32:33], s[34:35], v[26:27] op_sel_hi:[1,0,1]
	s_nop 0
	v_cvt_pk_f16_f32 v32, v26, v27
	v_cvt_f32_f16_e32 v26, v37
	v_cvt_f32_f16_sdwa v27, v37 dst_sel:DWORD dst_unused:UNUSED_PAD src0_sel:WORD_1
	v_pk_fma_f32 v[26:27], v[26:27], s[34:35], v[28:29] op_sel_hi:[1,0,1]
	s_nop 0
	v_cvt_pk_f16_f32 v33, v26, v27
	s_nop 0
	global_store_dwordx4 v[34:35], v[30:33], off
	s_waitcnt vmcnt(15)
	v_mov_b64_e32 v[26:27], v[220:221]
	v_mov_b64_e32 v[28:29], v[222:223]
	s_nop 0
	v_cvt_f32_f16_e32 v30, v26
	v_cvt_f32_f16_sdwa v31, v26 dst_sel:DWORD dst_unused:UNUSED_PAD src0_sel:WORD_1
	v_cvt_f32_f16_e32 v26, v27
	v_cvt_f32_f16_sdwa v27, v27 dst_sel:DWORD dst_unused:UNUSED_PAD src0_sel:WORD_1
	v_pk_fma_f32 v[22:23], v[30:31], s[34:35], v[22:23] op_sel_hi:[1,0,1]
	s_nop 0
	v_cvt_pk_f16_f32 v22, v22, v23
	v_pk_fma_f32 v[24:25], v[26:27], s[34:35], v[24:25] op_sel_hi:[1,0,1]
	s_nop 0
	v_cvt_pk_f16_f32 v23, v24, v25
	v_cvt_f32_f16_e32 v24, v28
	v_cvt_f32_f16_sdwa v25, v28 dst_sel:DWORD dst_unused:UNUSED_PAD src0_sel:WORD_1
	v_pk_fma_f32 v[18:19], v[24:25], s[34:35], v[18:19] op_sel_hi:[1,0,1]
	s_nop 0
	v_cvt_pk_f16_f32 v24, v18, v19
	v_cvt_f32_f16_e32 v18, v29
	v_cvt_f32_f16_sdwa v19, v29 dst_sel:DWORD dst_unused:UNUSED_PAD src0_sel:WORD_1
	v_pk_fma_f32 v[18:19], v[18:19], s[34:35], v[20:21] op_sel_hi:[1,0,1]
	s_nop 0
	v_cvt_pk_f16_f32 v25, v18, v19
	global_store_dwordx4 v[34:35], v[22:25], off offset:256
	s_nop 1
	v_lshl_add_u64 v[22:23], v[140:141], 0, s[4:5]
	v_lshl_add_u64 v[24:25], s[94:95], 0, v[22:23]
	s_waitcnt vmcnt(15)
	v_mov_b64_e32 v[18:19], v[224:225]
	v_mov_b64_e32 v[20:21], v[226:227]
	v_cvt_f32_f16_e32 v26, v18
	v_cvt_f32_f16_sdwa v27, v18 dst_sel:DWORD dst_unused:UNUSED_PAD src0_sel:WORD_1
	v_cvt_f32_f16_e32 v18, v19
	v_cvt_f32_f16_sdwa v19, v19 dst_sel:DWORD dst_unused:UNUSED_PAD src0_sel:WORD_1
	v_pk_fma_f32 v[14:15], v[26:27], s[34:35], v[14:15] op_sel_hi:[1,0,1]
	s_nop 0
	v_cvt_pk_f16_f32 v14, v14, v15
	v_pk_fma_f32 v[16:17], v[18:19], s[34:35], v[16:17] op_sel_hi:[1,0,1]
	v_lshl_add_u64 v[18:19], s[8:9], 0, v[22:23]
	v_cvt_pk_f16_f32 v15, v16, v17
	v_cvt_f32_f16_e32 v16, v20
	v_cvt_f32_f16_sdwa v17, v20 dst_sel:DWORD dst_unused:UNUSED_PAD src0_sel:WORD_1
	v_pk_fma_f32 v[10:11], v[16:17], s[34:35], v[10:11] op_sel_hi:[1,0,1]
	s_nop 0
	v_cvt_pk_f16_f32 v16, v10, v11
	v_cvt_f32_f16_e32 v10, v21
	v_cvt_f32_f16_sdwa v11, v21 dst_sel:DWORD dst_unused:UNUSED_PAD src0_sel:WORD_1
	v_pk_fma_f32 v[10:11], v[10:11], s[34:35], v[12:13] op_sel_hi:[1,0,1]
	s_nop 0
	v_cvt_pk_f16_f32 v17, v10, v11
	s_nop 0
	global_store_dwordx4 v[18:19], v[14:17], off
	s_waitcnt vmcnt(15)
	v_mov_b64_e32 v[10:11], v[228:229]
	v_mov_b64_e32 v[12:13], v[230:231]
	s_nop 0
	v_cvt_f32_f16_e32 v14, v10
	v_cvt_f32_f16_sdwa v15, v10 dst_sel:DWORD dst_unused:UNUSED_PAD src0_sel:WORD_1
	v_cvt_f32_f16_e32 v10, v11
	v_cvt_f32_f16_sdwa v11, v11 dst_sel:DWORD dst_unused:UNUSED_PAD src0_sel:WORD_1
	v_pk_fma_f32 v[6:7], v[14:15], s[34:35], v[6:7] op_sel_hi:[1,0,1]
	s_nop 0
	v_cvt_pk_f16_f32 v6, v6, v7
	v_pk_fma_f32 v[8:9], v[10:11], s[34:35], v[8:9] op_sel_hi:[1,0,1]
	s_nop 0
	v_cvt_pk_f16_f32 v7, v8, v9
	v_cvt_f32_f16_e32 v8, v12
	v_cvt_f32_f16_sdwa v9, v12 dst_sel:DWORD dst_unused:UNUSED_PAD src0_sel:WORD_1
	v_pk_fma_f32 v[2:3], v[8:9], s[34:35], v[2:3] op_sel_hi:[1,0,1]
	s_nop 0
	v_cvt_pk_f16_f32 v8, v2, v3
	v_cvt_f32_f16_e32 v2, v13
	v_cvt_f32_f16_sdwa v3, v13 dst_sel:DWORD dst_unused:UNUSED_PAD src0_sel:WORD_1
	v_pk_fma_f32 v[2:3], v[2:3], s[34:35], v[4:5] op_sel_hi:[1,0,1]
	s_nop 0
	v_cvt_pk_f16_f32 v9, v2, v3
	s_mov_b32 s35, s73
	global_store_dwordx4 v[18:19], v[6:9], off offset:256
	s_cbranch_vccz .LBB0_50
	s_waitcnt vmcnt(0)
	s_cmpk_gt_u32 s46, 0xff
	s_cbranch_scc1 .LBB0_65
	s_barrier

; #define PG8_STAGE(bufoff, gbase, voff) do { _Pragma("unroll") for (int _i = 0; _i < 2; ++_i) \
;         __builtin_amdgcn_global_load_lds((const unsigned*)((const char*)(gbase) + (voff)[_i]), (LAS unsigned*)(lds + (bufoff) + ldsw + _i * 8192), 16, 0, 0); } while (0)
; #define PG8_LDA(dst, b, h) do { _Pragma("unroll") for (int m = 0; m < 4; ++m) _Pragma("unroll") for (int k = 0; k < 2; ++k) dst[m][k] = *(const LAS h16x8*)(lds + PG8_SA(b, h) + aoff + m * 2048 + k * 1024); } while (0)
; #define PG8_LDB(dst, b, h) do { _Pragma("unroll") for (int n = 0; n < 2; ++n) _Pragma("unroll") for (int k = 0; k < 2; ++k) dst[n][k] = *(const LAS h16x8*)(lds + PG8_SB(b, h) + boff + n * 2048 + k * 1024); } while (0)
; #define PG8_MMA(ai, bj, At, Bt_) do { __builtin_amdgcn_s_setprio(1); _Pragma("unroll") for (int m = 0; m < 4; ++m) _Pragma("unroll") for (int n = 0; n < 2; ++n) _Pragma("unroll") for (int k = 0; k < 2; ++k) \
;         acc[ai][bj][m][n] = __builtin_amdgcn_mfma_f32_16x16x32_f16(Bt_[n][k], At[m][k], acc[ai][bj][m][n], 0, 0, 0); __builtin_amdgcn_s_setprio(0); } while (0)
; #define PG8_WAIT_V(n) asm volatile("s_waitcnt vmcnt(" #n ")" ::: "memory")
; template <class Epi, class AMap>
; __device__ __forceinline__ void gemm_phase(LAS unsigned char* lds, const AMap am, const int lda, const h16* Bt, const int ldb, const int M, const int N, const int K, const Epi& E) {
;     ...
;         for (int t = 0; t < nt; t += 2) {
;             const bool last = (t == nt - 2);
;             const char* a1 = cA + (size_t)(t + 1) * kstep;
;             const char* a2 = last ? nA : cA + (size_t)(t + 2) * kstep; const char* b2 = last ? nB : cB + (size_t)(t + 2) * kstep;
;             const char* a3 = a2 + kstep; const char* b3 = b2 + kstep;
;             PG8_LDB(B0, 0, 0); PG8_SCHED; PG8_LDA(At, 0, 0); PG8_STAGE(PG8_SA(1, 1), a1 + hstepA, voffA);
;             PG8_WAIT_L(8); PG8_BAR; PG8_WAIT_L(0); PG8_MMA(0, 0, At, B0); PG8_BAR; PG8_SCHED;
;             PG8_LDB(B1, 0, 1); PG8_STAGE(PG8_SB(0, 0), b2, voffB);
;             PG8_BAR; PG8_WAIT_L(0); PG8_MMA(0, 1, At, B1); PG8_BAR;
;             PG8_LDA(At, 0, 1); PG8_STAGE(PG8_SA(0, 0), a2, voffA);
;             PG8_BAR; PG8_WAIT_L(0); PG8_MMA(1, 0, At, B0); PG8_BAR; PG8_SCHED;
;             PG8_STAGE(PG8_SB(0, 1), b2 + hstepB, voffB);
;             PG8_WAIT_V(6); PG8_BAR; PG8_MMA(1, 1, At, B1); PG8_BAR;
.LBB0_92:
	s_add_u32 s0, vcc_lo, 0xfff80080
	s_addc_u32 s1, vcc_hi, -1
	s_add_i32 s67, 0, 0x10000
	v_add_u32_e32 v226, s67, v169
	ds_read_b128 v[66:69], v226
	ds_read_b128 v[70:73], v226 offset:1024
	ds_read_b128 v[74:77], v226 offset:2048
	ds_read_b128 v[78:81], v226 offset:3072
	s_cmp_eq_u32 s60, 28
	s_cselect_b32 s27, s69, s1
	s_cselect_b32 s26, s29, s0
	s_cselect_b32 s49, s73, s66
	s_cselect_b32 s48, s20, s21
	v_lshl_add_u64 v[192:193], vcc, 0, v[172:173]
	s_add_i32 m0, s81, 0xc000
	ds_read_b128 v[90:93], v195
	ds_read_b128 v[94:97], v195 offset:1024
	ds_read_b128 v[98:101], v195 offset:2048
	ds_read_b128 v[102:105], v195 offset:3072
	ds_read_b128 v[176:179], v195 offset:4096
	ds_read_b128 v[180:183], v195 offset:5120
	ds_read_b128 v[184:187], v195 offset:6144
	ds_read_b128 v[188:191], v195 offset:7168
	global_load_lds_dwordx4 v[192:193], off
	v_lshl_add_u64 v[192:193], vcc, 0, v[174:175]
	s_add_i32 m0, s81, 0xe000
	s_nop 0
	global_load_lds_dwordx4 v[192:193], off
	s_waitcnt lgkmcnt(11)
	s_add_i32 s65, 0, 0x14000
	v_add_u32_e32 v192, s65, v169
	s_add_i32 s0, s67, s64
	ds_read_b128 v[196:199], v192
	ds_read_b128 v[200:203], v192 offset:1024
	ds_read_b128 v[204:207], v192 offset:2048
	ds_read_b128 v[220:223], v192 offset:3072
	s_waitcnt vmcnt(8) lgkmcnt(0)
	s_barrier
	v_mfma_f32_16x16x32_f16 v[158:161], v[66:69], v[90:93], v[158:161]
	v_mfma_f32_16x16x32_f16 v[154:157], v[74:77], v[90:93], v[154:157]
	v_mfma_f32_16x16x32_f16 v[142:145], v[66:69], v[98:101], v[142:145]
	v_mfma_f32_16x16x32_f16 v[134:137], v[74:77], v[98:101], v[134:137]
	v_mfma_f32_16x16x32_f16 v[126:129], v[66:69], v[176:179], v[126:129]
	v_mfma_f32_16x16x32_f16 v[118:121], v[74:77], v[176:179], v[118:121]
	v_mfma_f32_16x16x32_f16 v[110:113], v[66:69], v[184:187], v[110:113]
	v_mfma_f32_16x16x32_f16 v[106:109], v[74:77], v[184:187], v[106:109]
	v_mfma_f32_16x16x32_f16 v[158:161], v[70:73], v[94:97], v[158:161]
	v_mfma_f32_16x16x32_f16 v[154:157], v[78:81], v[94:97], v[154:157]
	v_mfma_f32_16x16x32_f16 v[142:145], v[70:73], v[102:105], v[142:145]
	v_mfma_f32_16x16x32_f16 v[134:137], v[78:81], v[102:105], v[134:137]
	v_mfma_f32_16x16x32_f16 v[126:129], v[70:73], v[180:183], v[126:129]
	v_mfma_f32_16x16x32_f16 v[118:121], v[78:81], v[180:183], v[118:121]
	v_mfma_f32_16x16x32_f16 v[110:113], v[70:73], v[188:191], v[110:113]
	v_mfma_f32_16x16x32_f16 v[106:109], v[78:81], v[188:191], v[106:109]
	v_mfma_f32_16x16x32_f16 v[150:153], v[196:199], v[90:93], v[150:153]
	v_mfma_f32_16x16x32_f16 v[146:149], v[204:207], v[90:93], v[146:149]
	v_mfma_f32_16x16x32_f16 v[150:153], v[200:203], v[94:97], v[150:153]
	v_mfma_f32_16x16x32_f16 v[146:149], v[220:223], v[94:97], v[146:149]
	v_mfma_f32_16x16x32_f16 v[138:141], v[196:199], v[98:101], v[138:141]
	v_mfma_f32_16x16x32_f16 v[130:133], v[204:207], v[98:101], v[130:133]
	v_mfma_f32_16x16x32_f16 v[114:117], v[204:207], v[176:179], v[114:117]
	v_mfma_f32_16x16x32_f16 v[86:89], v[196:199], v[184:187], v[86:89]
	v_mfma_f32_16x16x32_f16 v[82:85], v[204:207], v[184:187], v[82:85]
	v_mfma_f32_16x16x32_f16 v[138:141], v[200:203], v[102:105], v[138:141]
	v_mfma_f32_16x16x32_f16 v[130:133], v[220:223], v[102:105], v[130:133]
	v_mfma_f32_16x16x32_f16 v[122:125], v[196:199], v[176:179], v[122:125]
	v_mfma_f32_16x16x32_f16 v[114:117], v[220:223], v[180:183], v[114:117]
	v_mfma_f32_16x16x32_f16 v[86:89], v[200:203], v[188:191], v[86:89]
	v_mfma_f32_16x16x32_f16 v[82:85], v[220:223], v[188:191], v[82:85]
	v_mfma_f32_16x16x32_f16 v[122:125], v[200:203], v[180:183], v[122:125]
	s_barrier
	v_lshl_add_u64 v[192:193], s[48:49], 0, v[0:1]
	s_mov_b32 m0, s0
	v_lshl_add_u64 v[212:213], s[48:49], 0, v[162:163]
	global_load_lds_dwordx4 v[192:193], off
	s_add_i32 m0, s0, 0x2000
	s_nop 0
	global_load_lds_dwordx4 v[212:213], off
	s_mov_b32 m0, s81
	v_lshl_add_u64 v[214:215], s[26:27], 0, v[166:167]
	ds_read_b128 v[90:93], v195 offset:16384
	ds_read_b128 v[94:97], v195 offset:17408
	ds_read_b128 v[98:101], v195 offset:18432
	ds_read_b128 v[102:105], v195 offset:19456
	ds_read_b128 v[176:179], v195 offset:20480
	ds_read_b128 v[180:183], v195 offset:21504
	ds_read_b128 v[184:187], v195 offset:22528
	ds_read_b128 v[188:191], v195 offset:23552
	global_load_lds_dwordx4 v[214:215], off
	v_lshl_add_u64 v[216:217], s[26:27], 0, v[164:165]
	s_mov_b32 m0, s82
	s_nop 0
	global_load_lds_dwordx4 v[216:217], off
	s_add_u32 s0, s48, 0x80000
	s_addc_u32 s1, s49, 0
	s_add_i32 s65, s65, s64
	v_lshl_add_u64 v[224:225], s[0:1], 0, v[0:1]
	s_mov_b32 m0, s65
	s_nop 0
	global_load_lds_dwordx4 v[224:225], off
	v_lshl_add_u64 v[224:225], s[0:1], 0, v[162:163]
	s_add_i32 m0, s65, 0x2000
	s_nop 0
	global_load_lds_dwordx4 v[224:225], off
	s_waitcnt vmcnt(8) lgkmcnt(0)
	s_barrier
; #define PG8_STAGE(bufoff, gbase, voff) do { _Pragma("unroll") for (int _i = 0; _i < 2; ++_i) \
;         __builtin_amdgcn_global_load_lds((const unsigned*)((const char*)(gbase) + (voff)[_i]), (LAS unsigned*)(lds + (bufoff) + ldsw + _i * 8192), 16, 0, 0); } while (0)
; #define PG8_LDA(dst, b, h) do { _Pragma("unroll") for (int m = 0; m < 4; ++m) _Pragma("unroll") for (int k = 0; k < 2; ++k) dst[m][k] = *(const LAS h16x8*)(lds + PG8_SA(b, h) + aoff + m * 2048 + k * 1024); } while (0)
; #define PG8_LDB(dst, b, h) do { _Pragma("unroll") for (int n = 0; n < 2; ++n) _Pragma("unroll") for (int k = 0; k < 2; ++k) dst[n][k] = *(const LAS h16x8*)(lds + PG8_SB(b, h) + boff + n * 2048 + k * 1024); } while (0)
; #define PG8_MMA(ai, bj, At, Bt_) do { __builtin_amdgcn_s_setprio(1); _Pragma("unroll") for (int m = 0; m < 4; ++m) _Pragma("unroll") for (int n = 0; n < 2; ++n) _Pragma("unroll") for (int k = 0; k < 2; ++k) \
;         acc[ai][bj][m][n] = __builtin_amdgcn_mfma_f32_16x16x32_f16(Bt_[n][k], At[m][k], acc[ai][bj][m][n], 0, 0, 0); __builtin_amdgcn_s_setprio(0); } while (0)
; #define PG8_WAIT_V(n) asm volatile("s_waitcnt vmcnt(" #n ")" ::: "memory")
; #define PG8_WAIT_L(n) asm volatile("s_waitcnt lgkmcnt(" #n ")" ::: "memory")
; #define PG8_BAR __builtin_amdgcn_s_barrier()
; #define PG8_SCHED __builtin_amdgcn_sched_barrier(0)
; template <class Epi, class AMap>
; __device__ __forceinline__ void gemm_phase(LAS unsigned char* lds, const AMap am, const int lda, const h16* Bt, const int ldb, const int M, const int N, const int K, const Epi& E) {
;     ...
;             PG8_BAR; PG8_WAIT_L(0); PG8_MMA(1, 0, At, B0); PG8_BAR; PG8_SCHED;
;             PG8_STAGE(PG8_SB(0, 1), b2 + hstepB, voffB);
;             PG8_WAIT_V(6); PG8_BAR; PG8_MMA(1, 1, At, B1); PG8_BAR;
;             PG8_LDB(B0, 1, 0); PG8_SCHED; PG8_LDA(At, 1, 0); PG8_STAGE(PG8_SA(0, 1), a2 + hstepA, voffA);
;             PG8_WAIT_L(8); PG8_BAR; PG8_WAIT_L(0); PG8_MMA(0, 0, At, B0); PG8_BAR; PG8_SCHED;
;             PG8_LDB(B1, 1, 1); PG8_STAGE(PG8_SB(1, 0), b3, voffB);
;             PG8_BAR; PG8_WAIT_L(0); PG8_MMA(0, 1, At, B1); PG8_BAR;
;             PG8_LDA(At, 1, 1); PG8_STAGE(PG8_SA(1, 0), a3, voffA);
;             PG8_BAR; PG8_WAIT_L(0); PG8_MMA(1, 0, At, B0); PG8_BAR; PG8_SCHED;
;             PG8_STAGE(PG8_SB(1, 1), b3 + hstepB, voffB);
;             PG8_WAIT_V(6); PG8_BAR; PG8_MMA(1, 1, At, B1); PG8_BAR;
	v_mfma_f32_16x16x32_f16 v[62:65], v[66:69], v[90:93], v[62:65]
	v_mfma_f32_16x16x32_f16 v[58:61], v[74:77], v[90:93], v[58:61]
	v_mfma_f32_16x16x32_f16 v[46:49], v[66:69], v[98:101], v[46:49]
	v_mfma_f32_16x16x32_f16 v[38:41], v[74:77], v[98:101], v[38:41]
	v_mfma_f32_16x16x32_f16 v[30:33], v[66:69], v[176:179], v[30:33]
	v_mfma_f32_16x16x32_f16 v[22:25], v[74:77], v[176:179], v[22:25]
	v_mfma_f32_16x16x32_f16 v[14:17], v[66:69], v[184:187], v[14:17]
	v_mfma_f32_16x16x32_f16 v[10:13], v[74:77], v[184:187], v[10:13]
	v_mfma_f32_16x16x32_f16 v[62:65], v[70:73], v[94:97], v[62:65]
	v_mfma_f32_16x16x32_f16 v[58:61], v[78:81], v[94:97], v[58:61]
	v_mfma_f32_16x16x32_f16 v[46:49], v[70:73], v[102:105], v[46:49]
	v_mfma_f32_16x16x32_f16 v[38:41], v[78:81], v[102:105], v[38:41]
	v_mfma_f32_16x16x32_f16 v[30:33], v[70:73], v[180:183], v[30:33]
	v_mfma_f32_16x16x32_f16 v[22:25], v[78:81], v[180:183], v[22:25]
	v_mfma_f32_16x16x32_f16 v[14:17], v[70:73], v[188:191], v[14:17]
	v_mfma_f32_16x16x32_f16 v[10:13], v[78:81], v[188:191], v[10:13]
	v_mfma_f32_16x16x32_f16 v[54:57], v[196:199], v[90:93], v[54:57]
	v_mfma_f32_16x16x32_f16 v[50:53], v[204:207], v[90:93], v[50:53]
	v_mfma_f32_16x16x32_f16 v[42:45], v[196:199], v[98:101], v[42:45]
	v_mfma_f32_16x16x32_f16 v[34:37], v[204:207], v[98:101], v[34:37]
	v_mfma_f32_16x16x32_f16 v[26:29], v[196:199], v[176:179], v[26:29]
	v_mfma_f32_16x16x32_f16 v[18:21], v[204:207], v[176:179], v[18:21]
	v_mfma_f32_16x16x32_f16 v[6:9], v[196:199], v[184:187], v[6:9]
	v_mfma_f32_16x16x32_f16 v[2:5], v[204:207], v[184:187], v[2:5]
	v_mfma_f32_16x16x32_f16 v[54:57], v[200:203], v[94:97], v[54:57]
	v_mfma_f32_16x16x32_f16 v[50:53], v[220:223], v[94:97], v[50:53]
	v_mfma_f32_16x16x32_f16 v[42:45], v[200:203], v[102:105], v[42:45]
	v_mfma_f32_16x16x32_f16 v[34:37], v[220:223], v[102:105], v[34:37]
	v_mfma_f32_16x16x32_f16 v[26:29], v[200:203], v[180:183], v[26:29]
	v_mfma_f32_16x16x32_f16 v[18:21], v[220:223], v[180:183], v[18:21]
	v_mfma_f32_16x16x32_f16 v[6:9], v[200:203], v[188:191], v[6:9]
	v_mfma_f32_16x16x32_f16 v[2:5], v[220:223], v[188:191], v[2:5]
	s_barrier
	s_add_i32 s65, 0, 0x18000
	v_add_u32_e32 v226, s65, v169
	ds_read_b128 v[66:69], v226
	ds_read_b128 v[70:73], v226 offset:1024
	ds_read_b128 v[74:77], v226 offset:2048
	ds_read_b128 v[78:81], v226 offset:3072
	s_add_u32 s0, s26, 0x80000
	s_addc_u32 s1, s27, 0
	s_mov_b32 m0, s83
	v_lshl_add_u64 v[224:225], s[0:1], 0, v[166:167]
	ds_read_b128 v[90:93], v195 offset:32768
	ds_read_b128 v[94:97], v195 offset:33792
	ds_read_b128 v[98:101], v195 offset:34816
	ds_read_b128 v[102:105], v195 offset:35840
	ds_read_b128 v[176:179], v195 offset:36864
	ds_read_b128 v[180:183], v195 offset:37888
	ds_read_b128 v[184:187], v195 offset:38912
	ds_read_b128 v[188:191], v195 offset:39936
	global_load_lds_dwordx4 v[224:225], off
	v_lshl_add_u64 v[224:225], s[0:1], 0, v[164:165]
	s_mov_b32 m0, s50
	s_nop 0
	global_load_lds_dwordx4 v[224:225], off
	s_waitcnt lgkmcnt(11)
	s_add_i32 s26, 0, 0x1c000
	v_add_u32_e32 v226, s26, v169
	s_add_i32 s0, s65, s64
	ds_read_b128 v[196:199], v226
	ds_read_b128 v[200:203], v226 offset:1024
	ds_read_b128 v[204:207], v226 offset:2048
	ds_read_b128 v[220:223], v226 offset:3072
	s_waitcnt vmcnt(8) lgkmcnt(0)
	s_barrier
	v_mfma_f32_16x16x32_f16 v[158:161], v[66:69], v[90:93], v[158:161]
	v_mfma_f32_16x16x32_f16 v[158:161], v[70:73], v[94:97], v[158:161]
	v_mfma_f32_16x16x32_f16 v[154:157], v[74:77], v[90:93], v[154:157]
	v_mfma_f32_16x16x32_f16 v[154:157], v[78:81], v[94:97], v[154:157]
	v_mfma_f32_16x16x32_f16 v[142:145], v[66:69], v[98:101], v[142:145]
	v_mfma_f32_16x16x32_f16 v[134:137], v[74:77], v[98:101], v[134:137]
	v_mfma_f32_16x16x32_f16 v[126:129], v[66:69], v[176:179], v[126:129]
	v_mfma_f32_16x16x32_f16 v[118:121], v[74:77], v[176:179], v[118:121]
	v_mfma_f32_16x16x32_f16 v[110:113], v[66:69], v[184:187], v[110:113]
	v_mfma_f32_16x16x32_f16 v[106:109], v[74:77], v[184:187], v[106:109]
	v_mfma_f32_16x16x32_f16 v[142:145], v[70:73], v[102:105], v[142:145]
	v_mfma_f32_16x16x32_f16 v[134:137], v[78:81], v[102:105], v[134:137]
	v_mfma_f32_16x16x32_f16 v[126:129], v[70:73], v[180:183], v[126:129]
	v_mfma_f32_16x16x32_f16 v[118:121], v[78:81], v[180:183], v[118:121]
	v_mfma_f32_16x16x32_f16 v[110:113], v[70:73], v[188:191], v[110:113]
	v_mfma_f32_16x16x32_f16 v[106:109], v[78:81], v[188:191], v[106:109]
	v_mfma_f32_16x16x32_f16 v[146:149], v[204:207], v[90:93], v[146:149]
	v_mfma_f32_16x16x32_f16 v[150:153], v[196:199], v[90:93], v[150:153]
	v_mfma_f32_16x16x32_f16 v[146:149], v[220:223], v[94:97], v[146:149]
	v_mfma_f32_16x16x32_f16 v[138:141], v[196:199], v[98:101], v[138:141]
	v_mfma_f32_16x16x32_f16 v[150:153], v[200:203], v[94:97], v[150:153]
	v_mfma_f32_16x16x32_f16 v[138:141], v[200:203], v[102:105], v[138:141]
	v_mfma_f32_16x16x32_f16 v[130:133], v[204:207], v[98:101], v[130:133]
	v_mfma_f32_16x16x32_f16 v[130:133], v[220:223], v[102:105], v[130:133]
	v_mfma_f32_16x16x32_f16 v[122:125], v[196:199], v[176:179], v[122:125]
	v_mfma_f32_16x16x32_f16 v[122:125], v[200:203], v[180:183], v[122:125]
	v_mfma_f32_16x16x32_f16 v[114:117], v[204:207], v[176:179], v[114:117]
	v_mfma_f32_16x16x32_f16 v[86:89], v[196:199], v[184:187], v[86:89]
	v_mfma_f32_16x16x32_f16 v[82:85], v[204:207], v[184:187], v[82:85]
	v_mfma_f32_16x16x32_f16 v[114:117], v[220:223], v[180:183], v[114:117]
	v_mfma_f32_16x16x32_f16 v[86:89], v[200:203], v[188:191], v[86:89]
	v_mfma_f32_16x16x32_f16 v[82:85], v[220:223], v[188:191], v[82:85]
	s_barrier
; #define PG8_STAGE(bufoff, gbase, voff) do { _Pragma("unroll") for (int _i = 0; _i < 2; ++_i) \
;         __builtin_amdgcn_global_load_lds((const unsigned*)((const char*)(gbase) + (voff)[_i]), (LAS unsigned*)(lds + (bufoff) + ldsw + _i * 8192), 16, 0, 0); } while (0)
; #define PG8_LDA(dst, b, h) do { _Pragma("unroll") for (int m = 0; m < 4; ++m) _Pragma("unroll") for (int k = 0; k < 2; ++k) dst[m][k] = *(const LAS h16x8*)(lds + PG8_SA(b, h) + aoff + m * 2048 + k * 1024); } while (0)
; #define PG8_LDB(dst, b, h) do { _Pragma("unroll") for (int n = 0; n < 2; ++n) _Pragma("unroll") for (int k = 0; k < 2; ++k) dst[n][k] = *(const LAS h16x8*)(lds + PG8_SB(b, h) + boff + n * 2048 + k * 1024); } while (0)
; #define PG8_MMA(ai, bj, At, Bt_) do { __builtin_amdgcn_s_setprio(1); _Pragma("unroll") for (int m = 0; m < 4; ++m) _Pragma("unroll") for (int n = 0; n < 2; ++n) _Pragma("unroll") for (int k = 0; k < 2; ++k) \
;         acc[ai][bj][m][n] = __builtin_amdgcn_mfma_f32_16x16x32_f16(Bt_[n][k], At[m][k], acc[ai][bj][m][n], 0, 0, 0); __builtin_amdgcn_s_setprio(0); } while (0)
; #define PG8_WAIT_V(n) asm volatile("s_waitcnt vmcnt(" #n ")" ::: "memory")
; #define PG8_WAIT_L(n) asm volatile("s_waitcnt lgkmcnt(" #n ")" ::: "memory")
; #define PG8_BAR __builtin_amdgcn_s_barrier()
; #define PG8_SCHED __builtin_amdgcn_sched_barrier(0)
; template <class Epi, class AMap>
; __device__ __forceinline__ void gemm_phase(LAS unsigned char* lds, const AMap am, const int lda, const h16* Bt, const int ldb, const int M, const int N, const int K, const Epi& E) {
;     ...
;             PG8_LDB(B1, 1, 1); PG8_STAGE(PG8_SB(1, 0), b3, voffB);
;             PG8_BAR; PG8_WAIT_L(0); PG8_MMA(0, 1, At, B1); PG8_BAR;
;             PG8_LDA(At, 1, 1); PG8_STAGE(PG8_SA(1, 0), a3, voffA);
;             PG8_BAR; PG8_WAIT_L(0); PG8_MMA(1, 0, At, B0); PG8_BAR; PG8_SCHED;
;             PG8_STAGE(PG8_SB(1, 1), b3 + hstepB, voffB);
;             PG8_WAIT_V(6); PG8_BAR; PG8_MMA(1, 1, At, B1); PG8_BAR;
;         }
	v_lshl_add_u64 v[224:225], v[192:193], 0, s[92:93]
	s_mov_b32 m0, s0
	s_nop 0
	global_load_lds_dwordx4 v[224:225], off
	v_lshl_add_u64 v[224:225], v[212:213], 0, s[92:93]
	s_add_i32 m0, s0, 0x2000
	s_nop 0
	global_load_lds_dwordx4 v[224:225], off
	s_mov_b32 m0, s89
	v_lshl_add_u64 v[192:193], v[214:215], 0, s[92:93]
	ds_read_b128 v[90:93], v195 offset:49152
	ds_read_b128 v[94:97], v195 offset:50176
	ds_read_b128 v[98:101], v195 offset:51200
	ds_read_b128 v[102:105], v195 offset:52224
	ds_read_b128 v[176:179], v195 offset:53248
	ds_read_b128 v[180:183], v195 offset:54272
	ds_read_b128 v[184:187], v195 offset:55296
	ds_read_b128 v[188:191], v195 offset:56320
	global_load_lds_dwordx4 v[192:193], off
	v_lshl_add_u64 v[192:193], v[216:217], 0, s[92:93]
	s_mov_b32 m0, s35
	s_nop 0
	global_load_lds_dwordx4 v[192:193], off
	s_add_u32 s0, s48, 0x80080
	s_addc_u32 s1, s49, 0
	s_add_i32 s26, s26, s64
	v_lshl_add_u64 v[224:225], s[0:1], 0, v[0:1]
	s_mov_b32 m0, s26
	s_nop 0
	global_load_lds_dwordx4 v[224:225], off
	v_lshl_add_u64 v[224:225], s[0:1], 0, v[162:163]
	s_add_i32 m0, s26, 0x2000
	s_nop 0
	global_load_lds_dwordx4 v[224:225], off
	s_waitcnt vmcnt(8) lgkmcnt(0)
	s_barrier
	v_mfma_f32_16x16x32_f16 v[62:65], v[66:69], v[90:93], v[62:65]
	v_mfma_f32_16x16x32_f16 v[58:61], v[74:77], v[90:93], v[58:61]
	v_mfma_f32_16x16x32_f16 v[46:49], v[66:69], v[98:101], v[46:49]
	v_mfma_f32_16x16x32_f16 v[38:41], v[74:77], v[98:101], v[38:41]
	v_mfma_f32_16x16x32_f16 v[30:33], v[66:69], v[176:179], v[30:33]
	v_mfma_f32_16x16x32_f16 v[22:25], v[74:77], v[176:179], v[22:25]
	v_mfma_f32_16x16x32_f16 v[14:17], v[66:69], v[184:187], v[14:17]
	v_mfma_f32_16x16x32_f16 v[10:13], v[74:77], v[184:187], v[10:13]
	v_mfma_f32_16x16x32_f16 v[62:65], v[70:73], v[94:97], v[62:65]
	v_mfma_f32_16x16x32_f16 v[58:61], v[78:81], v[94:97], v[58:61]
	v_mfma_f32_16x16x32_f16 v[46:49], v[70:73], v[102:105], v[46:49]
	v_mfma_f32_16x16x32_f16 v[38:41], v[78:81], v[102:105], v[38:41]
	v_mfma_f32_16x16x32_f16 v[30:33], v[70:73], v[180:183], v[30:33]
	v_mfma_f32_16x16x32_f16 v[22:25], v[78:81], v[180:183], v[22:25]
	v_mfma_f32_16x16x32_f16 v[14:17], v[70:73], v[188:191], v[14:17]
	v_mfma_f32_16x16x32_f16 v[10:13], v[78:81], v[188:191], v[10:13]
	v_mfma_f32_16x16x32_f16 v[54:57], v[196:199], v[90:93], v[54:57]
	v_mfma_f32_16x16x32_f16 v[50:53], v[204:207], v[90:93], v[50:53]
	v_mfma_f32_16x16x32_f16 v[42:45], v[196:199], v[98:101], v[42:45]
	v_mfma_f32_16x16x32_f16 v[34:37], v[204:207], v[98:101], v[34:37]
	v_mfma_f32_16x16x32_f16 v[26:29], v[196:199], v[176:179], v[26:29]
	v_mfma_f32_16x16x32_f16 v[18:21], v[204:207], v[176:179], v[18:21]
	v_mfma_f32_16x16x32_f16 v[6:9], v[196:199], v[184:187], v[6:9]
	v_mfma_f32_16x16x32_f16 v[2:5], v[204:207], v[184:187], v[2:5]
	v_mfma_f32_16x16x32_f16 v[54:57], v[200:203], v[94:97], v[54:57]
	v_mfma_f32_16x16x32_f16 v[50:53], v[220:223], v[94:97], v[50:53]
	v_mfma_f32_16x16x32_f16 v[42:45], v[200:203], v[102:105], v[42:45]
	v_mfma_f32_16x16x32_f16 v[34:37], v[220:223], v[102:105], v[34:37]
	v_mfma_f32_16x16x32_f16 v[26:29], v[200:203], v[180:183], v[26:29]
	v_mfma_f32_16x16x32_f16 v[18:21], v[220:223], v[180:183], v[18:21]
	v_mfma_f32_16x16x32_f16 v[6:9], v[200:203], v[188:191], v[6:9]
	v_mfma_f32_16x16x32_f16 v[2:5], v[220:223], v[188:191], v[2:5]
	s_add_i32 s60, s60, 2
	s_add_u32 vcc_lo, vcc_lo, 0x100
	s_addc_u32 vcc_hi, vcc_hi, 0
	s_add_u32 s21, s21, 0x100
	s_addc_u32 s66, s66, 0
	s_cmp_gt_u32 s60, 29
	s_barrier
	s_cbranch_scc0 .LBB0_92
; template <int CTRL> __device__ __forceinline__ float dpp_f(float x) { return __int_as_float(__builtin_amdgcn_update_dpp(0, __float_as_int(x), CTRL, 0xF, 0xF, true)); }
;     __device__ __forceinline__ void operator()(const f32x4 (&acc)[2][2][4][2], const Unit& u, int wr, int wc, int fr, int fq) const {
;         const int row0 = u.pm * 256 + wr * 64 + fr, f0 = u.pn * 128 + wc * 32 + 8 * fq;
;         f32x4 w0[2], w1[2], w2[2], bb[2];
; #pragma unroll
;         for (int n = 0; n < 2; ++n) { w0[n] = *(const f32x4*)(cw + f0 + 4 * n); w1[n] = *(const f32x4*)(cw + FF + f0 + 4 * n); w2[n] = *(const f32x4*)(cw + 2 * FF + f0 + 4 * n); bb[n] = *(const f32x4*)(cb + f0 + 4 * n); }
; #pragma unroll
;         for (int ai = 0; ai < 2; ++ai) {
;             f32x4 p1[2], p2[2];
; #pragma unroll
;             for (int n = 0; n < 2; ++n) { p1[n] = (f32x4){0.f, 0.f, 0.f, 0.f}; p2[n] = p1[n]; }
; #pragma unroll
;             for (int m = 0; m < 4; ++m) {
;                 const int row = row0 + ai * 128 + m * 16;
;                 f32x4 r1[2], r2[2], o[2];
; #pragma unroll
;                 for (int n = 0; n < 2; ++n)
; #pragma unroll
;                     for (int e = 0; e < 4; ++e) {
;                         const float g = acc[ai][1][m][n][e];
;                         r1[n][e] = dpp_f<0x121>(g); r2[n][e] = dpp_f<0x122>(g);
;                         const float g1 = fr >= 1 ? r1[n][e] : p1[n][e], g2 = fr >= 2 ? r2[n][e] : p2[n][e];
;                         const float gc = bb[n][e] + g2 * w0[n][e] + g1 * w1[n][e] + g * w2[n][e];
;                         o[n][e] = gelu_mul(acc[ai][0][m][n][e], gc);
	v_lshl_or_b32 v176, s23, 7, v194
	v_ashrrev_i32_e32 v177, 31, v176
	v_lshlrev_b64 v[66:67], 2, v[176:177]
	v_lshl_add_u64 v[70:71], s[74:75], 0, v[66:67]
	v_lshl_add_u64 v[74:75], s[8:9], 0, v[66:67]
	v_lshl_add_u64 v[78:79], s[70:71], 0, v[66:67]
	v_lshl_add_u64 v[102:103], s[78:79], 0, v[66:67]
	global_load_dwordx4 v[66:69], v[70:71], off offset:16
	global_load_dwordx4 v[90:93], v[70:71], off
	s_nop 0
	global_load_dwordx4 v[70:73], v[74:75], off offset:16
	global_load_dwordx4 v[94:97], v[74:75], off
	s_nop 0
	global_load_dwordx4 v[74:77], v[78:79], off offset:16
	global_load_dwordx4 v[98:101], v[78:79], off
	s_nop 0
	global_load_dwordx4 v[78:81], v[102:103], off offset:16
	s_nop 0
	global_load_dwordx4 v[102:105], v[102:103], off
	s_lshl_b32 s20, s22, 8
	s_add_i32 s20, s20, s51
	v_or_b32_e32 v196, s20, v168
	v_mov_b32_dpp v192, v150 row_ror:1 row_mask:0xf bank_mask:0xf bound_ctrl:1
	v_mov_b32_dpp v190, v150 row_ror:2 row_mask:0xf bank_mask:0xf bound_ctrl:1
	v_mov_b32_dpp v193, v151 row_ror:1 row_mask:0xf bank_mask:0xf bound_ctrl:1
	v_mov_b32_dpp v191, v151 row_ror:2 row_mask:0xf bank_mask:0xf bound_ctrl:1
	v_mov_b32_dpp v188, v152 row_ror:1 row_mask:0xf bank_mask:0xf bound_ctrl:1
	v_mov_b32_dpp v186, v152 row_ror:2 row_mask:0xf bank_mask:0xf bound_ctrl:1
	v_mov_b32_dpp v189, v153 row_ror:1 row_mask:0xf bank_mask:0xf bound_ctrl:1
	v_mov_b32_dpp v187, v153 row_ror:2 row_mask:0xf bank_mask:0xf bound_ctrl:1
	v_mov_b32_dpp v184, v146 row_ror:1 row_mask:0xf bank_mask:0xf bound_ctrl:1
	v_mov_b32_dpp v182, v146 row_ror:2 row_mask:0xf bank_mask:0xf bound_ctrl:1
	v_mov_b32_dpp v185, v147 row_ror:1 row_mask:0xf bank_mask:0xf bound_ctrl:1
	v_mov_b32_dpp v183, v147 row_ror:2 row_mask:0xf bank_mask:0xf bound_ctrl:1
	v_mov_b32_dpp v180, v148 row_ror:1 row_mask:0xf bank_mask:0xf bound_ctrl:1
	v_mov_b32_dpp v178, v148 row_ror:2 row_mask:0xf bank_mask:0xf bound_ctrl:1
	v_mov_b32_dpp v181, v149 row_ror:1 row_mask:0xf bank_mask:0xf bound_ctrl:1
	v_mov_b32_dpp v179, v149 row_ror:2 row_mask:0xf bank_mask:0xf bound_ctrl:1
	s_and_saveexec_b64 s[22:23], s[40:41]
	s_cbranch_execz .LBB0_95
	s_waitcnt vmcnt(0)
	v_pk_fma_f32 v[198:199], v[90:91], v[190:191], v[102:103]
	v_readlane_b32 s0, v254, 58
	v_pk_fma_f32 v[198:199], v[94:95], v[192:193], v[198:199]
	v_readlane_b32 s1, v254, 59
	v_pk_fma_f32 v[198:199], v[150:151], v[98:99], v[198:199]
	s_nop 0
	v_pk_mul_f32 v[200:201], v[198:199], v[198:199]
	v_pk_mul_f32 v[202:203], v[158:159], v[198:199]
	v_fmamk_f32 v197, v201, 0x3dd2d3e7, v241
	v_mul_f32_e64 v197, v199, -v197
	v_exp_f32_e32 v197, v197
	s_nop 0
	v_add_f32_e32 v197, 1.0, v197
	v_rcp_f32_e32 v201, v197
	v_fmamk_f32 v197, v200, 0x3dd2d3e7, v241
	v_mul_f32_e64 v197, v198, -v197
	v_exp_f32_e32 v197, v197
	s_nop 0
	v_add_f32_e32 v197, 1.0, v197
	v_rcp_f32_e32 v200, v197
	s_nop 0
	v_pk_mul_f32 v[198:199], v[202:203], v[200:201]
	v_pk_fma_f32 v[200:201], v[92:93], v[186:187], v[104:105]
	v_cvt_pk_f16_f32 v198, v198, v199
	v_pk_fma_f32 v[200:201], v[96:97], v[188:189], v[200:201]
	s_nop 0
	v_pk_fma_f32 v[200:201], v[152:153], v[100:101], v[200:201]
	s_nop 0
	v_pk_mul_f32 v[202:203], v[200:201], v[200:201]
	v_pk_mul_f32 v[204:205], v[160:161], v[200:201]
	v_fmamk_f32 v197, v203, 0x3dd2d3e7, v241
	v_mul_f32_e64 v197, v201, -v197
	v_exp_f32_e32 v197, v197
	s_nop 0
	v_add_f32_e32 v197, 1.0, v197
	v_rcp_f32_e32 v203, v197
	v_fmamk_f32 v197, v202, 0x3dd2d3e7, v241
	v_mul_f32_e64 v197, v200, -v197
	v_exp_f32_e32 v197, v197
	s_nop 0
	v_add_f32_e32 v197, 1.0, v197
	v_rcp_f32_e32 v202, v197
	s_nop 0
	v_pk_mul_f32 v[200:201], v[204:205], v[202:203]
	s_nop 0
	v_cvt_pk_f16_f32 v199, v200, v201
	v_pk_fma_f32 v[200:201], v[66:67], v[182:183], v[78:79]
	s_nop 0
	v_pk_fma_f32 v[200:201], v[70:71], v[184:185], v[200:201]
	s_nop 0
	v_pk_fma_f32 v[200:201], v[146:147], v[74:75], v[200:201]
	s_nop 0
	v_pk_mul_f32 v[202:203], v[200:201], v[200:201]
	v_pk_mul_f32 v[204:205], v[154:155], v[200:201]
	v_fmamk_f32 v197, v203, 0x3dd2d3e7, v241
	v_mul_f32_e64 v197, v201, -v197
	v_exp_f32_e32 v197, v197
	s_nop 0
	v_add_f32_e32 v197, 1.0, v197
	v_rcp_f32_e32 v203, v197
	v_fmamk_f32 v197, v202, 0x3dd2d3e7, v241
	v_mul_f32_e64 v197, v200, -v197
	v_exp_f32_e32 v197, v197
	s_nop 0
	v_add_f32_e32 v197, 1.0, v197
	v_rcp_f32_e32 v202, v197
	s_nop 0
	v_pk_mul_f32 v[200:201], v[204:205], v[202:203]
	v_pk_fma_f32 v[202:203], v[68:69], v[178:179], v[80:81]
	v_cvt_pk_f16_f32 v200, v200, v201
	v_pk_fma_f32 v[202:203], v[72:73], v[180:181], v[202:203]
	s_nop 0
	v_pk_fma_f32 v[202:203], v[148:149], v[76:77], v[202:203]
	s_nop 0
	v_pk_mul_f32 v[204:205], v[202:203], v[202:203]
	v_pk_mul_f32 v[206:207], v[156:157], v[202:203]
	v_fmamk_f32 v197, v204, 0x3dd2d3e7, v241
	v_mul_f32_e64 v197, v202, -v197
	v_exp_f32_e32 v197, v197
	s_nop 0
	v_add_f32_e32 v197, 1.0, v197
	v_rcp_f32_e32 v204, v197
	v_fmamk_f32 v197, v205, 0x3dd2d3e7, v241
	v_mul_f32_e64 v197, v203, -v197
	v_exp_f32_e32 v197, v197
	s_nop 0
	v_add_f32_e32 v197, 1.0, v197
	v_rcp_f32_e32 v205, v197
	s_nop 0
	v_pk_mul_f32 v[202:203], v[206:207], v[204:205]
	s_nop 0
	v_cvt_pk_f16_f32 v201, v202, v203
	v_mov_b64_e32 v[202:203], s[0:1]
	v_mad_i64_i32 v[202:203], s[26:27], v196, s13, v[202:203]
	v_lshl_add_u64 v[202:203], v[176:177], 1, v[202:203]
	global_store_dwordx4 v[202:203], v[198:201], off

; #define PG8_STAGE(bufoff, gbase, voff) do { _Pragma("unroll") for (int _i = 0; _i < 2; ++_i) \
;         __builtin_amdgcn_global_load_lds((const unsigned*)((const char*)(gbase) + (voff)[_i]), (LAS unsigned*)(lds + (bufoff) + ldsw + _i * 8192), 16, 0, 0); } while (0)
; #define PG8_LDA(dst, b, h) do { _Pragma("unroll") for (int m = 0; m < 4; ++m) _Pragma("unroll") for (int k = 0; k < 2; ++k) dst[m][k] = *(const LAS h16x8*)(lds + PG8_SA(b, h) + aoff + m * 2048 + k * 1024); } while (0)
; #define PG8_LDB(dst, b, h) do { _Pragma("unroll") for (int n = 0; n < 2; ++n) _Pragma("unroll") for (int k = 0; k < 2; ++k) dst[n][k] = *(const LAS h16x8*)(lds + PG8_SB(b, h) + boff + n * 2048 + k * 1024); } while (0)
; #define PG8_MMA(ai, bj, At, Bt_) do { __builtin_amdgcn_s_setprio(1); _Pragma("unroll") for (int m = 0; m < 4; ++m) _Pragma("unroll") for (int n = 0; n < 2; ++n) _Pragma("unroll") for (int k = 0; k < 2; ++k) \
;         acc[ai][bj][m][n] = __builtin_amdgcn_mfma_f32_16x16x32_f16(Bt_[n][k], At[m][k], acc[ai][bj][m][n], 0, 0, 0); __builtin_amdgcn_s_setprio(0); } while (0)
; #define PG8_WAIT_V(n) asm volatile("s_waitcnt vmcnt(" #n ")" ::: "memory")
; #define PG8_WAIT_L(n) asm volatile("s_waitcnt lgkmcnt(" #n ")" ::: "memory")
; #define PG8_BAR __builtin_amdgcn_s_barrier()
; #define PG8_SCHED __builtin_amdgcn_sched_barrier(0)
; template <class Epi, class AMap>
; __device__ __forceinline__ void gemm_phase(LAS unsigned char* lds, const AMap am, const int lda, const h16* Bt, const int ldb, const int M, const int N, const int K, const Epi& E) {
;     ...
;             PG8_LDB(B0, 0, 0); PG8_SCHED; PG8_LDA(At, 0, 0); PG8_STAGE(PG8_SA(1, 1), a1 + hstepA, voffA);
;             PG8_WAIT_L(8); PG8_BAR; PG8_WAIT_L(0); PG8_MMA(0, 0, At, B0); PG8_BAR; PG8_SCHED;
;             PG8_LDB(B1, 0, 1); PG8_STAGE(PG8_SB(0, 0), b2, voffB);
;             PG8_BAR; PG8_WAIT_L(0); PG8_MMA(0, 1, At, B1); PG8_BAR;
;             PG8_LDA(At, 0, 1); PG8_STAGE(PG8_SA(0, 0), a2, voffA);
;             PG8_BAR; PG8_WAIT_L(0); PG8_MMA(1, 0, At, B0); PG8_BAR; PG8_SCHED;
;             PG8_STAGE(PG8_SB(0, 1), b2 + hstepB, voffB);
;             PG8_WAIT_V(6); PG8_BAR; PG8_MMA(1, 1, At, B1); PG8_BAR;
.LBB0_147:
	s_add_u32 s46, s26, 0xfff80080
	s_addc_u32 s47, s27, -1
	s_add_i32 s60, 0, 0x10000
	v_add_u32_e32 v144, s60, v147
	ds_read_b128 v[140:143], v144
	ds_read_b128 v[150:153], v144 offset:1024
	ds_read_b128 v[154:157], v144 offset:2048
	ds_read_b128 v[158:161], v144 offset:3072
	s_cmp_eq_u32 s51, 28
	s_cselect_b32 s49, s41, s47
	s_cselect_b32 s48, s29, s46
	s_cselect_b32 s47, s1, s50
	s_cselect_b32 s46, s20, s21
	v_lshl_add_u64 v[144:145], s[26:27], 0, v[136:137]
	s_add_i32 m0, s23, 0xc000
	ds_read_b128 v[162:165], v149
	ds_read_b128 v[166:169], v149 offset:1024
	ds_read_b128 v[170:173], v149 offset:2048
	ds_read_b128 v[174:177], v149 offset:3072
	ds_read_b128 v[178:181], v149 offset:4096
	ds_read_b128 v[182:185], v149 offset:5120
	ds_read_b128 v[186:189], v149 offset:6144
	ds_read_b128 v[190:193], v149 offset:7168
	global_load_lds_dwordx4 v[144:145], off
	v_lshl_add_u64 v[144:145], s[26:27], 0, v[138:139]
	s_add_i32 m0, s23, 0xe000
	s_nop 0
	global_load_lds_dwordx4 v[144:145], off
	s_waitcnt lgkmcnt(11)
	s_add_i32 s66, 0, 0x14000
	v_add_u32_e32 v144, s66, v147
	s_add_i32 s60, s60, s64
	ds_read_b128 v[194:197], v144
	ds_read_b128 v[198:201], v144 offset:1024
	ds_read_b128 v[202:205], v144 offset:2048
	ds_read_b128 v[220:223], v144 offset:3072
	s_waitcnt vmcnt(8) lgkmcnt(0)
	s_barrier
	v_mfma_f32_16x16x32_f16 v[126:129], v[140:143], v[162:165], v[126:129]
	v_mfma_f32_16x16x32_f16 v[122:125], v[154:157], v[162:165], v[122:125]
	v_mfma_f32_16x16x32_f16 v[110:113], v[140:143], v[170:173], v[110:113]
	v_mfma_f32_16x16x32_f16 v[106:109], v[154:157], v[170:173], v[106:109]
	v_mfma_f32_16x16x32_f16 v[94:97], v[140:143], v[178:181], v[94:97]
	v_mfma_f32_16x16x32_f16 v[90:93], v[154:157], v[178:181], v[90:93]
	v_mfma_f32_16x16x32_f16 v[78:81], v[140:143], v[186:189], v[78:81]
	v_mfma_f32_16x16x32_f16 v[74:77], v[154:157], v[186:189], v[74:77]
	v_mfma_f32_16x16x32_f16 v[126:129], v[150:153], v[166:169], v[126:129]
	v_mfma_f32_16x16x32_f16 v[122:125], v[158:161], v[166:169], v[122:125]
	v_mfma_f32_16x16x32_f16 v[110:113], v[150:153], v[174:177], v[110:113]
	v_mfma_f32_16x16x32_f16 v[106:109], v[158:161], v[174:177], v[106:109]
	v_mfma_f32_16x16x32_f16 v[94:97], v[150:153], v[182:185], v[94:97]
	v_mfma_f32_16x16x32_f16 v[90:93], v[158:161], v[182:185], v[90:93]
	v_mfma_f32_16x16x32_f16 v[78:81], v[150:153], v[190:193], v[78:81]
	v_mfma_f32_16x16x32_f16 v[74:77], v[158:161], v[190:193], v[74:77]
	v_mfma_f32_16x16x32_f16 v[118:121], v[194:197], v[162:165], v[118:121]
	v_mfma_f32_16x16x32_f16 v[114:117], v[202:205], v[162:165], v[114:117]
	v_mfma_f32_16x16x32_f16 v[102:105], v[194:197], v[170:173], v[102:105]
	v_mfma_f32_16x16x32_f16 v[98:101], v[202:205], v[170:173], v[98:101]
	v_mfma_f32_16x16x32_f16 v[86:89], v[194:197], v[178:181], v[86:89]
	v_mfma_f32_16x16x32_f16 v[82:85], v[202:205], v[178:181], v[82:85]
	v_mfma_f32_16x16x32_f16 v[70:73], v[194:197], v[186:189], v[70:73]
	v_mfma_f32_16x16x32_f16 v[66:69], v[202:205], v[186:189], v[66:69]
	v_mfma_f32_16x16x32_f16 v[118:121], v[198:201], v[166:169], v[118:121]
	v_mfma_f32_16x16x32_f16 v[114:117], v[220:223], v[166:169], v[114:117]
	v_mfma_f32_16x16x32_f16 v[102:105], v[198:201], v[174:177], v[102:105]
	v_mfma_f32_16x16x32_f16 v[98:101], v[220:223], v[174:177], v[98:101]
	v_mfma_f32_16x16x32_f16 v[86:89], v[198:201], v[182:185], v[86:89]
	v_mfma_f32_16x16x32_f16 v[82:85], v[220:223], v[182:185], v[82:85]
	v_mfma_f32_16x16x32_f16 v[70:73], v[198:201], v[190:193], v[70:73]
	v_mfma_f32_16x16x32_f16 v[66:69], v[220:223], v[190:193], v[66:69]
	s_barrier
	v_lshl_add_u64 v[144:145], s[46:47], 0, v[0:1]
	s_mov_b32 m0, s60
	v_lshl_add_u64 v[206:207], s[46:47], 0, v[134:135]
	global_load_lds_dwordx4 v[144:145], off
	s_add_i32 m0, s60, 0x2000
	s_nop 0
	global_load_lds_dwordx4 v[206:207], off
	s_mov_b32 m0, s23
	v_lshl_add_u64 v[212:213], s[48:49], 0, v[130:131]
	ds_read_b128 v[162:165], v149 offset:16384
	ds_read_b128 v[166:169], v149 offset:17408
	ds_read_b128 v[170:173], v149 offset:18432
	ds_read_b128 v[174:177], v149 offset:19456
	ds_read_b128 v[178:181], v149 offset:20480
	ds_read_b128 v[182:185], v149 offset:21504
	ds_read_b128 v[186:189], v149 offset:22528
	ds_read_b128 v[190:193], v149 offset:23552
	global_load_lds_dwordx4 v[212:213], off
	v_lshl_add_u64 v[214:215], s[48:49], 0, v[132:133]
	s_mov_b32 m0, s71
	s_nop 0
	global_load_lds_dwordx4 v[214:215], off
	s_add_u32 s78, s46, 0x80000
	s_addc_u32 s79, s47, 0
	s_add_i32 s60, s66, s64
	v_lshl_add_u64 v[232:233], s[78:79], 0, v[0:1]
	s_mov_b32 m0, s60
	s_nop 0
	global_load_lds_dwordx4 v[232:233], off
	v_lshl_add_u64 v[232:233], s[78:79], 0, v[134:135]
	s_add_i32 m0, s60, 0x2000
	s_nop 0
	global_load_lds_dwordx4 v[232:233], off
	s_waitcnt vmcnt(8) lgkmcnt(0)
	s_barrier
; #define PG8_STAGE(bufoff, gbase, voff) do { _Pragma("unroll") for (int _i = 0; _i < 2; ++_i) \
;         __builtin_amdgcn_global_load_lds((const unsigned*)((const char*)(gbase) + (voff)[_i]), (LAS unsigned*)(lds + (bufoff) + ldsw + _i * 8192), 16, 0, 0); } while (0)
; #define PG8_LDA(dst, b, h) do { _Pragma("unroll") for (int m = 0; m < 4; ++m) _Pragma("unroll") for (int k = 0; k < 2; ++k) dst[m][k] = *(const LAS h16x8*)(lds + PG8_SA(b, h) + aoff + m * 2048 + k * 1024); } while (0)
; #define PG8_LDB(dst, b, h) do { _Pragma("unroll") for (int n = 0; n < 2; ++n) _Pragma("unroll") for (int k = 0; k < 2; ++k) dst[n][k] = *(const LAS h16x8*)(lds + PG8_SB(b, h) + boff + n * 2048 + k * 1024); } while (0)
; #define PG8_MMA(ai, bj, At, Bt_) do { __builtin_amdgcn_s_setprio(1); _Pragma("unroll") for (int m = 0; m < 4; ++m) _Pragma("unroll") for (int n = 0; n < 2; ++n) _Pragma("unroll") for (int k = 0; k < 2; ++k) \
;         acc[ai][bj][m][n] = __builtin_amdgcn_mfma_f32_16x16x32_f16(Bt_[n][k], At[m][k], acc[ai][bj][m][n], 0, 0, 0); __builtin_amdgcn_s_setprio(0); } while (0)
; #define PG8_WAIT_V(n) asm volatile("s_waitcnt vmcnt(" #n ")" ::: "memory")
; #define PG8_WAIT_L(n) asm volatile("s_waitcnt lgkmcnt(" #n ")" ::: "memory")
; #define PG8_BAR __builtin_amdgcn_s_barrier()
; #define PG8_SCHED __builtin_amdgcn_sched_barrier(0)
; template <class Epi, class AMap>
; __device__ __forceinline__ void gemm_phase(LAS unsigned char* lds, const AMap am, const int lda, const h16* Bt, const int ldb, const int M, const int N, const int K, const Epi& E) {
;     ...
;             PG8_BAR; PG8_WAIT_L(0); PG8_MMA(0, 1, At, B1); PG8_BAR;
;             PG8_LDA(At, 0, 1); PG8_STAGE(PG8_SA(0, 0), a2, voffA);
;             PG8_BAR; PG8_WAIT_L(0); PG8_MMA(1, 0, At, B0); PG8_BAR; PG8_SCHED;
;             PG8_STAGE(PG8_SB(0, 1), b2 + hstepB, voffB);
;             PG8_WAIT_V(6); PG8_BAR; PG8_MMA(1, 1, At, B1); PG8_BAR;
;             PG8_LDB(B0, 1, 0); PG8_SCHED; PG8_LDA(At, 1, 0); PG8_STAGE(PG8_SA(0, 1), a2 + hstepA, voffA);
;             PG8_WAIT_L(8); PG8_BAR; PG8_WAIT_L(0); PG8_MMA(0, 0, At, B0); PG8_BAR; PG8_SCHED;
;             PG8_LDB(B1, 1, 1); PG8_STAGE(PG8_SB(1, 0), b3, voffB);
;             PG8_BAR; PG8_WAIT_L(0); PG8_MMA(0, 1, At, B1); PG8_BAR;
	v_mfma_f32_16x16x32_f16 v[62:65], v[140:143], v[162:165], v[62:65]
	v_mfma_f32_16x16x32_f16 v[58:61], v[154:157], v[162:165], v[58:61]
	v_mfma_f32_16x16x32_f16 v[46:49], v[140:143], v[170:173], v[46:49]
	v_mfma_f32_16x16x32_f16 v[42:45], v[154:157], v[170:173], v[42:45]
	v_mfma_f32_16x16x32_f16 v[30:33], v[140:143], v[178:181], v[30:33]
	v_mfma_f32_16x16x32_f16 v[26:29], v[154:157], v[178:181], v[26:29]
	v_mfma_f32_16x16x32_f16 v[14:17], v[140:143], v[186:189], v[14:17]
	v_mfma_f32_16x16x32_f16 v[10:13], v[154:157], v[186:189], v[10:13]
	v_mfma_f32_16x16x32_f16 v[62:65], v[150:153], v[166:169], v[62:65]
	v_mfma_f32_16x16x32_f16 v[58:61], v[158:161], v[166:169], v[58:61]
	v_mfma_f32_16x16x32_f16 v[46:49], v[150:153], v[174:177], v[46:49]
	v_mfma_f32_16x16x32_f16 v[42:45], v[158:161], v[174:177], v[42:45]
	v_mfma_f32_16x16x32_f16 v[30:33], v[150:153], v[182:185], v[30:33]
	v_mfma_f32_16x16x32_f16 v[26:29], v[158:161], v[182:185], v[26:29]
	v_mfma_f32_16x16x32_f16 v[14:17], v[150:153], v[190:193], v[14:17]
	v_mfma_f32_16x16x32_f16 v[10:13], v[158:161], v[190:193], v[10:13]
	v_mfma_f32_16x16x32_f16 v[54:57], v[194:197], v[162:165], v[54:57]
	v_mfma_f32_16x16x32_f16 v[50:53], v[202:205], v[162:165], v[50:53]
	v_mfma_f32_16x16x32_f16 v[38:41], v[194:197], v[170:173], v[38:41]
	v_mfma_f32_16x16x32_f16 v[34:37], v[202:205], v[170:173], v[34:37]
	v_mfma_f32_16x16x32_f16 v[22:25], v[194:197], v[178:181], v[22:25]
	v_mfma_f32_16x16x32_f16 v[18:21], v[202:205], v[178:181], v[18:21]
	v_mfma_f32_16x16x32_f16 v[6:9], v[194:197], v[186:189], v[6:9]
	v_mfma_f32_16x16x32_f16 v[2:5], v[202:205], v[186:189], v[2:5]
	v_mfma_f32_16x16x32_f16 v[54:57], v[198:201], v[166:169], v[54:57]
	v_mfma_f32_16x16x32_f16 v[50:53], v[220:223], v[166:169], v[50:53]
	v_mfma_f32_16x16x32_f16 v[38:41], v[198:201], v[174:177], v[38:41]
	v_mfma_f32_16x16x32_f16 v[34:37], v[220:223], v[174:177], v[34:37]
	v_mfma_f32_16x16x32_f16 v[22:25], v[198:201], v[182:185], v[22:25]
	v_mfma_f32_16x16x32_f16 v[18:21], v[220:223], v[182:185], v[18:21]
	v_mfma_f32_16x16x32_f16 v[6:9], v[198:201], v[190:193], v[6:9]
	v_mfma_f32_16x16x32_f16 v[2:5], v[220:223], v[190:193], v[2:5]
	s_barrier
	s_add_i32 s60, 0, 0x18000
	v_add_u32_e32 v234, s60, v147
	ds_read_b128 v[140:143], v234
	ds_read_b128 v[150:153], v234 offset:1024
	ds_read_b128 v[154:157], v234 offset:2048
	ds_read_b128 v[158:161], v234 offset:3072
	s_add_u32 s48, s48, 0x80000
	s_addc_u32 s49, s49, 0
	s_mov_b32 m0, s72
	v_lshl_add_u64 v[232:233], s[48:49], 0, v[130:131]
	ds_read_b128 v[162:165], v149 offset:32768
	ds_read_b128 v[166:169], v149 offset:33792
	ds_read_b128 v[170:173], v149 offset:34816
	ds_read_b128 v[174:177], v149 offset:35840
	ds_read_b128 v[178:181], v149 offset:36864
	ds_read_b128 v[182:185], v149 offset:37888
	ds_read_b128 v[186:189], v149 offset:38912
	ds_read_b128 v[190:193], v149 offset:39936
	global_load_lds_dwordx4 v[232:233], off
	v_lshl_add_u64 v[232:233], s[48:49], 0, v[132:133]
	s_mov_b32 m0, s73
	s_nop 0
	global_load_lds_dwordx4 v[232:233], off
	s_waitcnt lgkmcnt(11)
	s_add_i32 s48, 0, 0x1c000
	s_add_i32 s49, s60, s64
	v_add_u32_e32 v216, s48, v147
	v_lshl_add_u64 v[144:145], v[144:145], 0, s[92:93]
	s_mov_b32 m0, s49
	ds_read_b128 v[194:197], v216
	ds_read_b128 v[198:201], v216 offset:1024
	ds_read_b128 v[202:205], v216 offset:2048
	ds_read_b128 v[220:223], v216 offset:3072
	s_waitcnt vmcnt(8) lgkmcnt(0)
	s_barrier
	v_mfma_f32_16x16x32_f16 v[126:129], v[140:143], v[162:165], v[126:129]
	v_mfma_f32_16x16x32_f16 v[122:125], v[154:157], v[162:165], v[122:125]
	v_mfma_f32_16x16x32_f16 v[110:113], v[140:143], v[170:173], v[110:113]
	v_mfma_f32_16x16x32_f16 v[106:109], v[154:157], v[170:173], v[106:109]
	v_mfma_f32_16x16x32_f16 v[94:97], v[140:143], v[178:181], v[94:97]
	v_mfma_f32_16x16x32_f16 v[90:93], v[154:157], v[178:181], v[90:93]
	v_mfma_f32_16x16x32_f16 v[78:81], v[140:143], v[186:189], v[78:81]
	v_mfma_f32_16x16x32_f16 v[74:77], v[154:157], v[186:189], v[74:77]
	v_mfma_f32_16x16x32_f16 v[126:129], v[150:153], v[166:169], v[126:129]
	v_mfma_f32_16x16x32_f16 v[122:125], v[158:161], v[166:169], v[122:125]
	v_mfma_f32_16x16x32_f16 v[110:113], v[150:153], v[174:177], v[110:113]
	v_mfma_f32_16x16x32_f16 v[106:109], v[158:161], v[174:177], v[106:109]
	v_mfma_f32_16x16x32_f16 v[94:97], v[150:153], v[182:185], v[94:97]
	v_mfma_f32_16x16x32_f16 v[90:93], v[158:161], v[182:185], v[90:93]
	v_mfma_f32_16x16x32_f16 v[78:81], v[150:153], v[190:193], v[78:81]
	v_mfma_f32_16x16x32_f16 v[74:77], v[158:161], v[190:193], v[74:77]
	v_mfma_f32_16x16x32_f16 v[118:121], v[194:197], v[162:165], v[118:121]
	v_mfma_f32_16x16x32_f16 v[114:117], v[202:205], v[162:165], v[114:117]
	v_mfma_f32_16x16x32_f16 v[102:105], v[194:197], v[170:173], v[102:105]
	v_mfma_f32_16x16x32_f16 v[98:101], v[202:205], v[170:173], v[98:101]
	v_mfma_f32_16x16x32_f16 v[86:89], v[194:197], v[178:181], v[86:89]
	v_mfma_f32_16x16x32_f16 v[82:85], v[202:205], v[178:181], v[82:85]
	v_mfma_f32_16x16x32_f16 v[70:73], v[194:197], v[186:189], v[70:73]
	v_mfma_f32_16x16x32_f16 v[66:69], v[202:205], v[186:189], v[66:69]
	v_mfma_f32_16x16x32_f16 v[118:121], v[198:201], v[166:169], v[118:121]
	v_mfma_f32_16x16x32_f16 v[114:117], v[220:223], v[166:169], v[114:117]
	v_mfma_f32_16x16x32_f16 v[102:105], v[198:201], v[174:177], v[102:105]
	v_mfma_f32_16x16x32_f16 v[98:101], v[220:223], v[174:177], v[98:101]
	v_mfma_f32_16x16x32_f16 v[86:89], v[198:201], v[182:185], v[86:89]
	v_mfma_f32_16x16x32_f16 v[82:85], v[220:223], v[182:185], v[82:85]
	v_mfma_f32_16x16x32_f16 v[70:73], v[198:201], v[190:193], v[70:73]
	v_mfma_f32_16x16x32_f16 v[66:69], v[220:223], v[190:193], v[66:69]
	s_barrier
; #define PG8_STAGE(bufoff, gbase, voff) do { _Pragma("unroll") for (int _i = 0; _i < 2; ++_i) \
;         __builtin_amdgcn_global_load_lds((const unsigned*)((const char*)(gbase) + (voff)[_i]), (LAS unsigned*)(lds + (bufoff) + ldsw + _i * 8192), 16, 0, 0); } while (0)
; #define PG8_LDA(dst, b, h) do { _Pragma("unroll") for (int m = 0; m < 4; ++m) _Pragma("unroll") for (int k = 0; k < 2; ++k) dst[m][k] = *(const LAS h16x8*)(lds + PG8_SA(b, h) + aoff + m * 2048 + k * 1024); } while (0)
; #define PG8_MMA(ai, bj, At, Bt_) do { __builtin_amdgcn_s_setprio(1); _Pragma("unroll") for (int m = 0; m < 4; ++m) _Pragma("unroll") for (int n = 0; n < 2; ++n) _Pragma("unroll") for (int k = 0; k < 2; ++k) \
;         acc[ai][bj][m][n] = __builtin_amdgcn_mfma_f32_16x16x32_f16(Bt_[n][k], At[m][k], acc[ai][bj][m][n], 0, 0, 0); __builtin_amdgcn_s_setprio(0); } while (0)
; #define PG8_WAIT_V(n) asm volatile("s_waitcnt vmcnt(" #n ")" ::: "memory")
; #define PG8_WAIT_L(n) asm volatile("s_waitcnt lgkmcnt(" #n ")" ::: "memory")
; #define PG8_BAR __builtin_amdgcn_s_barrier()
; #define PG8_SCHED __builtin_amdgcn_sched_barrier(0)
; template <class Epi, class AMap>
; __device__ __forceinline__ void gemm_phase(LAS unsigned char* lds, const AMap am, const int lda, const h16* Bt, const int ldb, const int M, const int N, const int K, const Epi& E) {
;     ...
;             PG8_LDA(At, 1, 1); PG8_STAGE(PG8_SA(1, 0), a3, voffA);
;             PG8_BAR; PG8_WAIT_L(0); PG8_MMA(1, 0, At, B0); PG8_BAR; PG8_SCHED;
;             PG8_STAGE(PG8_SB(1, 1), b3 + hstepB, voffB);
;             PG8_WAIT_V(6); PG8_BAR; PG8_MMA(1, 1, At, B1); PG8_BAR;
;         }
;     __device__ __forceinline__ void operator()(const f32x4 (&acc)[2][2][4][2], const Unit& u, int wr, int wc, int fr, int fq) const {
;     ...
;             for (int m = 0; m < 4; ++m) { const size_t off = (size_t)(row0 + ai * 128 + m * 16) * DM + colt;
; #pragma unroll
;                 for (int bj = 0; bj < 2; ++bj) {
;                     const h16x8 x = *(const h16x8*)(X + off + bj * 128);
	global_load_lds_dwordx4 v[144:145], off
	v_lshl_add_u64 v[144:145], v[206:207], 0, s[92:93]
	s_add_i32 m0, s49, 0x2000
	s_nop 0
	global_load_lds_dwordx4 v[144:145], off
	s_mov_b32 m0, s74
	v_lshl_add_u64 v[144:145], v[212:213], 0, s[92:93]
	ds_read_b128 v[162:165], v149 offset:49152
	ds_read_b128 v[166:169], v149 offset:50176
	ds_read_b128 v[170:173], v149 offset:51200
	ds_read_b128 v[174:177], v149 offset:52224
	ds_read_b128 v[178:181], v149 offset:53248
	ds_read_b128 v[182:185], v149 offset:54272
	ds_read_b128 v[186:189], v149 offset:55296
	ds_read_b128 v[190:193], v149 offset:56320
	global_load_lds_dwordx4 v[144:145], off
	v_lshl_add_u64 v[144:145], v[214:215], 0, s[92:93]
	s_mov_b32 m0, s75
	s_nop 0
	global_load_lds_dwordx4 v[144:145], off
	s_add_u32 s46, s46, 0x80080
	s_addc_u32 s47, s47, 0
	s_add_i32 s48, s48, s64
	v_lshl_add_u64 v[232:233], s[46:47], 0, v[0:1]
	s_mov_b32 m0, s48
	s_nop 0
	global_load_lds_dwordx4 v[232:233], off
	v_lshl_add_u64 v[232:233], s[46:47], 0, v[134:135]
	s_add_i32 m0, s48, 0x2000
	s_nop 0
	global_load_lds_dwordx4 v[232:233], off
	s_waitcnt vmcnt(8) lgkmcnt(0)
	s_barrier
	v_mfma_f32_16x16x32_f16 v[62:65], v[140:143], v[162:165], v[62:65]
	v_mfma_f32_16x16x32_f16 v[58:61], v[154:157], v[162:165], v[58:61]
	v_mfma_f32_16x16x32_f16 v[46:49], v[140:143], v[170:173], v[46:49]
	v_mfma_f32_16x16x32_f16 v[42:45], v[154:157], v[170:173], v[42:45]
	v_mfma_f32_16x16x32_f16 v[30:33], v[140:143], v[178:181], v[30:33]
	v_mfma_f32_16x16x32_f16 v[26:29], v[154:157], v[178:181], v[26:29]
	v_mfma_f32_16x16x32_f16 v[14:17], v[140:143], v[186:189], v[14:17]
	v_mfma_f32_16x16x32_f16 v[10:13], v[154:157], v[186:189], v[10:13]
	v_mfma_f32_16x16x32_f16 v[62:65], v[150:153], v[166:169], v[62:65]
	v_mfma_f32_16x16x32_f16 v[58:61], v[158:161], v[166:169], v[58:61]
	v_mfma_f32_16x16x32_f16 v[46:49], v[150:153], v[174:177], v[46:49]
	v_mfma_f32_16x16x32_f16 v[42:45], v[158:161], v[174:177], v[42:45]
	v_mfma_f32_16x16x32_f16 v[30:33], v[150:153], v[182:185], v[30:33]
	v_mfma_f32_16x16x32_f16 v[26:29], v[158:161], v[182:185], v[26:29]
	v_mfma_f32_16x16x32_f16 v[14:17], v[150:153], v[190:193], v[14:17]
	v_mfma_f32_16x16x32_f16 v[10:13], v[158:161], v[190:193], v[10:13]
	v_mfma_f32_16x16x32_f16 v[54:57], v[194:197], v[162:165], v[54:57]
	v_mfma_f32_16x16x32_f16 v[50:53], v[202:205], v[162:165], v[50:53]
	v_mfma_f32_16x16x32_f16 v[38:41], v[194:197], v[170:173], v[38:41]
	v_mfma_f32_16x16x32_f16 v[34:37], v[202:205], v[170:173], v[34:37]
	v_mfma_f32_16x16x32_f16 v[22:25], v[194:197], v[178:181], v[22:25]
	v_mfma_f32_16x16x32_f16 v[18:21], v[202:205], v[178:181], v[18:21]
	v_mfma_f32_16x16x32_f16 v[6:9], v[194:197], v[186:189], v[6:9]
	v_mfma_f32_16x16x32_f16 v[2:5], v[202:205], v[186:189], v[2:5]
	v_mfma_f32_16x16x32_f16 v[54:57], v[198:201], v[166:169], v[54:57]
	v_mfma_f32_16x16x32_f16 v[50:53], v[220:223], v[166:169], v[50:53]
	v_mfma_f32_16x16x32_f16 v[38:41], v[198:201], v[174:177], v[38:41]
	v_mfma_f32_16x16x32_f16 v[34:37], v[220:223], v[174:177], v[34:37]
	v_mfma_f32_16x16x32_f16 v[22:25], v[198:201], v[182:185], v[22:25]
	v_mfma_f32_16x16x32_f16 v[18:21], v[220:223], v[182:185], v[18:21]
	v_mfma_f32_16x16x32_f16 v[6:9], v[198:201], v[190:193], v[6:9]
	v_mfma_f32_16x16x32_f16 v[2:5], v[220:223], v[190:193], v[2:5]
	s_add_i32 s51, s51, 2
	s_add_u32 s26, s26, 0x100
	s_addc_u32 s27, s27, 0
	s_add_u32 s21, s21, 0x100
	s_addc_u32 s50, s50, 0
	s_cmp_gt_u32 s51, 29
	s_barrier
	s_cbranch_scc0 .LBB0_147
	v_lshl_add_u32 v144, s22, 8, v146
	v_lshl_or_b32 v142, s35, 8, v148
	v_ashrrev_i32_e32 v145, 31, v144
	v_ashrrev_i32_e32 v143, 31, v142
	v_lshlrev_b64 v[140:141], 11, v[144:145]
	v_lshl_add_u64 v[140:141], v[140:141], 0, v[142:143]
	v_lshlrev_b64 v[140:141], 1, v[140:141]
	v_lshl_add_u64 v[154:155], s[94:95], 0, v[140:141]
	s_mov_b32 s101, 0
	global_load_dwordx4 v[158:161], v[154:155], off
	global_load_dwordx4 v[162:165], v[154:155], off offset:256
	s_mov_b32 s100, 0x10000
	v_lshl_add_u64 v[232:233], v[154:155], 0, s[100:101]
	global_load_dwordx4 v[166:169], v[232:233], off
	global_load_dwordx4 v[170:173], v[232:233], off offset:256
	s_mov_b32 s100, 0x20000
	v_lshl_add_u64 v[232:233], v[154:155], 0, s[100:101]
	global_load_dwordx4 v[174:177], v[232:233], off
	global_load_dwordx4 v[178:181], v[232:233], off offset:256
	s_mov_b32 s100, 0x30000
	v_lshl_add_u64 v[232:233], v[154:155], 0, s[100:101]
	global_load_dwordx4 v[182:185], v[232:233], off
	global_load_dwordx4 v[186:189], v[232:233], off offset:256
	s_mov_b32 s100, 0x80000
	v_lshl_add_u64 v[232:233], v[154:155], 0, s[100:101]
	global_load_dwordx4 v[190:193], v[232:233], off
	global_load_dwordx4 v[194:197], v[232:233], off offset:256
	s_mov_b32 s100, 0x90000
	v_lshl_add_u64 v[232:233], v[154:155], 0, s[100:101]
	global_load_dwordx4 v[198:201], v[232:233], off
	global_load_dwordx4 v[202:205], v[232:233], off offset:256
	s_mov_b32 s100, 0xa0000
	v_lshl_add_u64 v[232:233], v[154:155], 0, s[100:101]
	global_load_dwordx4 v[212:215], v[232:233], off
	global_load_dwordx4 v[220:223], v[232:233], off offset:256
	s_mov_b32 s100, 0xb0000
	v_lshl_add_u64 v[232:233], v[154:155], 0, s[100:101]
	global_load_dwordx4 v[224:227], v[232:233], off
	global_load_dwordx4 v[228:231], v[232:233], off offset:256
	s_mov_b64 s[2:3], 0xb0000
	s_and_b64 vcc, exec, s[38:39]
	s_mov_b32 s22, s40
	s_mov_b64 s[46:47], s[44:45]
	s_mov_b64 s[26:27], s[42:43]
	s_movk_i32 s66, 0x80
	s_waitcnt vmcnt(15)
;     __device__ __forceinline__ void operator()(const f32x4 (&acc)[2][2][4][2], const Unit& u, int wr, int wc, int fr, int fq) const {
;     ...
;             for (int m = 0; m < 4; ++m) { const size_t off = (size_t)(row0 + ai * 128 + m * 16) * DM + colt;
; #pragma unroll
;                 for (int bj = 0; bj < 2; ++bj) {
;                     const h16x8 x = *(const h16x8*)(X + off + bj * 128);
;                     f32x4 o0, o1;
; #pragma unroll
;                     for (int e = 0; e < 4; ++e) { o0[e] = (float)x[e] * ALPHA + acc[ai][bj][m][0][e]; o1[e] = (float)x[4 + e] * ALPHA + acc[ai][bj][m][1][e]; }
;                     *(u32x4*)(PRE + off + bj * 128) = pack8(o0, o1); } }
	v_mov_b64_e32 v[150:151], v[158:159]
	v_mov_b64_e32 v[152:153], v[160:161]
	v_cvt_f32_f16_e32 v156, v150
	v_cvt_f32_f16_sdwa v157, v150 dst_sel:DWORD dst_unused:UNUSED_PAD src0_sel:WORD_1
	v_cvt_f32_f16_e32 v150, v151
	v_cvt_f32_f16_sdwa v151, v151 dst_sel:DWORD dst_unused:UNUSED_PAD src0_sel:WORD_1
	v_pk_fma_f32 v[126:127], v[156:157], s[34:35], v[126:127] op_sel_hi:[1,0,1]
	s_nop 0
	v_cvt_pk_f16_f32 v126, v126, v127
	v_pk_fma_f32 v[128:129], v[150:151], s[34:35], v[128:129] op_sel_hi:[1,0,1]
	v_lshl_add_u64 v[150:151], s[4:5], 0, v[140:141]
	v_cvt_pk_f16_f32 v127, v128, v129
	v_cvt_f32_f16_e32 v128, v152
	v_cvt_f32_f16_sdwa v129, v152 dst_sel:DWORD dst_unused:UNUSED_PAD src0_sel:WORD_1
	v_pk_fma_f32 v[122:123], v[128:129], s[34:35], v[122:123] op_sel_hi:[1,0,1]
	s_nop 0
	v_cvt_pk_f16_f32 v128, v122, v123
	v_cvt_f32_f16_e32 v122, v153
	v_cvt_f32_f16_sdwa v123, v153 dst_sel:DWORD dst_unused:UNUSED_PAD src0_sel:WORD_1
	v_pk_fma_f32 v[122:123], v[122:123], s[34:35], v[124:125] op_sel_hi:[1,0,1]
	s_nop 0
	v_cvt_pk_f16_f32 v129, v122, v123
	s_nop 0
	global_store_dwordx4 v[150:151], v[126:129], off
	s_waitcnt vmcnt(15)
	v_mov_b64_e32 v[122:123], v[162:163]
	v_mov_b64_e32 v[124:125], v[164:165]
	s_nop 0
	v_cvt_f32_f16_e32 v126, v122
	v_cvt_f32_f16_sdwa v127, v122 dst_sel:DWORD dst_unused:UNUSED_PAD src0_sel:WORD_1
	v_cvt_f32_f16_e32 v122, v123
	v_cvt_f32_f16_sdwa v123, v123 dst_sel:DWORD dst_unused:UNUSED_PAD src0_sel:WORD_1
	v_pk_fma_f32 v[118:119], v[126:127], s[34:35], v[118:119] op_sel_hi:[1,0,1]
	s_nop 0
	v_cvt_pk_f16_f32 v118, v118, v119
	v_pk_fma_f32 v[120:121], v[122:123], s[34:35], v[120:121] op_sel_hi:[1,0,1]
	s_nop 0
	v_cvt_pk_f16_f32 v119, v120, v121
	v_cvt_f32_f16_e32 v120, v124
	v_cvt_f32_f16_sdwa v121, v124 dst_sel:DWORD dst_unused:UNUSED_PAD src0_sel:WORD_1
	v_pk_fma_f32 v[114:115], v[120:121], s[34:35], v[114:115] op_sel_hi:[1,0,1]
	s_nop 0
	v_cvt_pk_f16_f32 v120, v114, v115
	v_cvt_f32_f16_e32 v114, v125
	v_cvt_f32_f16_sdwa v115, v125 dst_sel:DWORD dst_unused:UNUSED_PAD src0_sel:WORD_1
	v_pk_fma_f32 v[114:115], v[114:115], s[34:35], v[116:117] op_sel_hi:[1,0,1]
	s_nop 0
	v_cvt_pk_f16_f32 v121, v114, v115
	v_or_b32_e32 v114, 16, v144
	v_ashrrev_i32_e32 v115, 31, v114
	v_lshlrev_b64 v[114:115], 11, v[114:115]
	v_lshl_add_u64 v[114:115], v[114:115], 0, v[142:143]
	global_store_dwordx4 v[150:151], v[118:121], off offset:256
	s_nop 1
	v_lshlrev_b64 v[118:119], 1, v[114:115]
	v_lshl_add_u64 v[120:121], s[94:95], 0, v[118:119]
	s_waitcnt vmcnt(15)
	v_mov_b64_e32 v[114:115], v[166:167]
	v_mov_b64_e32 v[116:117], v[168:169]
	v_cvt_f32_f16_e32 v122, v114
	v_cvt_f32_f16_sdwa v123, v114 dst_sel:DWORD dst_unused:UNUSED_PAD src0_sel:WORD_1
	v_cvt_f32_f16_e32 v114, v115
	v_cvt_f32_f16_sdwa v115, v115 dst_sel:DWORD dst_unused:UNUSED_PAD src0_sel:WORD_1
	v_pk_fma_f32 v[110:111], v[122:123], s[34:35], v[110:111] op_sel_hi:[1,0,1]
	s_nop 0
	v_cvt_pk_f16_f32 v110, v110, v111
	v_pk_fma_f32 v[112:113], v[114:115], s[34:35], v[112:113] op_sel_hi:[1,0,1]
	v_lshl_add_u64 v[114:115], s[4:5], 0, v[118:119]
	v_cvt_pk_f16_f32 v111, v112, v113
	v_cvt_f32_f16_e32 v112, v116
	v_cvt_f32_f16_sdwa v113, v116 dst_sel:DWORD dst_unused:UNUSED_PAD src0_sel:WORD_1
	v_pk_fma_f32 v[106:107], v[112:113], s[34:35], v[106:107] op_sel_hi:[1,0,1]
	s_nop 0
	v_cvt_pk_f16_f32 v112, v106, v107
	v_cvt_f32_f16_e32 v106, v117
	v_cvt_f32_f16_sdwa v107, v117 dst_sel:DWORD dst_unused:UNUSED_PAD src0_sel:WORD_1
	v_pk_fma_f32 v[106:107], v[106:107], s[34:35], v[108:109] op_sel_hi:[1,0,1]
	s_nop 0
	v_cvt_pk_f16_f32 v113, v106, v107
	s_nop 0
	global_store_dwordx4 v[114:115], v[110:113], off
	s_waitcnt vmcnt(15)
	v_mov_b64_e32 v[106:107], v[170:171]
	v_mov_b64_e32 v[108:109], v[172:173]
	s_nop 0
	v_cvt_f32_f16_e32 v110, v106
	v_cvt_f32_f16_sdwa v111, v106 dst_sel:DWORD dst_unused:UNUSED_PAD src0_sel:WORD_1
	v_cvt_f32_f16_e32 v106, v107
	v_cvt_f32_f16_sdwa v107, v107 dst_sel:DWORD dst_unused:UNUSED_PAD src0_sel:WORD_1
	v_pk_fma_f32 v[102:103], v[110:111], s[34:35], v[102:103] op_sel_hi:[1,0,1]
	s_nop 0
	v_cvt_pk_f16_f32 v102, v102, v103
	v_pk_fma_f32 v[104:105], v[106:107], s[34:35], v[104:105] op_sel_hi:[1,0,1]
	s_nop 0
	v_cvt_pk_f16_f32 v103, v104, v105
	v_cvt_f32_f16_e32 v104, v108
	v_cvt_f32_f16_sdwa v105, v108 dst_sel:DWORD dst_unused:UNUSED_PAD src0_sel:WORD_1
	v_pk_fma_f32 v[98:99], v[104:105], s[34:35], v[98:99] op_sel_hi:[1,0,1]
	s_nop 0
	v_cvt_pk_f16_f32 v104, v98, v99
	v_cvt_f32_f16_e32 v98, v109
	v_cvt_f32_f16_sdwa v99, v109 dst_sel:DWORD dst_unused:UNUSED_PAD src0_sel:WORD_1
	v_pk_fma_f32 v[98:99], v[98:99], s[34:35], v[100:101] op_sel_hi:[1,0,1]
	s_nop 0
	v_cvt_pk_f16_f32 v105, v98, v99
	v_or_b32_e32 v98, 32, v144
	v_ashrrev_i32_e32 v99, 31, v98
	v_lshlrev_b64 v[98:99], 11, v[98:99]
	v_lshl_add_u64 v[98:99], v[98:99], 0, v[142:143]
	global_store_dwordx4 v[114:115], v[102:105], off offset:256
	s_nop 1
	v_lshlrev_b64 v[102:103], 1, v[98:99]
	v_lshl_add_u64 v[104:105], s[94:95], 0, v[102:103]
	s_waitcnt vmcnt(15)
	v_mov_b64_e32 v[98:99], v[174:175]
	v_mov_b64_e32 v[100:101], v[176:177]
	v_cvt_f32_f16_e32 v106, v98
	v_cvt_f32_f16_sdwa v107, v98 dst_sel:DWORD dst_unused:UNUSED_PAD src0_sel:WORD_1
	v_cvt_f32_f16_e32 v98, v99
	v_cvt_f32_f16_sdwa v99, v99 dst_sel:DWORD dst_unused:UNUSED_PAD src0_sel:WORD_1
	v_pk_fma_f32 v[94:95], v[106:107], s[34:35], v[94:95] op_sel_hi:[1,0,1]
	s_nop 0
	v_cvt_pk_f16_f32 v94, v94, v95
	v_pk_fma_f32 v[96:97], v[98:99], s[34:35], v[96:97] op_sel_hi:[1,0,1]
	v_lshl_add_u64 v[98:99], s[4:5], 0, v[102:103]
	v_cvt_pk_f16_f32 v95, v96, v97
	v_cvt_f32_f16_e32 v96, v100
	v_cvt_f32_f16_sdwa v97, v100 dst_sel:DWORD dst_unused:UNUSED_PAD src0_sel:WORD_1
	v_pk_fma_f32 v[90:91], v[96:97], s[34:35], v[90:91] op_sel_hi:[1,0,1]
	s_nop 0
	v_cvt_pk_f16_f32 v96, v90, v91
	v_cvt_f32_f16_e32 v90, v101
	v_cvt_f32_f16_sdwa v91, v101 dst_sel:DWORD dst_unused:UNUSED_PAD src0_sel:WORD_1
	v_pk_fma_f32 v[90:91], v[90:91], s[34:35], v[92:93] op_sel_hi:[1,0,1]
	s_nop 0
	v_cvt_pk_f16_f32 v97, v90, v91
	s_nop 0
	global_store_dwordx4 v[98:99], v[94:97], off
	s_waitcnt vmcnt(15)
;     __device__ __forceinline__ void operator()(const f32x4 (&acc)[2][2][4][2], const Unit& u, int wr, int wc, int fr, int fq) const {
;     ...
;             for (int m = 0; m < 4; ++m) { const size_t off = (size_t)(row0 + ai * 128 + m * 16) * DM + colt;
; #pragma unroll
;                 for (int bj = 0; bj < 2; ++bj) {
;                     const h16x8 x = *(const h16x8*)(X + off + bj * 128);
;                     f32x4 o0, o1;
; #pragma unroll
;                     for (int e = 0; e < 4; ++e) { o0[e] = (float)x[e] * ALPHA + acc[ai][bj][m][0][e]; o1[e] = (float)x[4 + e] * ALPHA + acc[ai][bj][m][1][e]; }
;                     *(u32x4*)(PRE + off + bj * 128) = pack8(o0, o1); } }
	v_mov_b64_e32 v[90:91], v[178:179]
	v_mov_b64_e32 v[92:93], v[180:181]
	s_nop 0
	v_cvt_f32_f16_e32 v94, v90
	v_cvt_f32_f16_sdwa v95, v90 dst_sel:DWORD dst_unused:UNUSED_PAD src0_sel:WORD_1
	v_cvt_f32_f16_e32 v90, v91
	v_cvt_f32_f16_sdwa v91, v91 dst_sel:DWORD dst_unused:UNUSED_PAD src0_sel:WORD_1
	v_pk_fma_f32 v[86:87], v[94:95], s[34:35], v[86:87] op_sel_hi:[1,0,1]
	s_nop 0
	v_cvt_pk_f16_f32 v86, v86, v87
	v_pk_fma_f32 v[88:89], v[90:91], s[34:35], v[88:89] op_sel_hi:[1,0,1]
	s_nop 0
	v_cvt_pk_f16_f32 v87, v88, v89
	v_cvt_f32_f16_e32 v88, v92
	v_cvt_f32_f16_sdwa v89, v92 dst_sel:DWORD dst_unused:UNUSED_PAD src0_sel:WORD_1
	v_pk_fma_f32 v[82:83], v[88:89], s[34:35], v[82:83] op_sel_hi:[1,0,1]
	s_nop 0
	v_cvt_pk_f16_f32 v88, v82, v83
	v_cvt_f32_f16_e32 v82, v93
	v_cvt_f32_f16_sdwa v83, v93 dst_sel:DWORD dst_unused:UNUSED_PAD src0_sel:WORD_1
	v_pk_fma_f32 v[82:83], v[82:83], s[34:35], v[84:85] op_sel_hi:[1,0,1]
	s_nop 0
	v_cvt_pk_f16_f32 v89, v82, v83
	v_or_b32_e32 v82, 48, v144
	v_ashrrev_i32_e32 v83, 31, v82
	v_lshlrev_b64 v[82:83], 11, v[82:83]
	v_lshl_add_u64 v[82:83], v[82:83], 0, v[142:143]
	global_store_dwordx4 v[98:99], v[86:89], off offset:256
	s_nop 1
	v_lshlrev_b64 v[86:87], 1, v[82:83]
	v_lshl_add_u64 v[88:89], s[94:95], 0, v[86:87]
	s_waitcnt vmcnt(15)
	v_mov_b64_e32 v[82:83], v[182:183]
	v_mov_b64_e32 v[84:85], v[184:185]
	v_cvt_f32_f16_e32 v90, v82
	v_cvt_f32_f16_sdwa v91, v82 dst_sel:DWORD dst_unused:UNUSED_PAD src0_sel:WORD_1
	v_cvt_f32_f16_e32 v82, v83
	v_cvt_f32_f16_sdwa v83, v83 dst_sel:DWORD dst_unused:UNUSED_PAD src0_sel:WORD_1
	v_pk_fma_f32 v[78:79], v[90:91], s[34:35], v[78:79] op_sel_hi:[1,0,1]
	s_nop 0
	v_cvt_pk_f16_f32 v78, v78, v79
	v_pk_fma_f32 v[80:81], v[82:83], s[34:35], v[80:81] op_sel_hi:[1,0,1]
	v_lshl_add_u64 v[82:83], s[4:5], 0, v[86:87]
	v_cvt_pk_f16_f32 v79, v80, v81
	v_cvt_f32_f16_e32 v80, v84
	v_cvt_f32_f16_sdwa v81, v84 dst_sel:DWORD dst_unused:UNUSED_PAD src0_sel:WORD_1
	v_pk_fma_f32 v[74:75], v[80:81], s[34:35], v[74:75] op_sel_hi:[1,0,1]
	s_nop 0
	v_cvt_pk_f16_f32 v80, v74, v75
	v_cvt_f32_f16_e32 v74, v85
	v_cvt_f32_f16_sdwa v75, v85 dst_sel:DWORD dst_unused:UNUSED_PAD src0_sel:WORD_1
	v_pk_fma_f32 v[74:75], v[74:75], s[34:35], v[76:77] op_sel_hi:[1,0,1]
	s_nop 0
	v_cvt_pk_f16_f32 v81, v74, v75
	s_nop 0
	global_store_dwordx4 v[82:83], v[78:81], off
	s_waitcnt vmcnt(15)
	v_mov_b64_e32 v[74:75], v[186:187]
	v_mov_b64_e32 v[76:77], v[188:189]
	s_nop 0
	v_cvt_f32_f16_e32 v78, v74
	v_cvt_f32_f16_sdwa v79, v74 dst_sel:DWORD dst_unused:UNUSED_PAD src0_sel:WORD_1
	v_cvt_f32_f16_e32 v74, v75
	v_cvt_f32_f16_sdwa v75, v75 dst_sel:DWORD dst_unused:UNUSED_PAD src0_sel:WORD_1
	v_pk_fma_f32 v[70:71], v[78:79], s[34:35], v[70:71] op_sel_hi:[1,0,1]
	s_nop 0
	v_cvt_pk_f16_f32 v70, v70, v71
	v_pk_fma_f32 v[72:73], v[74:75], s[34:35], v[72:73] op_sel_hi:[1,0,1]
	s_nop 0
	v_cvt_pk_f16_f32 v71, v72, v73
	v_cvt_f32_f16_e32 v72, v76
	v_cvt_f32_f16_sdwa v73, v76 dst_sel:DWORD dst_unused:UNUSED_PAD src0_sel:WORD_1
	v_pk_fma_f32 v[66:67], v[72:73], s[34:35], v[66:67] op_sel_hi:[1,0,1]
	s_nop 0
	v_cvt_pk_f16_f32 v72, v66, v67
	v_cvt_f32_f16_e32 v66, v77
	v_cvt_f32_f16_sdwa v67, v77 dst_sel:DWORD dst_unused:UNUSED_PAD src0_sel:WORD_1
	v_pk_fma_f32 v[66:67], v[66:67], s[34:35], v[68:69] op_sel_hi:[1,0,1]
	s_nop 0
	v_cvt_pk_f16_f32 v73, v66, v67
	global_store_dwordx4 v[82:83], v[70:73], off offset:256
	s_nop 1
	v_lshl_add_u64 v[70:71], v[140:141], 0, s[16:17]
	v_lshl_add_u64 v[72:73], s[94:95], 0, v[70:71]
	s_waitcnt vmcnt(15)
	v_mov_b64_e32 v[66:67], v[190:191]
	v_mov_b64_e32 v[68:69], v[192:193]
	v_cvt_f32_f16_e32 v74, v66
	v_cvt_f32_f16_sdwa v75, v66 dst_sel:DWORD dst_unused:UNUSED_PAD src0_sel:WORD_1
	v_cvt_f32_f16_e32 v66, v67
	v_cvt_f32_f16_sdwa v67, v67 dst_sel:DWORD dst_unused:UNUSED_PAD src0_sel:WORD_1
	v_pk_fma_f32 v[62:63], v[74:75], s[34:35], v[62:63] op_sel_hi:[1,0,1]
	s_nop 0
	v_cvt_pk_f16_f32 v62, v62, v63
	v_pk_fma_f32 v[64:65], v[66:67], s[34:35], v[64:65] op_sel_hi:[1,0,1]
	v_lshl_add_u64 v[66:67], s[4:5], 0, v[70:71]
	v_cvt_pk_f16_f32 v63, v64, v65
	v_cvt_f32_f16_e32 v64, v68
	v_cvt_f32_f16_sdwa v65, v68 dst_sel:DWORD dst_unused:UNUSED_PAD src0_sel:WORD_1
	v_pk_fma_f32 v[58:59], v[64:65], s[34:35], v[58:59] op_sel_hi:[1,0,1]
	s_nop 0
	v_cvt_pk_f16_f32 v64, v58, v59
	v_cvt_f32_f16_e32 v58, v69
	v_cvt_f32_f16_sdwa v59, v69 dst_sel:DWORD dst_unused:UNUSED_PAD src0_sel:WORD_1
	v_pk_fma_f32 v[58:59], v[58:59], s[34:35], v[60:61] op_sel_hi:[1,0,1]
	s_nop 0
	v_cvt_pk_f16_f32 v65, v58, v59
	s_nop 0
	global_store_dwordx4 v[66:67], v[62:65], off
	s_waitcnt vmcnt(15)
	v_mov_b64_e32 v[58:59], v[194:195]
	v_mov_b64_e32 v[60:61], v[196:197]
	s_nop 0
	v_cvt_f32_f16_e32 v62, v58
	v_cvt_f32_f16_sdwa v63, v58 dst_sel:DWORD dst_unused:UNUSED_PAD src0_sel:WORD_1
	v_cvt_f32_f16_e32 v58, v59
	v_cvt_f32_f16_sdwa v59, v59 dst_sel:DWORD dst_unused:UNUSED_PAD src0_sel:WORD_1
	v_pk_fma_f32 v[54:55], v[62:63], s[34:35], v[54:55] op_sel_hi:[1,0,1]
	s_nop 0
	v_cvt_pk_f16_f32 v54, v54, v55
	v_pk_fma_f32 v[56:57], v[58:59], s[34:35], v[56:57] op_sel_hi:[1,0,1]
	s_nop 0
	v_cvt_pk_f16_f32 v55, v56, v57
	v_cvt_f32_f16_e32 v56, v60
	v_cvt_f32_f16_sdwa v57, v60 dst_sel:DWORD dst_unused:UNUSED_PAD src0_sel:WORD_1
	v_pk_fma_f32 v[50:51], v[56:57], s[34:35], v[50:51] op_sel_hi:[1,0,1]
	s_nop 0
	v_cvt_pk_f16_f32 v56, v50, v51
	v_cvt_f32_f16_e32 v50, v61
	v_cvt_f32_f16_sdwa v51, v61 dst_sel:DWORD dst_unused:UNUSED_PAD src0_sel:WORD_1
	v_pk_fma_f32 v[50:51], v[50:51], s[34:35], v[52:53] op_sel_hi:[1,0,1]
	s_nop 0
	v_cvt_pk_f16_f32 v57, v50, v51
	global_store_dwordx4 v[66:67], v[54:57], off offset:256
	s_nop 1
	v_lshl_add_u64 v[54:55], v[140:141], 0, s[18:19]
	v_lshl_add_u64 v[56:57], s[94:95], 0, v[54:55]
	s_waitcnt vmcnt(15)
; #define PG8_WAIT_V(n) asm volatile("s_waitcnt vmcnt(" #n ")" ::: "memory")
; #define PG8_BAR __builtin_amdgcn_s_barrier()
; template <class Epi, class AMap>
; __device__ __forceinline__ void gemm_phase(LAS unsigned char* lds, const AMap am, const int lda, const h16* Bt, const int ldb, const int M, const int N, const int K, const Epi& E) {
;     ...
;         E(acc, cur, wr, wc, fr, fq);
;         if (!has_next) break;
; #pragma unroll
;         for (int a = 0; a < 2; ++a)
; #pragma unroll
;             for (int b = 0; b < 2; ++b)
; #pragma unroll
;                 for (int m = 0; m < 4; ++m)
; #pragma unroll
;                     for (int n = 0; n < 2; ++n) acc[a][b][m][n] = (f32x4){0.f, 0.f, 0.f, 0.f};
;         cur = nxt; cA = nA; cB = nB; ++ui;
;     }
;     PG8_WAIT_V(0);
;     if (wr == 0) PG8_BAR;
;     PG8_BAR;
;     __device__ __forceinline__ void operator()(const f32x4 (&acc)[2][2][4][2], const Unit& u, int wr, int wc, int fr, int fq) const {
;     ...
;             for (int m = 0; m < 4; ++m) { const size_t off = (size_t)(row0 + ai * 128 + m * 16) * DM + colt;
; #pragma unroll
;                 for (int bj = 0; bj < 2; ++bj) {
;                     const h16x8 x = *(const h16x8*)(X + off + bj * 128);
;                     f32x4 o0, o1;
; #pragma unroll
;                     for (int e = 0; e < 4; ++e) { o0[e] = (float)x[e] * ALPHA + acc[ai][bj][m][0][e]; o1[e] = (float)x[4 + e] * ALPHA + acc[ai][bj][m][1][e]; }
;                     *(u32x4*)(PRE + off + bj * 128) = pack8(o0, o1); } }
	v_mov_b64_e32 v[50:51], v[198:199]
	v_mov_b64_e32 v[52:53], v[200:201]
	v_cvt_f32_f16_e32 v58, v50
	v_cvt_f32_f16_sdwa v59, v50 dst_sel:DWORD dst_unused:UNUSED_PAD src0_sel:WORD_1
	v_cvt_f32_f16_e32 v50, v51
	v_cvt_f32_f16_sdwa v51, v51 dst_sel:DWORD dst_unused:UNUSED_PAD src0_sel:WORD_1
	v_pk_fma_f32 v[46:47], v[58:59], s[34:35], v[46:47] op_sel_hi:[1,0,1]
	s_nop 0
	v_cvt_pk_f16_f32 v46, v46, v47
	v_pk_fma_f32 v[48:49], v[50:51], s[34:35], v[48:49] op_sel_hi:[1,0,1]
	v_lshl_add_u64 v[50:51], s[4:5], 0, v[54:55]
	v_cvt_pk_f16_f32 v47, v48, v49
	v_cvt_f32_f16_e32 v48, v52
	v_cvt_f32_f16_sdwa v49, v52 dst_sel:DWORD dst_unused:UNUSED_PAD src0_sel:WORD_1
	v_pk_fma_f32 v[42:43], v[48:49], s[34:35], v[42:43] op_sel_hi:[1,0,1]
	s_nop 0
	v_cvt_pk_f16_f32 v48, v42, v43
	v_cvt_f32_f16_e32 v42, v53
	v_cvt_f32_f16_sdwa v43, v53 dst_sel:DWORD dst_unused:UNUSED_PAD src0_sel:WORD_1
	v_pk_fma_f32 v[42:43], v[42:43], s[34:35], v[44:45] op_sel_hi:[1,0,1]
	s_nop 0
	v_cvt_pk_f16_f32 v49, v42, v43
	s_nop 0
	global_store_dwordx4 v[50:51], v[46:49], off
	s_waitcnt vmcnt(15)
	v_mov_b64_e32 v[42:43], v[202:203]
	v_mov_b64_e32 v[44:45], v[204:205]
	s_nop 0
	v_cvt_f32_f16_e32 v46, v42
	v_cvt_f32_f16_sdwa v47, v42 dst_sel:DWORD dst_unused:UNUSED_PAD src0_sel:WORD_1
	v_cvt_f32_f16_e32 v42, v43
	v_cvt_f32_f16_sdwa v43, v43 dst_sel:DWORD dst_unused:UNUSED_PAD src0_sel:WORD_1
	v_pk_fma_f32 v[38:39], v[46:47], s[34:35], v[38:39] op_sel_hi:[1,0,1]
	s_nop 0
	v_cvt_pk_f16_f32 v38, v38, v39
	v_pk_fma_f32 v[40:41], v[42:43], s[34:35], v[40:41] op_sel_hi:[1,0,1]
	s_nop 0
	v_cvt_pk_f16_f32 v39, v40, v41
	v_cvt_f32_f16_e32 v40, v44
	v_cvt_f32_f16_sdwa v41, v44 dst_sel:DWORD dst_unused:UNUSED_PAD src0_sel:WORD_1
	v_pk_fma_f32 v[34:35], v[40:41], s[34:35], v[34:35] op_sel_hi:[1,0,1]
	s_nop 0
	v_cvt_pk_f16_f32 v40, v34, v35
	v_cvt_f32_f16_e32 v34, v45
	v_cvt_f32_f16_sdwa v35, v45 dst_sel:DWORD dst_unused:UNUSED_PAD src0_sel:WORD_1
	v_pk_fma_f32 v[34:35], v[34:35], s[34:35], v[36:37] op_sel_hi:[1,0,1]
	s_nop 0
	v_cvt_pk_f16_f32 v41, v34, v35
	global_store_dwordx4 v[50:51], v[38:41], off offset:256
	s_nop 1
	v_lshl_add_u64 v[38:39], v[140:141], 0, s[8:9]
	v_lshl_add_u64 v[40:41], s[94:95], 0, v[38:39]
	s_waitcnt vmcnt(15)
	v_mov_b64_e32 v[34:35], v[212:213]
	v_mov_b64_e32 v[36:37], v[214:215]
	v_cvt_f32_f16_e32 v42, v34
	v_cvt_f32_f16_sdwa v43, v34 dst_sel:DWORD dst_unused:UNUSED_PAD src0_sel:WORD_1
	v_cvt_f32_f16_e32 v34, v35
	v_cvt_f32_f16_sdwa v35, v35 dst_sel:DWORD dst_unused:UNUSED_PAD src0_sel:WORD_1
	v_pk_fma_f32 v[30:31], v[42:43], s[34:35], v[30:31] op_sel_hi:[1,0,1]
	s_nop 0
	v_cvt_pk_f16_f32 v30, v30, v31
	v_pk_fma_f32 v[32:33], v[34:35], s[34:35], v[32:33] op_sel_hi:[1,0,1]
	v_lshl_add_u64 v[34:35], s[4:5], 0, v[38:39]
	v_cvt_pk_f16_f32 v31, v32, v33
	v_cvt_f32_f16_e32 v32, v36
	v_cvt_f32_f16_sdwa v33, v36 dst_sel:DWORD dst_unused:UNUSED_PAD src0_sel:WORD_1
	v_pk_fma_f32 v[26:27], v[32:33], s[34:35], v[26:27] op_sel_hi:[1,0,1]
	s_nop 0
	v_cvt_pk_f16_f32 v32, v26, v27
	v_cvt_f32_f16_e32 v26, v37
	v_cvt_f32_f16_sdwa v27, v37 dst_sel:DWORD dst_unused:UNUSED_PAD src0_sel:WORD_1
	v_pk_fma_f32 v[26:27], v[26:27], s[34:35], v[28:29] op_sel_hi:[1,0,1]
	s_nop 0
	v_cvt_pk_f16_f32 v33, v26, v27
	s_nop 0
	global_store_dwordx4 v[34:35], v[30:33], off
	s_waitcnt vmcnt(15)
	v_mov_b64_e32 v[26:27], v[220:221]
	v_mov_b64_e32 v[28:29], v[222:223]
	s_nop 0
	v_cvt_f32_f16_e32 v30, v26
	v_cvt_f32_f16_sdwa v31, v26 dst_sel:DWORD dst_unused:UNUSED_PAD src0_sel:WORD_1
	v_cvt_f32_f16_e32 v26, v27
	v_cvt_f32_f16_sdwa v27, v27 dst_sel:DWORD dst_unused:UNUSED_PAD src0_sel:WORD_1
	v_pk_fma_f32 v[22:23], v[30:31], s[34:35], v[22:23] op_sel_hi:[1,0,1]
	s_nop 0
	v_cvt_pk_f16_f32 v22, v22, v23
	v_pk_fma_f32 v[24:25], v[26:27], s[34:35], v[24:25] op_sel_hi:[1,0,1]
	s_nop 0
	v_cvt_pk_f16_f32 v23, v24, v25
	v_cvt_f32_f16_e32 v24, v28
	v_cvt_f32_f16_sdwa v25, v28 dst_sel:DWORD dst_unused:UNUSED_PAD src0_sel:WORD_1
	v_pk_fma_f32 v[18:19], v[24:25], s[34:35], v[18:19] op_sel_hi:[1,0,1]
	s_nop 0
	v_cvt_pk_f16_f32 v24, v18, v19
	v_cvt_f32_f16_e32 v18, v29
	v_cvt_f32_f16_sdwa v19, v29 dst_sel:DWORD dst_unused:UNUSED_PAD src0_sel:WORD_1
	v_pk_fma_f32 v[18:19], v[18:19], s[34:35], v[20:21] op_sel_hi:[1,0,1]
	s_nop 0
	v_cvt_pk_f16_f32 v25, v18, v19
	global_store_dwordx4 v[34:35], v[22:25], off offset:256
	s_nop 1
	v_lshl_add_u64 v[22:23], v[140:141], 0, s[2:3]
	v_lshl_add_u64 v[24:25], s[94:95], 0, v[22:23]
	s_waitcnt vmcnt(15)
	v_mov_b64_e32 v[18:19], v[224:225]
	v_mov_b64_e32 v[20:21], v[226:227]
	v_cvt_f32_f16_e32 v26, v18
	v_cvt_f32_f16_sdwa v27, v18 dst_sel:DWORD dst_unused:UNUSED_PAD src0_sel:WORD_1
	v_cvt_f32_f16_e32 v18, v19
	v_cvt_f32_f16_sdwa v19, v19 dst_sel:DWORD dst_unused:UNUSED_PAD src0_sel:WORD_1
	v_pk_fma_f32 v[14:15], v[26:27], s[34:35], v[14:15] op_sel_hi:[1,0,1]
	s_nop 0
	v_cvt_pk_f16_f32 v14, v14, v15
	v_pk_fma_f32 v[16:17], v[18:19], s[34:35], v[16:17] op_sel_hi:[1,0,1]
	v_lshl_add_u64 v[18:19], s[4:5], 0, v[22:23]
	v_cvt_pk_f16_f32 v15, v16, v17
	v_cvt_f32_f16_e32 v16, v20
	v_cvt_f32_f16_sdwa v17, v20 dst_sel:DWORD dst_unused:UNUSED_PAD src0_sel:WORD_1
	v_pk_fma_f32 v[10:11], v[16:17], s[34:35], v[10:11] op_sel_hi:[1,0,1]
	s_nop 0
	v_cvt_pk_f16_f32 v16, v10, v11
	v_cvt_f32_f16_e32 v10, v21
	v_cvt_f32_f16_sdwa v11, v21 dst_sel:DWORD dst_unused:UNUSED_PAD src0_sel:WORD_1
	v_pk_fma_f32 v[10:11], v[10:11], s[34:35], v[12:13] op_sel_hi:[1,0,1]
	s_nop 0
	v_cvt_pk_f16_f32 v17, v10, v11
	s_nop 0
	global_store_dwordx4 v[18:19], v[14:17], off
	s_waitcnt vmcnt(15)
	v_mov_b64_e32 v[10:11], v[228:229]
	v_mov_b64_e32 v[12:13], v[230:231]
	s_nop 0
	v_cvt_f32_f16_e32 v14, v10
	v_cvt_f32_f16_sdwa v15, v10 dst_sel:DWORD dst_unused:UNUSED_PAD src0_sel:WORD_1
	v_cvt_f32_f16_e32 v10, v11
	v_cvt_f32_f16_sdwa v11, v11 dst_sel:DWORD dst_unused:UNUSED_PAD src0_sel:WORD_1
	v_pk_fma_f32 v[6:7], v[14:15], s[34:35], v[6:7] op_sel_hi:[1,0,1]
	s_nop 0
	v_cvt_pk_f16_f32 v6, v6, v7
	v_pk_fma_f32 v[8:9], v[10:11], s[34:35], v[8:9] op_sel_hi:[1,0,1]
	s_nop 0
	v_cvt_pk_f16_f32 v7, v8, v9
	v_cvt_f32_f16_e32 v8, v12
	v_cvt_f32_f16_sdwa v9, v12 dst_sel:DWORD dst_unused:UNUSED_PAD src0_sel:WORD_1
	v_pk_fma_f32 v[2:3], v[8:9], s[34:35], v[2:3] op_sel_hi:[1,0,1]
	s_nop 0
	v_cvt_pk_f16_f32 v8, v2, v3
	v_cvt_f32_f16_e32 v2, v13
	v_cvt_f32_f16_sdwa v3, v13 dst_sel:DWORD dst_unused:UNUSED_PAD src0_sel:WORD_1
	v_pk_fma_f32 v[2:3], v[2:3], s[34:35], v[4:5] op_sel_hi:[1,0,1]
	s_nop 0
	v_cvt_pk_f16_f32 v9, v2, v3
	s_mov_b32 s35, s0
	global_store_dwordx4 v[18:19], v[6:9], off offset:256
	s_cbranch_vccz .LBB0_140
	s_waitcnt vmcnt(0)
	s_cmpk_gt_u32 s62, 0xff
	s_cbranch_scc1 .LBB0_151
	s_barrier

; #define PG8_STAGE(bufoff, gbase, voff) do { _Pragma("unroll") for (int _i = 0; _i < 2; ++_i) \
;         __builtin_amdgcn_global_load_lds((const unsigned*)((const char*)(gbase) + (voff)[_i]), (LAS unsigned*)(lds + (bufoff) + ldsw + _i * 8192), 16, 0, 0); } while (0)
; #define PG8_LDA(dst, b, h) do { _Pragma("unroll") for (int m = 0; m < 4; ++m) _Pragma("unroll") for (int k = 0; k < 2; ++k) dst[m][k] = *(const LAS h16x8*)(lds + PG8_SA(b, h) + aoff + m * 2048 + k * 1024); } while (0)
; #define PG8_LDB(dst, b, h) do { _Pragma("unroll") for (int n = 0; n < 2; ++n) _Pragma("unroll") for (int k = 0; k < 2; ++k) dst[n][k] = *(const LAS h16x8*)(lds + PG8_SB(b, h) + boff + n * 2048 + k * 1024); } while (0)
; #define PG8_MMA(ai, bj, At, Bt_) do { __builtin_amdgcn_s_setprio(1); _Pragma("unroll") for (int m = 0; m < 4; ++m) _Pragma("unroll") for (int n = 0; n < 2; ++n) _Pragma("unroll") for (int k = 0; k < 2; ++k) \
;         acc[ai][bj][m][n] = __builtin_amdgcn_mfma_f32_16x16x32_f16(Bt_[n][k], At[m][k], acc[ai][bj][m][n], 0, 0, 0); __builtin_amdgcn_s_setprio(0); } while (0)
; #define PG8_WAIT_V(n) asm volatile("s_waitcnt vmcnt(" #n ")" ::: "memory")
; #define PG8_WAIT_L(n) asm volatile("s_waitcnt lgkmcnt(" #n ")" ::: "memory")
; #define PG8_BAR __builtin_amdgcn_s_barrier()
; #define PG8_SCHED __builtin_amdgcn_sched_barrier(0)
; template <class Epi, class AMap>
; __device__ __forceinline__ void gemm_phase(LAS unsigned char* lds, const AMap am, const int lda, const h16* Bt, const int ldb, const int M, const int N, const int K, const Epi& E) {
;     ...
;             PG8_LDB(B0, 0, 0); PG8_SCHED; PG8_LDA(At, 0, 0); PG8_STAGE(PG8_SA(1, 1), a1 + hstepA, voffA);
;             PG8_WAIT_L(8); PG8_BAR; PG8_WAIT_L(0); PG8_MMA(0, 0, At, B0); PG8_BAR; PG8_SCHED;
;             PG8_LDB(B1, 0, 1); PG8_STAGE(PG8_SB(0, 0), b2, voffB);
;             PG8_BAR; PG8_WAIT_L(0); PG8_MMA(0, 1, At, B1); PG8_BAR;
;             PG8_LDA(At, 0, 1); PG8_STAGE(PG8_SA(0, 0), a2, voffA);
;             PG8_BAR; PG8_WAIT_L(0); PG8_MMA(1, 0, At, B0); PG8_BAR; PG8_SCHED;
;             PG8_STAGE(PG8_SB(0, 1), b2 + hstepB, voffB);
;             PG8_WAIT_V(6); PG8_BAR; PG8_MMA(1, 1, At, B1); PG8_BAR;
.LBB0_268:
	s_add_u32 s42, s40, 0xfff80080
	s_addc_u32 s43, s41, -1
	s_add_i32 s45, 0, 0x10000
	v_add_u32_e32 v0, s45, v149
	ds_read_b128 v[142:145], v0
	ds_read_b128 v[154:157], v0 offset:1024
	ds_read_b128 v[158:161], v0 offset:2048
	ds_read_b128 v[162:165], v0 offset:3072
	s_cmp_eq_u32 s35, 28
	s_cselect_b32 s49, s23, s43
	s_cselect_b32 s48, s27, s42
	s_cselect_b32 s43, s1, s29
	s_cselect_b32 s42, s20, s21
	v_lshl_add_u64 v[146:147], s[40:41], 0, v[138:139]
	s_add_i32 m0, s72, 0xc000
	ds_read_b128 v[166:169], v153
	ds_read_b128 v[170:173], v153 offset:1024
	ds_read_b128 v[174:177], v153 offset:2048
	ds_read_b128 v[178:181], v153 offset:3072
	ds_read_b128 v[182:185], v153 offset:4096
	ds_read_b128 v[186:189], v153 offset:5120
	ds_read_b128 v[190:193], v153 offset:6144
	ds_read_b128 v[194:197], v153 offset:7168
	global_load_lds_dwordx4 v[146:147], off
	v_lshl_add_u64 v[146:147], s[40:41], 0, v[140:141]
	s_add_i32 m0, s72, 0xe000
	s_nop 0
	global_load_lds_dwordx4 v[146:147], off
	s_waitcnt lgkmcnt(11)
	s_add_i32 s60, 0, 0x14000
	s_add_i32 s45, s45, s65
	v_add_u32_e32 v0, s60, v149
	v_lshl_add_u64 v[146:147], s[42:43], 0, v[132:133]
	s_mov_b32 m0, s45
	ds_read_b128 v[198:201], v0
	ds_read_b128 v[202:205], v0 offset:1024
	ds_read_b128 v[220:223], v0 offset:2048
	ds_read_b128 v[224:227], v0 offset:3072
	s_waitcnt vmcnt(8) lgkmcnt(0)
	s_barrier
	v_mfma_f32_16x16x32_f16 v[126:129], v[142:145], v[166:169], v[126:129]
	v_mfma_f32_16x16x32_f16 v[122:125], v[158:161], v[166:169], v[122:125]
	v_mfma_f32_16x16x32_f16 v[110:113], v[142:145], v[174:177], v[110:113]
	v_mfma_f32_16x16x32_f16 v[106:109], v[158:161], v[174:177], v[106:109]
	v_mfma_f32_16x16x32_f16 v[94:97], v[142:145], v[182:185], v[94:97]
	v_mfma_f32_16x16x32_f16 v[90:93], v[158:161], v[182:185], v[90:93]
	v_mfma_f32_16x16x32_f16 v[78:81], v[142:145], v[190:193], v[78:81]
	v_mfma_f32_16x16x32_f16 v[74:77], v[158:161], v[190:193], v[74:77]
	v_mfma_f32_16x16x32_f16 v[126:129], v[154:157], v[170:173], v[126:129]
	v_mfma_f32_16x16x32_f16 v[122:125], v[162:165], v[170:173], v[122:125]
	v_mfma_f32_16x16x32_f16 v[110:113], v[154:157], v[178:181], v[110:113]
	v_mfma_f32_16x16x32_f16 v[106:109], v[162:165], v[178:181], v[106:109]
	v_mfma_f32_16x16x32_f16 v[94:97], v[154:157], v[186:189], v[94:97]
	v_mfma_f32_16x16x32_f16 v[90:93], v[162:165], v[186:189], v[90:93]
	v_mfma_f32_16x16x32_f16 v[78:81], v[154:157], v[194:197], v[78:81]
	v_mfma_f32_16x16x32_f16 v[74:77], v[162:165], v[194:197], v[74:77]
	v_mfma_f32_16x16x32_f16 v[118:121], v[198:201], v[166:169], v[118:121]
	v_mfma_f32_16x16x32_f16 v[114:117], v[220:223], v[166:169], v[114:117]
	v_mfma_f32_16x16x32_f16 v[102:105], v[198:201], v[174:177], v[102:105]
	v_mfma_f32_16x16x32_f16 v[98:101], v[220:223], v[174:177], v[98:101]
	v_mfma_f32_16x16x32_f16 v[86:89], v[198:201], v[182:185], v[86:89]
	v_mfma_f32_16x16x32_f16 v[82:85], v[220:223], v[182:185], v[82:85]
	v_mfma_f32_16x16x32_f16 v[70:73], v[198:201], v[190:193], v[70:73]
	v_mfma_f32_16x16x32_f16 v[66:69], v[220:223], v[190:193], v[66:69]
	v_mfma_f32_16x16x32_f16 v[118:121], v[202:205], v[170:173], v[118:121]
	v_mfma_f32_16x16x32_f16 v[114:117], v[224:227], v[170:173], v[114:117]
	v_mfma_f32_16x16x32_f16 v[102:105], v[202:205], v[178:181], v[102:105]
	v_mfma_f32_16x16x32_f16 v[98:101], v[224:227], v[178:181], v[98:101]
	v_mfma_f32_16x16x32_f16 v[86:89], v[202:205], v[186:189], v[86:89]
	v_mfma_f32_16x16x32_f16 v[82:85], v[224:227], v[186:189], v[82:85]
	v_mfma_f32_16x16x32_f16 v[70:73], v[202:205], v[194:197], v[70:73]
	v_mfma_f32_16x16x32_f16 v[66:69], v[224:227], v[194:197], v[66:69]
	s_barrier
	global_load_lds_dwordx4 v[146:147], off
	v_lshl_add_u64 v[206:207], s[42:43], 0, v[136:137]
	s_add_i32 m0, s45, 0x2000
	s_nop 0
	global_load_lds_dwordx4 v[206:207], off
	s_mov_b32 m0, s72
	v_lshl_add_u64 v[212:213], s[48:49], 0, v[130:131]
	ds_read_b128 v[166:169], v153 offset:16384
	ds_read_b128 v[170:173], v153 offset:17408
	ds_read_b128 v[174:177], v153 offset:18432
	ds_read_b128 v[178:181], v153 offset:19456
	ds_read_b128 v[182:185], v153 offset:20480
	ds_read_b128 v[186:189], v153 offset:21504
	ds_read_b128 v[190:193], v153 offset:22528
	ds_read_b128 v[194:197], v153 offset:23552
	global_load_lds_dwordx4 v[212:213], off
	v_lshl_add_u64 v[228:229], s[48:49], 0, v[134:135]
	s_mov_b32 m0, s73
	s_nop 0
	global_load_lds_dwordx4 v[228:229], off
	s_add_u32 s50, s42, 0x80000
	s_addc_u32 s51, s43, 0
	s_add_i32 s45, s60, s65
	v_lshl_add_u64 v[232:233], s[50:51], 0, v[132:133]
	s_mov_b32 m0, s45
	s_nop 0
	global_load_lds_dwordx4 v[232:233], off
	v_lshl_add_u64 v[232:233], s[50:51], 0, v[136:137]
	s_add_i32 m0, s45, 0x2000
	s_nop 0
	global_load_lds_dwordx4 v[232:233], off
	s_waitcnt vmcnt(8) lgkmcnt(0)
	s_barrier
; #define PG8_STAGE(bufoff, gbase, voff) do { _Pragma("unroll") for (int _i = 0; _i < 2; ++_i) \
;         __builtin_amdgcn_global_load_lds((const unsigned*)((const char*)(gbase) + (voff)[_i]), (LAS unsigned*)(lds + (bufoff) + ldsw + _i * 8192), 16, 0, 0); } while (0)
; #define PG8_LDA(dst, b, h) do { _Pragma("unroll") for (int m = 0; m < 4; ++m) _Pragma("unroll") for (int k = 0; k < 2; ++k) dst[m][k] = *(const LAS h16x8*)(lds + PG8_SA(b, h) + aoff + m * 2048 + k * 1024); } while (0)
; #define PG8_LDB(dst, b, h) do { _Pragma("unroll") for (int n = 0; n < 2; ++n) _Pragma("unroll") for (int k = 0; k < 2; ++k) dst[n][k] = *(const LAS h16x8*)(lds + PG8_SB(b, h) + boff + n * 2048 + k * 1024); } while (0)
; #define PG8_MMA(ai, bj, At, Bt_) do { __builtin_amdgcn_s_setprio(1); _Pragma("unroll") for (int m = 0; m < 4; ++m) _Pragma("unroll") for (int n = 0; n < 2; ++n) _Pragma("unroll") for (int k = 0; k < 2; ++k) \
;         acc[ai][bj][m][n] = __builtin_amdgcn_mfma_f32_16x16x32_f16(Bt_[n][k], At[m][k], acc[ai][bj][m][n], 0, 0, 0); __builtin_amdgcn_s_setprio(0); } while (0)
; #define PG8_WAIT_V(n) asm volatile("s_waitcnt vmcnt(" #n ")" ::: "memory")
; #define PG8_WAIT_L(n) asm volatile("s_waitcnt lgkmcnt(" #n ")" ::: "memory")
; #define PG8_BAR __builtin_amdgcn_s_barrier()
; #define PG8_SCHED __builtin_amdgcn_sched_barrier(0)
; template <class Epi, class AMap>
; __device__ __forceinline__ void gemm_phase(LAS unsigned char* lds, const AMap am, const int lda, const h16* Bt, const int ldb, const int M, const int N, const int K, const Epi& E) {
;     ...
;             PG8_BAR; PG8_WAIT_L(0); PG8_MMA(1, 0, At, B0); PG8_BAR; PG8_SCHED;
;             PG8_STAGE(PG8_SB(0, 1), b2 + hstepB, voffB);
;             PG8_WAIT_V(6); PG8_BAR; PG8_MMA(1, 1, At, B1); PG8_BAR;
;             PG8_LDB(B0, 1, 0); PG8_SCHED; PG8_LDA(At, 1, 0); PG8_STAGE(PG8_SA(0, 1), a2 + hstepA, voffA);
;             PG8_WAIT_L(8); PG8_BAR; PG8_WAIT_L(0); PG8_MMA(0, 0, At, B0); PG8_BAR; PG8_SCHED;
;             PG8_LDB(B1, 1, 1); PG8_STAGE(PG8_SB(1, 0), b3, voffB);
;             PG8_BAR; PG8_WAIT_L(0); PG8_MMA(0, 1, At, B1); PG8_BAR;
	v_mfma_f32_16x16x32_f16 v[62:65], v[142:145], v[166:169], v[62:65]
	v_mfma_f32_16x16x32_f16 v[58:61], v[158:161], v[166:169], v[58:61]
	v_mfma_f32_16x16x32_f16 v[46:49], v[142:145], v[174:177], v[46:49]
	v_mfma_f32_16x16x32_f16 v[42:45], v[158:161], v[174:177], v[42:45]
	v_mfma_f32_16x16x32_f16 v[30:33], v[142:145], v[182:185], v[30:33]
	v_mfma_f32_16x16x32_f16 v[26:29], v[158:161], v[182:185], v[26:29]
	v_mfma_f32_16x16x32_f16 v[14:17], v[142:145], v[190:193], v[14:17]
	v_mfma_f32_16x16x32_f16 v[10:13], v[158:161], v[190:193], v[10:13]
	v_mfma_f32_16x16x32_f16 v[62:65], v[154:157], v[170:173], v[62:65]
	v_mfma_f32_16x16x32_f16 v[58:61], v[162:165], v[170:173], v[58:61]
	v_mfma_f32_16x16x32_f16 v[46:49], v[154:157], v[178:181], v[46:49]
	v_mfma_f32_16x16x32_f16 v[42:45], v[162:165], v[178:181], v[42:45]
	v_mfma_f32_16x16x32_f16 v[30:33], v[154:157], v[186:189], v[30:33]
	v_mfma_f32_16x16x32_f16 v[26:29], v[162:165], v[186:189], v[26:29]
	v_mfma_f32_16x16x32_f16 v[14:17], v[154:157], v[194:197], v[14:17]
	v_mfma_f32_16x16x32_f16 v[10:13], v[162:165], v[194:197], v[10:13]
	v_mfma_f32_16x16x32_f16 v[54:57], v[198:201], v[166:169], v[54:57]
	v_mfma_f32_16x16x32_f16 v[50:53], v[220:223], v[166:169], v[50:53]
	v_mfma_f32_16x16x32_f16 v[38:41], v[198:201], v[174:177], v[38:41]
	v_mfma_f32_16x16x32_f16 v[34:37], v[220:223], v[174:177], v[34:37]
	v_mfma_f32_16x16x32_f16 v[22:25], v[198:201], v[182:185], v[22:25]
	v_mfma_f32_16x16x32_f16 v[18:21], v[220:223], v[182:185], v[18:21]
	v_mfma_f32_16x16x32_f16 v[6:9], v[198:201], v[190:193], v[6:9]
	v_mfma_f32_16x16x32_f16 v[2:5], v[220:223], v[190:193], v[2:5]
	v_mfma_f32_16x16x32_f16 v[54:57], v[202:205], v[170:173], v[54:57]
	v_mfma_f32_16x16x32_f16 v[50:53], v[224:227], v[170:173], v[50:53]
	v_mfma_f32_16x16x32_f16 v[38:41], v[202:205], v[178:181], v[38:41]
	v_mfma_f32_16x16x32_f16 v[34:37], v[224:227], v[178:181], v[34:37]
	v_mfma_f32_16x16x32_f16 v[22:25], v[202:205], v[186:189], v[22:25]
	v_mfma_f32_16x16x32_f16 v[18:21], v[224:227], v[186:189], v[18:21]
	v_mfma_f32_16x16x32_f16 v[6:9], v[202:205], v[194:197], v[6:9]
	v_mfma_f32_16x16x32_f16 v[2:5], v[224:227], v[194:197], v[2:5]
	s_barrier
	s_add_i32 s45, 0, 0x18000
	v_add_u32_e32 v0, s45, v149
	ds_read_b128 v[142:145], v0
	ds_read_b128 v[154:157], v0 offset:1024
	ds_read_b128 v[158:161], v0 offset:2048
	ds_read_b128 v[162:165], v0 offset:3072
	s_add_u32 s48, s48, 0x80000
	s_addc_u32 s49, s49, 0
	s_mov_b32 m0, s74
	v_lshl_add_u64 v[232:233], s[48:49], 0, v[130:131]
	ds_read_b128 v[166:169], v153 offset:32768
	ds_read_b128 v[170:173], v153 offset:33792
	ds_read_b128 v[174:177], v153 offset:34816
	ds_read_b128 v[178:181], v153 offset:35840
	ds_read_b128 v[182:185], v153 offset:36864
	ds_read_b128 v[186:189], v153 offset:37888
	ds_read_b128 v[190:193], v153 offset:38912
	ds_read_b128 v[194:197], v153 offset:39936
	global_load_lds_dwordx4 v[232:233], off
	v_lshl_add_u64 v[232:233], s[48:49], 0, v[134:135]
	s_mov_b32 m0, s75
	s_nop 0
	global_load_lds_dwordx4 v[232:233], off
	s_waitcnt lgkmcnt(11)
	s_add_i32 s48, 0, 0x1c000
	s_add_i32 s45, s45, s65
	v_add_u32_e32 v0, s48, v149
	v_lshl_add_u64 v[146:147], v[146:147], 0, s[92:93]
	s_mov_b32 m0, s45
	ds_read_b128 v[198:201], v0
	ds_read_b128 v[202:205], v0 offset:1024
	ds_read_b128 v[220:223], v0 offset:2048
	ds_read_b128 v[224:227], v0 offset:3072
	s_waitcnt vmcnt(8) lgkmcnt(0)
	s_barrier
	v_mfma_f32_16x16x32_f16 v[126:129], v[142:145], v[166:169], v[126:129]
	v_mfma_f32_16x16x32_f16 v[122:125], v[158:161], v[166:169], v[122:125]
	v_mfma_f32_16x16x32_f16 v[110:113], v[142:145], v[174:177], v[110:113]
	v_mfma_f32_16x16x32_f16 v[106:109], v[158:161], v[174:177], v[106:109]
	v_mfma_f32_16x16x32_f16 v[94:97], v[142:145], v[182:185], v[94:97]
	v_mfma_f32_16x16x32_f16 v[90:93], v[158:161], v[182:185], v[90:93]
	v_mfma_f32_16x16x32_f16 v[78:81], v[142:145], v[190:193], v[78:81]
	v_mfma_f32_16x16x32_f16 v[74:77], v[158:161], v[190:193], v[74:77]
	v_mfma_f32_16x16x32_f16 v[126:129], v[154:157], v[170:173], v[126:129]
	v_mfma_f32_16x16x32_f16 v[122:125], v[162:165], v[170:173], v[122:125]
	v_mfma_f32_16x16x32_f16 v[110:113], v[154:157], v[178:181], v[110:113]
	v_mfma_f32_16x16x32_f16 v[106:109], v[162:165], v[178:181], v[106:109]
	v_mfma_f32_16x16x32_f16 v[94:97], v[154:157], v[186:189], v[94:97]
	v_mfma_f32_16x16x32_f16 v[90:93], v[162:165], v[186:189], v[90:93]
	v_mfma_f32_16x16x32_f16 v[78:81], v[154:157], v[194:197], v[78:81]
	v_mfma_f32_16x16x32_f16 v[74:77], v[162:165], v[194:197], v[74:77]
	v_mfma_f32_16x16x32_f16 v[118:121], v[198:201], v[166:169], v[118:121]
	v_mfma_f32_16x16x32_f16 v[114:117], v[220:223], v[166:169], v[114:117]
	v_mfma_f32_16x16x32_f16 v[102:105], v[198:201], v[174:177], v[102:105]
	v_mfma_f32_16x16x32_f16 v[98:101], v[220:223], v[174:177], v[98:101]
	v_mfma_f32_16x16x32_f16 v[86:89], v[198:201], v[182:185], v[86:89]
	v_mfma_f32_16x16x32_f16 v[82:85], v[220:223], v[182:185], v[82:85]
	v_mfma_f32_16x16x32_f16 v[70:73], v[198:201], v[190:193], v[70:73]
	v_mfma_f32_16x16x32_f16 v[66:69], v[220:223], v[190:193], v[66:69]
	v_mfma_f32_16x16x32_f16 v[118:121], v[202:205], v[170:173], v[118:121]
	v_mfma_f32_16x16x32_f16 v[114:117], v[224:227], v[170:173], v[114:117]
	v_mfma_f32_16x16x32_f16 v[102:105], v[202:205], v[178:181], v[102:105]
	v_mfma_f32_16x16x32_f16 v[98:101], v[224:227], v[178:181], v[98:101]
	v_mfma_f32_16x16x32_f16 v[86:89], v[202:205], v[186:189], v[86:89]
	v_mfma_f32_16x16x32_f16 v[82:85], v[224:227], v[186:189], v[82:85]
	v_mfma_f32_16x16x32_f16 v[70:73], v[202:205], v[194:197], v[70:73]
	v_mfma_f32_16x16x32_f16 v[66:69], v[224:227], v[194:197], v[66:69]
	s_barrier
; #define PG8_STAGE(bufoff, gbase, voff) do { _Pragma("unroll") for (int _i = 0; _i < 2; ++_i) \
;         __builtin_amdgcn_global_load_lds((const unsigned*)((const char*)(gbase) + (voff)[_i]), (LAS unsigned*)(lds + (bufoff) + ldsw + _i * 8192), 16, 0, 0); } while (0)
; #define PG8_LDA(dst, b, h) do { _Pragma("unroll") for (int m = 0; m < 4; ++m) _Pragma("unroll") for (int k = 0; k < 2; ++k) dst[m][k] = *(const LAS h16x8*)(lds + PG8_SA(b, h) + aoff + m * 2048 + k * 1024); } while (0)
; #define PG8_WAIT_V(n) asm volatile("s_waitcnt vmcnt(" #n ")" ::: "memory")
; #define PG8_BAR __builtin_amdgcn_s_barrier()
; template <class Epi, class AMap>
; __device__ __forceinline__ void gemm_phase(LAS unsigned char* lds, const AMap am, const int lda, const h16* Bt, const int ldb, const int M, const int N, const int K, const Epi& E) {
;     ...
;             PG8_LDA(At, 1, 1); PG8_STAGE(PG8_SA(1, 0), a3, voffA);
;             PG8_BAR; PG8_WAIT_L(0); PG8_MMA(1, 0, At, B0); PG8_BAR; PG8_SCHED;
;             PG8_STAGE(PG8_SB(1, 1), b3 + hstepB, voffB);
;             PG8_WAIT_V(6); PG8_BAR; PG8_MMA(1, 1, At, B1); PG8_BAR;
;         }
;     __device__ __forceinline__ void operator()(const f32x4 (&acc)[2][2][4][2], const Unit& u, int wr, int wc, int fr, int fq) const {
;         const int row0 = u.pm * 256 + wr * 64 + fr; const int part = u.pn >> 3; const int colt = (u.pn & 7) * 256 + wc * 32 + 8 * fq;
; #pragma unroll
;         for (int ai = 0; ai < 2; ++ai)
; #pragma unroll
;             for (int m = 0; m < 4; ++m) { const int row = row0 + ai * 128 + m * 16;
; #pragma unroll
;                 for (int bj = 0; bj < 2; ++bj) { const int c = colt + bj * 128;
;                     if (part == 0) *(u32x4*)(Qb + (size_t)row * DM + c) = pack8(acc[ai][bj][m][0] * QSCALE, acc[ai][bj][m][1] * QSCALE);
;                     else if (part == 1) *(u32x4*)(Kb + (size_t)row * DM + c) = pack8(acc[ai][bj][m][0], acc[ai][bj][m][1]);
;                     else {
;                         const int b = row >> 13, t = row & 8191, hd = c >> 8, dv = c & 255;
;                         const int pos = (t & ~12) | ((t & 4) << 1) | ((t & 8) >> 1);
;                         h16* vp = Vt + ((size_t)((b * 8 + hd) * 256 + dv)) * SEQ + pos;
; #pragma unroll
;                         for (int j = 0; j < 4; ++j) { vp[(size_t)j * SEQ] = (h16)acc[ai][bj][m][0][j]; vp[(size_t)(4 + j) * SEQ] = (h16)acc[ai][bj][m][1][j]; }
	global_load_lds_dwordx4 v[146:147], off
	v_lshl_add_u64 v[146:147], v[206:207], 0, s[92:93]
	s_add_i32 m0, s45, 0x2000
	s_nop 0
	global_load_lds_dwordx4 v[146:147], off
	s_mov_b32 m0, s77
	v_lshl_add_u64 v[146:147], v[212:213], 0, s[92:93]
	ds_read_b128 v[166:169], v153 offset:49152
	ds_read_b128 v[170:173], v153 offset:50176
	ds_read_b128 v[174:177], v153 offset:51200
	ds_read_b128 v[178:181], v153 offset:52224
	ds_read_b128 v[182:185], v153 offset:53248
	ds_read_b128 v[186:189], v153 offset:54272
	ds_read_b128 v[190:193], v153 offset:55296
	ds_read_b128 v[194:197], v153 offset:56320
	global_load_lds_dwordx4 v[146:147], off
	v_lshl_add_u64 v[146:147], v[228:229], 0, s[92:93]
	s_mov_b32 m0, s78
	s_nop 0
	global_load_lds_dwordx4 v[146:147], off
	s_add_u32 s42, s42, 0x80080
	s_addc_u32 s43, s43, 0
	s_add_i32 s45, s48, s65
	v_lshl_add_u64 v[232:233], s[42:43], 0, v[132:133]
	s_mov_b32 m0, s45
	s_nop 0
	global_load_lds_dwordx4 v[232:233], off
	v_lshl_add_u64 v[232:233], s[42:43], 0, v[136:137]
	s_add_i32 m0, s45, 0x2000
	s_nop 0
	global_load_lds_dwordx4 v[232:233], off
	s_waitcnt vmcnt(8) lgkmcnt(0)
	s_barrier
	v_mfma_f32_16x16x32_f16 v[62:65], v[142:145], v[166:169], v[62:65]
	v_mfma_f32_16x16x32_f16 v[58:61], v[158:161], v[166:169], v[58:61]
	v_mfma_f32_16x16x32_f16 v[46:49], v[142:145], v[174:177], v[46:49]
	v_mfma_f32_16x16x32_f16 v[42:45], v[158:161], v[174:177], v[42:45]
	v_mfma_f32_16x16x32_f16 v[30:33], v[142:145], v[182:185], v[30:33]
	v_mfma_f32_16x16x32_f16 v[26:29], v[158:161], v[182:185], v[26:29]
	v_mfma_f32_16x16x32_f16 v[14:17], v[142:145], v[190:193], v[14:17]
	v_mfma_f32_16x16x32_f16 v[10:13], v[158:161], v[190:193], v[10:13]
	v_mfma_f32_16x16x32_f16 v[62:65], v[154:157], v[170:173], v[62:65]
	v_mfma_f32_16x16x32_f16 v[58:61], v[162:165], v[170:173], v[58:61]
	v_mfma_f32_16x16x32_f16 v[46:49], v[154:157], v[178:181], v[46:49]
	v_mfma_f32_16x16x32_f16 v[42:45], v[162:165], v[178:181], v[42:45]
	v_mfma_f32_16x16x32_f16 v[30:33], v[154:157], v[186:189], v[30:33]
	v_mfma_f32_16x16x32_f16 v[26:29], v[162:165], v[186:189], v[26:29]
	v_mfma_f32_16x16x32_f16 v[14:17], v[154:157], v[194:197], v[14:17]
	v_mfma_f32_16x16x32_f16 v[10:13], v[162:165], v[194:197], v[10:13]
	v_mfma_f32_16x16x32_f16 v[54:57], v[198:201], v[166:169], v[54:57]
	v_mfma_f32_16x16x32_f16 v[50:53], v[220:223], v[166:169], v[50:53]
	v_mfma_f32_16x16x32_f16 v[38:41], v[198:201], v[174:177], v[38:41]
	v_mfma_f32_16x16x32_f16 v[34:37], v[220:223], v[174:177], v[34:37]
	v_mfma_f32_16x16x32_f16 v[22:25], v[198:201], v[182:185], v[22:25]
	v_mfma_f32_16x16x32_f16 v[18:21], v[220:223], v[182:185], v[18:21]
	v_mfma_f32_16x16x32_f16 v[6:9], v[198:201], v[190:193], v[6:9]
	v_mfma_f32_16x16x32_f16 v[2:5], v[220:223], v[190:193], v[2:5]
	v_mfma_f32_16x16x32_f16 v[54:57], v[202:205], v[170:173], v[54:57]
	v_mfma_f32_16x16x32_f16 v[50:53], v[224:227], v[170:173], v[50:53]
	v_mfma_f32_16x16x32_f16 v[38:41], v[202:205], v[178:181], v[38:41]
	v_mfma_f32_16x16x32_f16 v[34:37], v[224:227], v[178:181], v[34:37]
	v_mfma_f32_16x16x32_f16 v[22:25], v[202:205], v[186:189], v[22:25]
	v_mfma_f32_16x16x32_f16 v[18:21], v[224:227], v[186:189], v[18:21]
	v_mfma_f32_16x16x32_f16 v[6:9], v[202:205], v[194:197], v[6:9]
	v_mfma_f32_16x16x32_f16 v[2:5], v[224:227], v[194:197], v[2:5]
	s_add_i32 s35, s35, 2
	s_add_u32 s40, s40, 0x100
	s_addc_u32 s41, s41, 0
	s_add_u32 s21, s21, 0x100
	s_addc_u32 s29, s29, 0
	s_cmp_gt_u32 s35, 29
	s_barrier
	s_cbranch_scc0 .LBB0_268
	s_lshl_b32 s1, s26, 8
	s_add_i32 s20, s1, s76
	s_lshl_b32 s1, s22, 8
	s_and_b32 s1, s1, 0x700
	s_cmp_gt_u32 s22, 7
	s_cselect_b64 s[26:27], -1, 0
	s_and_b32 s21, s22, -8
	v_or_b32_e32 v142, s20, v148
	s_cmp_lg_u32 s21, 8
	s_cselect_b64 s[22:23], -1, 0
	s_ashr_i32 s20, s20, 2
	v_ashrrev_i32_e32 v143, 31, v142
	v_or_b32_e32 v154, s1, v150
	s_and_b32 s35, s20, 0xfffff800
	v_and_or_b32 v155, v142, s5, v151
	v_lshlrev_b64 v[144:145], 12, v[142:143]
	s_mov_b64 s[40:41], -1
	s_and_b64 vcc, exec, s[26:27]
	s_cbranch_vccz .LBB0_275
	s_and_b64 vcc, exec, s[22:23]
	s_cbranch_vccz .LBB0_272
	v_or_b32_e32 v146, s35, v154
	v_ashrrev_i32_e32 v147, 31, v146
	v_lshlrev_b64 v[146:147], 14, v[146:147]
	v_lshl_add_u64 v[146:147], s[30:31], 0, v[146:147]
	v_lshlrev_b32_e32 v0, 1, v155
	v_lshl_add_u64 v[146:147], v[146:147], 0, v[0:1]
	v_cvt_f16_f32_e32 v0, v126
	v_add_co_u32_e32 v156, vcc, 0x10000, v146
	s_mov_b64 s[40:41], 0
	global_store_short v[146:147], v0, off
	v_cvt_f16_f32_e32 v0, v122
	v_addc_co_u32_e32 v157, vcc, 0, v147, vcc
	global_store_short v[156:157], v0, off
	v_cvt_f16_f32_e32 v0, v127
	v_add_co_u32_e32 v156, vcc, 0x4000, v146
	s_nop 1
	v_addc_co_u32_e32 v157, vcc, 0, v147, vcc
	global_store_short v[156:157], v0, off
	v_cvt_f16_f32_e32 v0, v123
	v_add_co_u32_e32 v156, vcc, 0x14000, v146
	s_nop 1
	v_addc_co_u32_e32 v157, vcc, 0, v147, vcc
	global_store_short v[156:157], v0, off
	v_cvt_f16_f32_e32 v0, v128
	v_add_co_u32_e32 v156, vcc, 0x8000, v146
	s_nop 1
	v_addc_co_u32_e32 v157, vcc, 0, v147, vcc
	global_store_short v[156:157], v0, off
	v_cvt_f16_f32_e32 v0, v124
	v_add_co_u32_e32 v156, vcc, 0x18000, v146
	s_nop 1
	v_addc_co_u32_e32 v157, vcc, 0, v147, vcc
	global_store_short v[156:157], v0, off
	v_cvt_f16_f32_e32 v0, v129
	v_add_co_u32_e32 v156, vcc, 0xc000, v146
	s_nop 1
	v_addc_co_u32_e32 v157, vcc, 0, v147, vcc
	global_store_short v[156:157], v0, off
	v_cvt_f16_f32_e32 v0, v125
	v_add_co_u32_e32 v146, vcc, 0x1c000, v146
	s_nop 1
	v_addc_co_u32_e32 v147, vcc, 0, v147, vcc
	global_store_short v[146:147], v0, off

; #define PG8_STAGE(bufoff, gbase, voff) do { _Pragma("unroll") for (int _i = 0; _i < 2; ++_i) \
;         __builtin_amdgcn_global_load_lds((const unsigned*)((const char*)(gbase) + (voff)[_i]), (LAS unsigned*)(lds + (bufoff) + ldsw + _i * 8192), 16, 0, 0); } while (0)
; #define PG8_LDA(dst, b, h) do { _Pragma("unroll") for (int m = 0; m < 4; ++m) _Pragma("unroll") for (int k = 0; k < 2; ++k) dst[m][k] = *(const LAS h16x8*)(lds + PG8_SA(b, h) + aoff + m * 2048 + k * 1024); } while (0)
; #define PG8_LDB(dst, b, h) do { _Pragma("unroll") for (int n = 0; n < 2; ++n) _Pragma("unroll") for (int k = 0; k < 2; ++k) dst[n][k] = *(const LAS h16x8*)(lds + PG8_SB(b, h) + boff + n * 2048 + k * 1024); } while (0)
; #define PG8_WAIT_V(n) asm volatile("s_waitcnt vmcnt(" #n ")" ::: "memory")
; #define PG8_WAIT_L(n) asm volatile("s_waitcnt lgkmcnt(" #n ")" ::: "memory")
; #define PG8_BAR __builtin_amdgcn_s_barrier()
; #define PG8_SCHED __builtin_amdgcn_sched_barrier(0)
; template <class Epi, class AMap>
; __device__ __forceinline__ void gemm_phase(LAS unsigned char* lds, const AMap am, const int lda, const h16* Bt, const int ldb, const int M, const int N, const int K, const Epi& E) {
;     ...
;         const bool has_next = S.next(ui + 1, nxt);
;         const char* nA = has_next ? am(nxt.pn) + (size_t)nxt.pm * tstepA : cA; const char* nB = has_next ? (const char*)Bt + (size_t)nxt.pn * tstepB : cB;
; #pragma unroll 1
;         for (int t = 0; t < nt; t += 2) {
;             const bool last = (t == nt - 2);
;             const char* a1 = cA + (size_t)(t + 1) * kstep;
;             const char* a2 = last ? nA : cA + (size_t)(t + 2) * kstep; const char* b2 = last ? nB : cB + (size_t)(t + 2) * kstep;
;             const char* a3 = a2 + kstep; const char* b3 = b2 + kstep;
;             PG8_LDB(B0, 0, 0); PG8_SCHED; PG8_LDA(At, 0, 0); PG8_STAGE(PG8_SA(1, 1), a1 + hstepA, voffA);
;             PG8_WAIT_L(8); PG8_BAR; PG8_WAIT_L(0); PG8_MMA(0, 0, At, B0); PG8_BAR; PG8_SCHED;
;             PG8_LDB(B1, 0, 1); PG8_STAGE(PG8_SB(0, 0), b2, voffB);
;             PG8_BAR; PG8_WAIT_L(0); PG8_MMA(0, 1, At, B1); PG8_BAR;
;             PG8_LDA(At, 0, 1); PG8_STAGE(PG8_SA(0, 0), a2, voffA);
;             PG8_BAR; PG8_WAIT_L(0); PG8_MMA(1, 0, At, B0); PG8_BAR; PG8_SCHED;
;             PG8_STAGE(PG8_SB(0, 1), b2 + hstepB, voffB);
;             PG8_WAIT_V(6); PG8_BAR; PG8_MMA(1, 1, At, B1); PG8_BAR;
.LBB0_621:
	s_add_i32 s51, s26, 2
	s_add_u32 s0, s22, 0x100
	s_addc_u32 s1, s23, 0
	s_add_i32 s60, 0, 0x10000
	v_add_u32_e32 v152, s60, v155
	ds_read_b128 v[90:93], v152
	ds_read_b128 v[94:97], v152 offset:1024
	ds_read_b128 v[148:151], v152 offset:2048
	ds_read_b128 v[158:161], v152 offset:3072
	s_cmp_eq_u32 s82, s26
	s_cselect_b32 s26, s21, s29
	s_cselect_b32 s49, s65, s1
	s_cselect_b32 s48, s64, s0
	s_cselect_b32 s27, s20, s45
	v_lshl_add_u64 v[152:153], s[22:23], 0, v[144:145]
	s_add_i32 m0, s76, 0xc000
	ds_read_b128 v[162:165], v157
	ds_read_b128 v[166:169], v157 offset:1024
	ds_read_b128 v[170:173], v157 offset:2048
	ds_read_b128 v[174:177], v157 offset:3072
	ds_read_b128 v[178:181], v157 offset:4096
	ds_read_b128 v[182:185], v157 offset:5120
	ds_read_b128 v[186:189], v157 offset:6144
	ds_read_b128 v[190:193], v157 offset:7168
	global_load_lds_dwordx4 v[152:153], off
	v_lshl_add_u64 v[152:153], s[22:23], 0, v[146:147]
	s_add_i32 m0, s76, 0xe000
	s_nop 0
	global_load_lds_dwordx4 v[152:153], off
	s_waitcnt lgkmcnt(11)
	s_add_i32 s62, 0, 0x14000
	v_add_u32_e32 v152, s62, v155
	s_add_i32 s22, s60, s73
	ds_read_b128 v[194:197], v152
	ds_read_b128 v[198:201], v152 offset:1024
	ds_read_b128 v[202:205], v152 offset:2048
	ds_read_b128 v[220:223], v152 offset:3072
	s_waitcnt vmcnt(8) lgkmcnt(0)
	s_barrier
	v_mfma_f32_16x16x32_f16 v[130:133], v[90:93], v[162:165], v[130:133]
	v_mfma_f32_16x16x32_f16 v[134:137], v[148:151], v[162:165], v[134:137]
	v_mfma_f32_16x16x32_f16 v[126:129], v[90:93], v[170:173], v[126:129]
	v_mfma_f32_16x16x32_f16 v[122:125], v[148:151], v[170:173], v[122:125]
	v_mfma_f32_16x16x32_f16 v[118:121], v[90:93], v[178:181], v[118:121]
	v_mfma_f32_16x16x32_f16 v[114:117], v[148:151], v[178:181], v[114:117]
	v_mfma_f32_16x16x32_f16 v[110:113], v[90:93], v[186:189], v[110:113]
	v_mfma_f32_16x16x32_f16 v[106:109], v[148:151], v[186:189], v[106:109]
	v_mfma_f32_16x16x32_f16 v[130:133], v[94:97], v[166:169], v[130:133]
	v_mfma_f32_16x16x32_f16 v[134:137], v[158:161], v[166:169], v[134:137]
	v_mfma_f32_16x16x32_f16 v[126:129], v[94:97], v[174:177], v[126:129]
	v_mfma_f32_16x16x32_f16 v[122:125], v[158:161], v[174:177], v[122:125]
	v_mfma_f32_16x16x32_f16 v[118:121], v[94:97], v[182:185], v[118:121]
	v_mfma_f32_16x16x32_f16 v[114:117], v[158:161], v[182:185], v[114:117]
	v_mfma_f32_16x16x32_f16 v[110:113], v[94:97], v[190:193], v[110:113]
	v_mfma_f32_16x16x32_f16 v[106:109], v[158:161], v[190:193], v[106:109]
	v_mfma_f32_16x16x32_f16 v[62:65], v[194:197], v[162:165], v[62:65]
	v_mfma_f32_16x16x32_f16 v[58:61], v[202:205], v[162:165], v[58:61]
	v_mfma_f32_16x16x32_f16 v[54:57], v[194:197], v[170:173], v[54:57]
	v_mfma_f32_16x16x32_f16 v[50:53], v[202:205], v[170:173], v[50:53]
	v_mfma_f32_16x16x32_f16 v[46:49], v[194:197], v[178:181], v[46:49]
	v_mfma_f32_16x16x32_f16 v[42:45], v[202:205], v[178:181], v[42:45]
	v_mfma_f32_16x16x32_f16 v[38:41], v[194:197], v[186:189], v[38:41]
	v_mfma_f32_16x16x32_f16 v[34:37], v[202:205], v[186:189], v[34:37]
	v_mfma_f32_16x16x32_f16 v[62:65], v[198:201], v[166:169], v[62:65]
	v_mfma_f32_16x16x32_f16 v[58:61], v[220:223], v[166:169], v[58:61]
	v_mfma_f32_16x16x32_f16 v[54:57], v[198:201], v[174:177], v[54:57]
	v_mfma_f32_16x16x32_f16 v[50:53], v[220:223], v[174:177], v[50:53]
	v_mfma_f32_16x16x32_f16 v[46:49], v[198:201], v[182:185], v[46:49]
	v_mfma_f32_16x16x32_f16 v[42:45], v[220:223], v[182:185], v[42:45]
	v_mfma_f32_16x16x32_f16 v[38:41], v[198:201], v[190:193], v[38:41]
	v_mfma_f32_16x16x32_f16 v[34:37], v[220:223], v[190:193], v[34:37]
	s_barrier
	v_lshl_add_u64 v[152:153], s[26:27], 0, v[0:1]
	s_mov_b32 m0, s22
	v_lshl_add_u64 v[206:207], s[26:27], 0, v[142:143]
	global_load_lds_dwordx4 v[152:153], off
	s_add_i32 m0, s22, 0x2000
	s_nop 0
	global_load_lds_dwordx4 v[206:207], off
	s_mov_b32 m0, s76
	v_lshl_add_u64 v[212:213], s[48:49], 0, v[138:139]
	ds_read_b128 v[162:165], v157 offset:16384
	ds_read_b128 v[166:169], v157 offset:17408
	ds_read_b128 v[170:173], v157 offset:18432
	ds_read_b128 v[174:177], v157 offset:19456
	ds_read_b128 v[178:181], v157 offset:20480
	ds_read_b128 v[182:185], v157 offset:21504
	ds_read_b128 v[186:189], v157 offset:22528
	ds_read_b128 v[190:193], v157 offset:23552
	global_load_lds_dwordx4 v[212:213], off
	v_lshl_add_u64 v[224:225], s[48:49], 0, v[140:141]
	s_mov_b32 m0, s77
	s_nop 0
	global_load_lds_dwordx4 v[224:225], off
	s_add_u32 s22, s26, 0x10000
	s_addc_u32 s23, s27, 0
	s_add_i32 s60, s62, s73
	v_lshl_add_u64 v[232:233], s[22:23], 0, v[0:1]
	s_mov_b32 m0, s60
	s_nop 0
	global_load_lds_dwordx4 v[232:233], off
	v_lshl_add_u64 v[232:233], s[22:23], 0, v[142:143]
	s_add_i32 m0, s60, 0x2000
	s_nop 0
	global_load_lds_dwordx4 v[232:233], off
	s_waitcnt vmcnt(8) lgkmcnt(0)
	s_barrier
; #define PG8_STAGE(bufoff, gbase, voff) do { _Pragma("unroll") for (int _i = 0; _i < 2; ++_i) \
;         __builtin_amdgcn_global_load_lds((const unsigned*)((const char*)(gbase) + (voff)[_i]), (LAS unsigned*)(lds + (bufoff) + ldsw + _i * 8192), 16, 0, 0); } while (0)
; #define PG8_LDA(dst, b, h) do { _Pragma("unroll") for (int m = 0; m < 4; ++m) _Pragma("unroll") for (int k = 0; k < 2; ++k) dst[m][k] = *(const LAS h16x8*)(lds + PG8_SA(b, h) + aoff + m * 2048 + k * 1024); } while (0)
; #define PG8_LDB(dst, b, h) do { _Pragma("unroll") for (int n = 0; n < 2; ++n) _Pragma("unroll") for (int k = 0; k < 2; ++k) dst[n][k] = *(const LAS h16x8*)(lds + PG8_SB(b, h) + boff + n * 2048 + k * 1024); } while (0)
; #define PG8_MMA(ai, bj, At, Bt_) do { __builtin_amdgcn_s_setprio(1); _Pragma("unroll") for (int m = 0; m < 4; ++m) _Pragma("unroll") for (int n = 0; n < 2; ++n) _Pragma("unroll") for (int k = 0; k < 2; ++k) \
;         acc[ai][bj][m][n] = __builtin_amdgcn_mfma_f32_16x16x32_f16(Bt_[n][k], At[m][k], acc[ai][bj][m][n], 0, 0, 0); __builtin_amdgcn_s_setprio(0); } while (0)
; #define PG8_WAIT_V(n) asm volatile("s_waitcnt vmcnt(" #n ")" ::: "memory")
; #define PG8_WAIT_L(n) asm volatile("s_waitcnt lgkmcnt(" #n ")" ::: "memory")
; #define PG8_BAR __builtin_amdgcn_s_barrier()
; #define PG8_SCHED __builtin_amdgcn_sched_barrier(0)
; template <class Epi, class AMap>
; __device__ __forceinline__ void gemm_phase(LAS unsigned char* lds, const AMap am, const int lda, const h16* Bt, const int ldb, const int M, const int N, const int K, const Epi& E) {
;     ...
;             PG8_BAR; PG8_WAIT_L(0); PG8_MMA(1, 0, At, B0); PG8_BAR; PG8_SCHED;
;             PG8_STAGE(PG8_SB(0, 1), b2 + hstepB, voffB);
;             PG8_WAIT_V(6); PG8_BAR; PG8_MMA(1, 1, At, B1); PG8_BAR;
;             PG8_LDB(B0, 1, 0); PG8_SCHED; PG8_LDA(At, 1, 0); PG8_STAGE(PG8_SA(0, 1), a2 + hstepA, voffA);
;             PG8_WAIT_L(8); PG8_BAR; PG8_WAIT_L(0); PG8_MMA(0, 0, At, B0); PG8_BAR; PG8_SCHED;
;             PG8_LDB(B1, 1, 1); PG8_STAGE(PG8_SB(1, 0), b3, voffB);
;             PG8_BAR; PG8_WAIT_L(0); PG8_MMA(0, 1, At, B1); PG8_BAR;
	v_mfma_f32_16x16x32_f16 v[102:105], v[90:93], v[162:165], v[102:105]
	v_mfma_f32_16x16x32_f16 v[98:101], v[148:151], v[162:165], v[98:101]
	v_mfma_f32_16x16x32_f16 v[86:89], v[90:93], v[170:173], v[86:89]
	v_mfma_f32_16x16x32_f16 v[82:85], v[148:151], v[170:173], v[82:85]
	v_mfma_f32_16x16x32_f16 v[78:81], v[90:93], v[178:181], v[78:81]
	v_mfma_f32_16x16x32_f16 v[74:77], v[148:151], v[178:181], v[74:77]
	v_mfma_f32_16x16x32_f16 v[70:73], v[90:93], v[186:189], v[70:73]
	v_mfma_f32_16x16x32_f16 v[66:69], v[148:151], v[186:189], v[66:69]
	v_mfma_f32_16x16x32_f16 v[102:105], v[94:97], v[166:169], v[102:105]
	v_mfma_f32_16x16x32_f16 v[98:101], v[158:161], v[166:169], v[98:101]
	v_mfma_f32_16x16x32_f16 v[86:89], v[94:97], v[174:177], v[86:89]
	v_mfma_f32_16x16x32_f16 v[82:85], v[158:161], v[174:177], v[82:85]
	v_mfma_f32_16x16x32_f16 v[78:81], v[94:97], v[182:185], v[78:81]
	v_mfma_f32_16x16x32_f16 v[74:77], v[158:161], v[182:185], v[74:77]
	v_mfma_f32_16x16x32_f16 v[70:73], v[94:97], v[190:193], v[70:73]
	v_mfma_f32_16x16x32_f16 v[66:69], v[158:161], v[190:193], v[66:69]
	v_mfma_f32_16x16x32_f16 v[30:33], v[194:197], v[162:165], v[30:33]
	v_mfma_f32_16x16x32_f16 v[26:29], v[202:205], v[162:165], v[26:29]
	v_mfma_f32_16x16x32_f16 v[22:25], v[194:197], v[170:173], v[22:25]
	v_mfma_f32_16x16x32_f16 v[18:21], v[202:205], v[170:173], v[18:21]
	v_mfma_f32_16x16x32_f16 v[14:17], v[194:197], v[178:181], v[14:17]
	v_mfma_f32_16x16x32_f16 v[10:13], v[202:205], v[178:181], v[10:13]
	v_mfma_f32_16x16x32_f16 v[6:9], v[194:197], v[186:189], v[6:9]
	v_mfma_f32_16x16x32_f16 v[2:5], v[202:205], v[186:189], v[2:5]
	v_mfma_f32_16x16x32_f16 v[30:33], v[198:201], v[166:169], v[30:33]
	v_mfma_f32_16x16x32_f16 v[26:29], v[220:223], v[166:169], v[26:29]
	v_mfma_f32_16x16x32_f16 v[22:25], v[198:201], v[174:177], v[22:25]
	v_mfma_f32_16x16x32_f16 v[18:21], v[220:223], v[174:177], v[18:21]
	v_mfma_f32_16x16x32_f16 v[14:17], v[198:201], v[182:185], v[14:17]
	v_mfma_f32_16x16x32_f16 v[10:13], v[220:223], v[182:185], v[10:13]
	v_mfma_f32_16x16x32_f16 v[6:9], v[198:201], v[190:193], v[6:9]
	v_mfma_f32_16x16x32_f16 v[2:5], v[220:223], v[190:193], v[2:5]
	s_barrier
	s_add_i32 s60, 0, 0x18000
	v_add_u32_e32 v234, s60, v155
	ds_read_b128 v[90:93], v234
	ds_read_b128 v[94:97], v234 offset:1024
	ds_read_b128 v[148:151], v234 offset:2048
	ds_read_b128 v[158:161], v234 offset:3072
	s_add_u32 s22, s48, 0x1c0000
	s_addc_u32 s23, s49, 0
	s_mov_b32 m0, s78
	v_lshl_add_u64 v[232:233], s[22:23], 0, v[138:139]
	ds_read_b128 v[162:165], v157 offset:32768
	ds_read_b128 v[166:169], v157 offset:33792
	ds_read_b128 v[170:173], v157 offset:34816
	ds_read_b128 v[174:177], v157 offset:35840
	ds_read_b128 v[178:181], v157 offset:36864
	ds_read_b128 v[182:185], v157 offset:37888
	ds_read_b128 v[186:189], v157 offset:38912
	ds_read_b128 v[190:193], v157 offset:39936
	global_load_lds_dwordx4 v[232:233], off
	v_lshl_add_u64 v[232:233], s[22:23], 0, v[140:141]
	s_mov_b32 m0, s79
	s_nop 0
	global_load_lds_dwordx4 v[232:233], off
	s_waitcnt lgkmcnt(11)
	s_add_i32 s48, 0, 0x1c000
	s_add_i32 s22, s60, s73
	v_add_u32_e32 v214, s48, v155
	v_lshl_add_u64 v[152:153], v[152:153], 0, s[92:93]
	s_mov_b32 m0, s22
	ds_read_b128 v[194:197], v214
	ds_read_b128 v[198:201], v214 offset:1024
	ds_read_b128 v[202:205], v214 offset:2048
	ds_read_b128 v[220:223], v214 offset:3072
	s_waitcnt vmcnt(8) lgkmcnt(0)
	s_barrier
	v_mfma_f32_16x16x32_f16 v[130:133], v[90:93], v[162:165], v[130:133]
	v_mfma_f32_16x16x32_f16 v[134:137], v[148:151], v[162:165], v[134:137]
	v_mfma_f32_16x16x32_f16 v[126:129], v[90:93], v[170:173], v[126:129]
	v_mfma_f32_16x16x32_f16 v[122:125], v[148:151], v[170:173], v[122:125]
	v_mfma_f32_16x16x32_f16 v[118:121], v[90:93], v[178:181], v[118:121]
	v_mfma_f32_16x16x32_f16 v[114:117], v[148:151], v[178:181], v[114:117]
	v_mfma_f32_16x16x32_f16 v[110:113], v[90:93], v[186:189], v[110:113]
	v_mfma_f32_16x16x32_f16 v[106:109], v[148:151], v[186:189], v[106:109]
	v_mfma_f32_16x16x32_f16 v[130:133], v[94:97], v[166:169], v[130:133]
	v_mfma_f32_16x16x32_f16 v[134:137], v[158:161], v[166:169], v[134:137]
	v_mfma_f32_16x16x32_f16 v[126:129], v[94:97], v[174:177], v[126:129]
	v_mfma_f32_16x16x32_f16 v[122:125], v[158:161], v[174:177], v[122:125]
	v_mfma_f32_16x16x32_f16 v[118:121], v[94:97], v[182:185], v[118:121]
	v_mfma_f32_16x16x32_f16 v[114:117], v[158:161], v[182:185], v[114:117]
	v_mfma_f32_16x16x32_f16 v[110:113], v[94:97], v[190:193], v[110:113]
	v_mfma_f32_16x16x32_f16 v[106:109], v[158:161], v[190:193], v[106:109]
	v_mfma_f32_16x16x32_f16 v[62:65], v[194:197], v[162:165], v[62:65]
	v_mfma_f32_16x16x32_f16 v[58:61], v[202:205], v[162:165], v[58:61]
	v_mfma_f32_16x16x32_f16 v[54:57], v[194:197], v[170:173], v[54:57]
	v_mfma_f32_16x16x32_f16 v[50:53], v[202:205], v[170:173], v[50:53]
	v_mfma_f32_16x16x32_f16 v[46:49], v[194:197], v[178:181], v[46:49]
	v_mfma_f32_16x16x32_f16 v[42:45], v[202:205], v[178:181], v[42:45]
	v_mfma_f32_16x16x32_f16 v[38:41], v[194:197], v[186:189], v[38:41]
	v_mfma_f32_16x16x32_f16 v[34:37], v[202:205], v[186:189], v[34:37]
	v_mfma_f32_16x16x32_f16 v[62:65], v[198:201], v[166:169], v[62:65]
	v_mfma_f32_16x16x32_f16 v[58:61], v[220:223], v[166:169], v[58:61]
	v_mfma_f32_16x16x32_f16 v[54:57], v[198:201], v[174:177], v[54:57]
	v_mfma_f32_16x16x32_f16 v[50:53], v[220:223], v[174:177], v[50:53]
	v_mfma_f32_16x16x32_f16 v[46:49], v[198:201], v[182:185], v[46:49]
	v_mfma_f32_16x16x32_f16 v[42:45], v[220:223], v[182:185], v[42:45]
	v_mfma_f32_16x16x32_f16 v[38:41], v[198:201], v[190:193], v[38:41]
	v_mfma_f32_16x16x32_f16 v[34:37], v[220:223], v[190:193], v[34:37]
	s_barrier
; #define PG8_STAGE(bufoff, gbase, voff) do { _Pragma("unroll") for (int _i = 0; _i < 2; ++_i) \
;         __builtin_amdgcn_global_load_lds((const unsigned*)((const char*)(gbase) + (voff)[_i]), (LAS unsigned*)(lds + (bufoff) + ldsw + _i * 8192), 16, 0, 0); } while (0)
; #define PG8_LDA(dst, b, h) do { _Pragma("unroll") for (int m = 0; m < 4; ++m) _Pragma("unroll") for (int k = 0; k < 2; ++k) dst[m][k] = *(const LAS h16x8*)(lds + PG8_SA(b, h) + aoff + m * 2048 + k * 1024); } while (0)
; #define PG8_MMA(ai, bj, At, Bt_) do { __builtin_amdgcn_s_setprio(1); _Pragma("unroll") for (int m = 0; m < 4; ++m) _Pragma("unroll") for (int n = 0; n < 2; ++n) _Pragma("unroll") for (int k = 0; k < 2; ++k) \
;         acc[ai][bj][m][n] = __builtin_amdgcn_mfma_f32_16x16x32_f16(Bt_[n][k], At[m][k], acc[ai][bj][m][n], 0, 0, 0); __builtin_amdgcn_s_setprio(0); } while (0)
; #define PG8_WAIT_V(n) asm volatile("s_waitcnt vmcnt(" #n ")" ::: "memory")
; #define PG8_WAIT_L(n) asm volatile("s_waitcnt lgkmcnt(" #n ")" ::: "memory")
; #define PG8_BAR __builtin_amdgcn_s_barrier()
; #define PG8_SCHED __builtin_amdgcn_sched_barrier(0)
; template <class Epi, class AMap>
; __device__ __forceinline__ void gemm_phase(LAS unsigned char* lds, const AMap am, const int lda, const h16* Bt, const int ldb, const int M, const int N, const int K, const Epi& E) {
;     ...
;             PG8_LDA(At, 1, 1); PG8_STAGE(PG8_SA(1, 0), a3, voffA);
;             PG8_BAR; PG8_WAIT_L(0); PG8_MMA(1, 0, At, B0); PG8_BAR; PG8_SCHED;
;             PG8_STAGE(PG8_SB(1, 1), b3 + hstepB, voffB);
;             PG8_WAIT_V(6); PG8_BAR; PG8_MMA(1, 1, At, B1); PG8_BAR;
;         }
	global_load_lds_dwordx4 v[152:153], off
	v_lshl_add_u64 v[152:153], v[206:207], 0, s[92:93]
	s_add_i32 m0, s22, 0x2000
	s_nop 0
	global_load_lds_dwordx4 v[152:153], off
	s_mov_b32 m0, s80
	v_lshl_add_u64 v[152:153], v[212:213], 0, s[92:93]
	ds_read_b128 v[162:165], v157 offset:49152
	ds_read_b128 v[166:169], v157 offset:50176
	ds_read_b128 v[170:173], v157 offset:51200
	ds_read_b128 v[174:177], v157 offset:52224
	ds_read_b128 v[178:181], v157 offset:53248
	ds_read_b128 v[182:185], v157 offset:54272
	ds_read_b128 v[186:189], v157 offset:55296
	ds_read_b128 v[190:193], v157 offset:56320
	global_load_lds_dwordx4 v[152:153], off
	v_lshl_add_u64 v[152:153], v[224:225], 0, s[92:93]
	s_mov_b32 m0, s81
	s_nop 0
	global_load_lds_dwordx4 v[152:153], off
	s_add_u32 s22, s26, 0x10080
	s_addc_u32 s23, s27, 0
	s_add_i32 s26, s48, s73
	v_lshl_add_u64 v[232:233], s[22:23], 0, v[0:1]
	s_mov_b32 m0, s26
	s_nop 0
	global_load_lds_dwordx4 v[232:233], off
	v_lshl_add_u64 v[232:233], s[22:23], 0, v[142:143]
	s_add_i32 m0, s26, 0x2000
	s_nop 0
	global_load_lds_dwordx4 v[232:233], off
	s_waitcnt vmcnt(8) lgkmcnt(0)
	s_barrier
	v_mfma_f32_16x16x32_f16 v[102:105], v[90:93], v[162:165], v[102:105]
	v_mfma_f32_16x16x32_f16 v[98:101], v[148:151], v[162:165], v[98:101]
	v_mfma_f32_16x16x32_f16 v[86:89], v[90:93], v[170:173], v[86:89]
	v_mfma_f32_16x16x32_f16 v[82:85], v[148:151], v[170:173], v[82:85]
	v_mfma_f32_16x16x32_f16 v[78:81], v[90:93], v[178:181], v[78:81]
	v_mfma_f32_16x16x32_f16 v[74:77], v[148:151], v[178:181], v[74:77]
	v_mfma_f32_16x16x32_f16 v[70:73], v[90:93], v[186:189], v[70:73]
	v_mfma_f32_16x16x32_f16 v[66:69], v[148:151], v[186:189], v[66:69]
	v_mfma_f32_16x16x32_f16 v[102:105], v[94:97], v[166:169], v[102:105]
	v_mfma_f32_16x16x32_f16 v[98:101], v[158:161], v[166:169], v[98:101]
	v_mfma_f32_16x16x32_f16 v[86:89], v[94:97], v[174:177], v[86:89]
	v_mfma_f32_16x16x32_f16 v[82:85], v[158:161], v[174:177], v[82:85]
	v_mfma_f32_16x16x32_f16 v[78:81], v[94:97], v[182:185], v[78:81]
	v_mfma_f32_16x16x32_f16 v[74:77], v[158:161], v[182:185], v[74:77]
	v_mfma_f32_16x16x32_f16 v[70:73], v[94:97], v[190:193], v[70:73]
	v_mfma_f32_16x16x32_f16 v[66:69], v[158:161], v[190:193], v[66:69]
	v_mfma_f32_16x16x32_f16 v[30:33], v[194:197], v[162:165], v[30:33]
	v_mfma_f32_16x16x32_f16 v[26:29], v[202:205], v[162:165], v[26:29]
	v_mfma_f32_16x16x32_f16 v[22:25], v[194:197], v[170:173], v[22:25]
	v_mfma_f32_16x16x32_f16 v[18:21], v[202:205], v[170:173], v[18:21]
	v_mfma_f32_16x16x32_f16 v[14:17], v[194:197], v[178:181], v[14:17]
	v_mfma_f32_16x16x32_f16 v[10:13], v[202:205], v[178:181], v[10:13]
	v_mfma_f32_16x16x32_f16 v[6:9], v[194:197], v[186:189], v[6:9]
	v_mfma_f32_16x16x32_f16 v[2:5], v[202:205], v[186:189], v[2:5]
	v_mfma_f32_16x16x32_f16 v[30:33], v[198:201], v[166:169], v[30:33]
	v_mfma_f32_16x16x32_f16 v[26:29], v[220:223], v[166:169], v[26:29]
	v_mfma_f32_16x16x32_f16 v[22:25], v[198:201], v[174:177], v[22:25]
	v_mfma_f32_16x16x32_f16 v[18:21], v[220:223], v[174:177], v[18:21]
	v_mfma_f32_16x16x32_f16 v[14:17], v[198:201], v[182:185], v[14:17]
	v_mfma_f32_16x16x32_f16 v[10:13], v[220:223], v[182:185], v[10:13]
	v_mfma_f32_16x16x32_f16 v[6:9], v[198:201], v[190:193], v[6:9]
	v_mfma_f32_16x16x32_f16 v[2:5], v[220:223], v[190:193], v[2:5]
	s_add_u32 s29, s29, 0x100
	s_addc_u32 s45, s45, 0
	s_cmp_ge_i32 s51, s24
	s_mov_b64 s[22:23], s[0:1]
	s_mov_b32 s26, s51
	s_barrier
	s_cbranch_scc0 .LBB0_621
	s_branch .LBB0_610

; #define PG8_STAGE(bufoff, gbase, voff) do { _Pragma("unroll") for (int _i = 0; _i < 2; ++_i) \
;         __builtin_amdgcn_global_load_lds((const unsigned*)((const char*)(gbase) + (voff)[_i]), (LAS unsigned*)(lds + (bufoff) + ldsw + _i * 8192), 16, 0, 0); } while (0)
; #define PG8_LDA(dst, b, h) do { _Pragma("unroll") for (int m = 0; m < 4; ++m) _Pragma("unroll") for (int k = 0; k < 2; ++k) dst[m][k] = *(const LAS h16x8*)(lds + PG8_SA(b, h) + aoff + m * 2048 + k * 1024); } while (0)
; #define PG8_LDB(dst, b, h) do { _Pragma("unroll") for (int n = 0; n < 2; ++n) _Pragma("unroll") for (int k = 0; k < 2; ++k) dst[n][k] = *(const LAS h16x8*)(lds + PG8_SB(b, h) + boff + n * 2048 + k * 1024); } while (0)
; #define PG8_MMA(ai, bj, At, Bt_) do { __builtin_amdgcn_s_setprio(1); _Pragma("unroll") for (int m = 0; m < 4; ++m) _Pragma("unroll") for (int n = 0; n < 2; ++n) _Pragma("unroll") for (int k = 0; k < 2; ++k) \
;         acc[ai][bj][m][n] = __builtin_amdgcn_mfma_f32_16x16x32_f16(Bt_[n][k], At[m][k], acc[ai][bj][m][n], 0, 0, 0); __builtin_amdgcn_s_setprio(0); } while (0)
; #define PG8_WAIT_V(n) asm volatile("s_waitcnt vmcnt(" #n ")" ::: "memory")
; #define PG8_WAIT_L(n) asm volatile("s_waitcnt lgkmcnt(" #n ")" ::: "memory")
; template <class Epi, class AMap>
; __device__ __forceinline__ void gemm_phase(LAS unsigned char* lds, const AMap am, const int lda, const h16* Bt, const int ldb, const int M, const int N, const int K, const Epi& E) {
;     ...
;             const bool last = (t == nt - 2);
;             const char* a1 = cA + (size_t)(t + 1) * kstep;
;             const char* a2 = last ? nA : cA + (size_t)(t + 2) * kstep; const char* b2 = last ? nB : cB + (size_t)(t + 2) * kstep;
;             const char* a3 = a2 + kstep; const char* b3 = b2 + kstep;
;             PG8_LDB(B0, 0, 0); PG8_SCHED; PG8_LDA(At, 0, 0); PG8_STAGE(PG8_SA(1, 1), a1 + hstepA, voffA);
;             PG8_WAIT_L(8); PG8_BAR; PG8_WAIT_L(0); PG8_MMA(0, 0, At, B0); PG8_BAR; PG8_SCHED;
;             PG8_LDB(B1, 0, 1); PG8_STAGE(PG8_SB(0, 0), b2, voffB);
;             PG8_BAR; PG8_WAIT_L(0); PG8_MMA(0, 1, At, B1); PG8_BAR;
;             PG8_LDA(At, 0, 1); PG8_STAGE(PG8_SA(0, 0), a2, voffA);
;             PG8_BAR; PG8_WAIT_L(0); PG8_MMA(1, 0, At, B0); PG8_BAR; PG8_SCHED;
;             PG8_STAGE(PG8_SB(0, 1), b2 + hstepB, voffB);
;             PG8_WAIT_V(6); PG8_BAR; PG8_MMA(1, 1, At, B1); PG8_BAR;
.LBB0_644:
	s_add_i32 s51, s26, 2
	s_add_u32 s0, s22, 0x100
	s_addc_u32 s1, s23, 0
	s_add_i32 s60, 0, 0x10000
	v_add_u32_e32 v234, s60, v203
	ds_read_b128 v[130:133], v234
	ds_read_b128 v[134:137], v234 offset:1024
	ds_read_b128 v[138:141], v234 offset:2048
	ds_read_b128 v[152:155], v234 offset:3072
	s_cmp_eq_u32 s80, s26
	s_cselect_b32 s26, s21, s29
	s_cselect_b32 s49, s47, s1
	s_cselect_b32 s48, s46, s0
	s_cselect_b32 s27, s20, s45
	v_lshl_add_u64 v[232:233], s[22:23], 0, v[148:149]
	s_add_i32 m0, s74, 0xc000
	ds_read_b128 v[156:159], v205
	ds_read_b128 v[160:163], v205 offset:1024
	ds_read_b128 v[164:167], v205 offset:2048
	ds_read_b128 v[168:171], v205 offset:3072
	ds_read_b128 v[172:175], v205 offset:4096
	ds_read_b128 v[176:179], v205 offset:5120
	ds_read_b128 v[180:183], v205 offset:6144
	ds_read_b128 v[184:187], v205 offset:7168
	global_load_lds_dwordx4 v[232:233], off
	v_lshl_add_u64 v[232:233], s[22:23], 0, v[150:151]
	s_add_i32 m0, s74, 0xe000
	s_nop 0
	global_load_lds_dwordx4 v[232:233], off
	s_waitcnt lgkmcnt(11)
	s_add_i32 s62, 0, 0x14000
	v_add_u32_e32 v200, s62, v203
	s_add_i32 s22, s60, s71
	ds_read_b128 v[188:191], v200
	ds_read_b128 v[192:195], v200 offset:1024
	ds_read_b128 v[196:199], v200 offset:2048
	ds_read_b128 v[220:223], v200 offset:3072
	s_waitcnt vmcnt(8) lgkmcnt(0)
	s_barrier
	v_mfma_f32_16x16x32_f16 v[122:125], v[130:133], v[156:159], v[122:125]
	v_mfma_f32_16x16x32_f16 v[126:129], v[138:141], v[156:159], v[126:129]
	v_mfma_f32_16x16x32_f16 v[110:113], v[130:133], v[164:167], v[110:113]
	v_mfma_f32_16x16x32_f16 v[106:109], v[138:141], v[164:167], v[106:109]
	v_mfma_f32_16x16x32_f16 v[94:97], v[130:133], v[172:175], v[94:97]
	v_mfma_f32_16x16x32_f16 v[90:93], v[138:141], v[172:175], v[90:93]
	v_mfma_f32_16x16x32_f16 v[78:81], v[130:133], v[180:183], v[78:81]
	v_mfma_f32_16x16x32_f16 v[74:77], v[138:141], v[180:183], v[74:77]
	v_mfma_f32_16x16x32_f16 v[122:125], v[134:137], v[160:163], v[122:125]
	v_mfma_f32_16x16x32_f16 v[126:129], v[152:155], v[160:163], v[126:129]
	v_mfma_f32_16x16x32_f16 v[110:113], v[134:137], v[168:171], v[110:113]
	v_mfma_f32_16x16x32_f16 v[106:109], v[152:155], v[168:171], v[106:109]
	v_mfma_f32_16x16x32_f16 v[94:97], v[134:137], v[176:179], v[94:97]
	v_mfma_f32_16x16x32_f16 v[90:93], v[152:155], v[176:179], v[90:93]
	v_mfma_f32_16x16x32_f16 v[78:81], v[134:137], v[184:187], v[78:81]
	v_mfma_f32_16x16x32_f16 v[74:77], v[152:155], v[184:187], v[74:77]
	v_mfma_f32_16x16x32_f16 v[118:121], v[188:191], v[156:159], v[118:121]
	v_mfma_f32_16x16x32_f16 v[114:117], v[196:199], v[156:159], v[114:117]
	v_mfma_f32_16x16x32_f16 v[102:105], v[188:191], v[164:167], v[102:105]
	v_mfma_f32_16x16x32_f16 v[98:101], v[196:199], v[164:167], v[98:101]
	v_mfma_f32_16x16x32_f16 v[86:89], v[188:191], v[172:175], v[86:89]
	v_mfma_f32_16x16x32_f16 v[82:85], v[196:199], v[172:175], v[82:85]
	v_mfma_f32_16x16x32_f16 v[70:73], v[188:191], v[180:183], v[70:73]
	v_mfma_f32_16x16x32_f16 v[66:69], v[196:199], v[180:183], v[66:69]
	v_mfma_f32_16x16x32_f16 v[118:121], v[192:195], v[160:163], v[118:121]
	v_mfma_f32_16x16x32_f16 v[114:117], v[220:223], v[160:163], v[114:117]
	v_mfma_f32_16x16x32_f16 v[102:105], v[192:195], v[168:171], v[102:105]
	v_mfma_f32_16x16x32_f16 v[98:101], v[220:223], v[168:171], v[98:101]
	v_mfma_f32_16x16x32_f16 v[86:89], v[192:195], v[176:179], v[86:89]
	v_mfma_f32_16x16x32_f16 v[82:85], v[220:223], v[176:179], v[82:85]
	v_mfma_f32_16x16x32_f16 v[70:73], v[192:195], v[184:187], v[70:73]
	v_mfma_f32_16x16x32_f16 v[66:69], v[220:223], v[184:187], v[66:69]
	s_barrier
	v_lshl_add_u64 v[200:201], s[26:27], 0, v[0:1]
	s_mov_b32 m0, s22
	v_lshl_add_u64 v[206:207], s[26:27], 0, v[146:147]
	global_load_lds_dwordx4 v[200:201], off
	s_add_i32 m0, s22, 0x2000
	s_nop 0
	global_load_lds_dwordx4 v[206:207], off
	s_mov_b32 m0, s74
	v_lshl_add_u64 v[212:213], s[48:49], 0, v[142:143]
	ds_read_b128 v[156:159], v205 offset:16384
	ds_read_b128 v[160:163], v205 offset:17408
	ds_read_b128 v[164:167], v205 offset:18432
	ds_read_b128 v[168:171], v205 offset:19456
	ds_read_b128 v[172:175], v205 offset:20480
	ds_read_b128 v[176:179], v205 offset:21504
	ds_read_b128 v[180:183], v205 offset:22528
	ds_read_b128 v[184:187], v205 offset:23552
	global_load_lds_dwordx4 v[212:213], off
	v_lshl_add_u64 v[224:225], s[48:49], 0, v[144:145]
	s_mov_b32 m0, s75
	s_nop 0
	global_load_lds_dwordx4 v[224:225], off
	s_add_u32 s22, s26, 0x10000
	s_addc_u32 s23, s27, 0
	s_add_i32 s60, s62, s71
	v_lshl_add_u64 v[232:233], s[22:23], 0, v[0:1]
	s_mov_b32 m0, s60
	s_nop 0
	global_load_lds_dwordx4 v[232:233], off
	v_lshl_add_u64 v[232:233], s[22:23], 0, v[146:147]
	s_add_i32 m0, s60, 0x2000
	s_nop 0
	global_load_lds_dwordx4 v[232:233], off
	s_waitcnt vmcnt(8) lgkmcnt(0)
	s_barrier
; #define PG8_STAGE(bufoff, gbase, voff) do { _Pragma("unroll") for (int _i = 0; _i < 2; ++_i) \
;         __builtin_amdgcn_global_load_lds((const unsigned*)((const char*)(gbase) + (voff)[_i]), (LAS unsigned*)(lds + (bufoff) + ldsw + _i * 8192), 16, 0, 0); } while (0)
; #define PG8_LDA(dst, b, h) do { _Pragma("unroll") for (int m = 0; m < 4; ++m) _Pragma("unroll") for (int k = 0; k < 2; ++k) dst[m][k] = *(const LAS h16x8*)(lds + PG8_SA(b, h) + aoff + m * 2048 + k * 1024); } while (0)
; #define PG8_LDB(dst, b, h) do { _Pragma("unroll") for (int n = 0; n < 2; ++n) _Pragma("unroll") for (int k = 0; k < 2; ++k) dst[n][k] = *(const LAS h16x8*)(lds + PG8_SB(b, h) + boff + n * 2048 + k * 1024); } while (0)
; #define PG8_MMA(ai, bj, At, Bt_) do { __builtin_amdgcn_s_setprio(1); _Pragma("unroll") for (int m = 0; m < 4; ++m) _Pragma("unroll") for (int n = 0; n < 2; ++n) _Pragma("unroll") for (int k = 0; k < 2; ++k) \
;         acc[ai][bj][m][n] = __builtin_amdgcn_mfma_f32_16x16x32_f16(Bt_[n][k], At[m][k], acc[ai][bj][m][n], 0, 0, 0); __builtin_amdgcn_s_setprio(0); } while (0)
; #define PG8_WAIT_V(n) asm volatile("s_waitcnt vmcnt(" #n ")" ::: "memory")
; #define PG8_WAIT_L(n) asm volatile("s_waitcnt lgkmcnt(" #n ")" ::: "memory")
; #define PG8_BAR __builtin_amdgcn_s_barrier()
; #define PG8_SCHED __builtin_amdgcn_sched_barrier(0)
; template <class Epi, class AMap>
; __device__ __forceinline__ void gemm_phase(LAS unsigned char* lds, const AMap am, const int lda, const h16* Bt, const int ldb, const int M, const int N, const int K, const Epi& E) {
;     ...
;             PG8_BAR; PG8_WAIT_L(0); PG8_MMA(1, 0, At, B0); PG8_BAR; PG8_SCHED;
;             PG8_STAGE(PG8_SB(0, 1), b2 + hstepB, voffB);
;             PG8_WAIT_V(6); PG8_BAR; PG8_MMA(1, 1, At, B1); PG8_BAR;
;             PG8_LDB(B0, 1, 0); PG8_SCHED; PG8_LDA(At, 1, 0); PG8_STAGE(PG8_SA(0, 1), a2 + hstepA, voffA);
;             PG8_WAIT_L(8); PG8_BAR; PG8_WAIT_L(0); PG8_MMA(0, 0, At, B0); PG8_BAR; PG8_SCHED;
;             PG8_LDB(B1, 1, 1); PG8_STAGE(PG8_SB(1, 0), b3, voffB);
;             PG8_BAR; PG8_WAIT_L(0); PG8_MMA(0, 1, At, B1); PG8_BAR;
	v_mfma_f32_16x16x32_f16 v[62:65], v[130:133], v[156:159], v[62:65]
	v_mfma_f32_16x16x32_f16 v[58:61], v[138:141], v[156:159], v[58:61]
	v_mfma_f32_16x16x32_f16 v[46:49], v[130:133], v[164:167], v[46:49]
	v_mfma_f32_16x16x32_f16 v[42:45], v[138:141], v[164:167], v[42:45]
	v_mfma_f32_16x16x32_f16 v[30:33], v[130:133], v[172:175], v[30:33]
	v_mfma_f32_16x16x32_f16 v[26:29], v[138:141], v[172:175], v[26:29]
	v_mfma_f32_16x16x32_f16 v[14:17], v[130:133], v[180:183], v[14:17]
	v_mfma_f32_16x16x32_f16 v[10:13], v[138:141], v[180:183], v[10:13]
	v_mfma_f32_16x16x32_f16 v[62:65], v[134:137], v[160:163], v[62:65]
	v_mfma_f32_16x16x32_f16 v[58:61], v[152:155], v[160:163], v[58:61]
	v_mfma_f32_16x16x32_f16 v[46:49], v[134:137], v[168:171], v[46:49]
	v_mfma_f32_16x16x32_f16 v[42:45], v[152:155], v[168:171], v[42:45]
	v_mfma_f32_16x16x32_f16 v[30:33], v[134:137], v[176:179], v[30:33]
	v_mfma_f32_16x16x32_f16 v[26:29], v[152:155], v[176:179], v[26:29]
	v_mfma_f32_16x16x32_f16 v[14:17], v[134:137], v[184:187], v[14:17]
	v_mfma_f32_16x16x32_f16 v[10:13], v[152:155], v[184:187], v[10:13]
	v_mfma_f32_16x16x32_f16 v[54:57], v[188:191], v[156:159], v[54:57]
	v_mfma_f32_16x16x32_f16 v[50:53], v[196:199], v[156:159], v[50:53]
	v_mfma_f32_16x16x32_f16 v[38:41], v[188:191], v[164:167], v[38:41]
	v_mfma_f32_16x16x32_f16 v[34:37], v[196:199], v[164:167], v[34:37]
	v_mfma_f32_16x16x32_f16 v[22:25], v[188:191], v[172:175], v[22:25]
	v_mfma_f32_16x16x32_f16 v[18:21], v[196:199], v[172:175], v[18:21]
	v_mfma_f32_16x16x32_f16 v[6:9], v[188:191], v[180:183], v[6:9]
	v_mfma_f32_16x16x32_f16 v[2:5], v[196:199], v[180:183], v[2:5]
	v_mfma_f32_16x16x32_f16 v[54:57], v[192:195], v[160:163], v[54:57]
	v_mfma_f32_16x16x32_f16 v[50:53], v[220:223], v[160:163], v[50:53]
	v_mfma_f32_16x16x32_f16 v[38:41], v[192:195], v[168:171], v[38:41]
	v_mfma_f32_16x16x32_f16 v[34:37], v[220:223], v[168:171], v[34:37]
	v_mfma_f32_16x16x32_f16 v[22:25], v[192:195], v[176:179], v[22:25]
	v_mfma_f32_16x16x32_f16 v[18:21], v[220:223], v[176:179], v[18:21]
	v_mfma_f32_16x16x32_f16 v[6:9], v[192:195], v[184:187], v[6:9]
	v_mfma_f32_16x16x32_f16 v[2:5], v[220:223], v[184:187], v[2:5]
	s_barrier
	s_add_i32 s60, 0, 0x18000
	v_add_u32_e32 v234, s60, v203
	ds_read_b128 v[130:133], v234
	ds_read_b128 v[134:137], v234 offset:1024
	ds_read_b128 v[138:141], v234 offset:2048
	ds_read_b128 v[152:155], v234 offset:3072
	s_add_u32 s22, s48, 0x1c0000
	s_addc_u32 s23, s49, 0
	s_mov_b32 m0, s76
	v_lshl_add_u64 v[232:233], s[22:23], 0, v[142:143]
	ds_read_b128 v[156:159], v205 offset:32768
	ds_read_b128 v[160:163], v205 offset:33792
	ds_read_b128 v[164:167], v205 offset:34816
	ds_read_b128 v[168:171], v205 offset:35840
	ds_read_b128 v[172:175], v205 offset:36864
	ds_read_b128 v[176:179], v205 offset:37888
	ds_read_b128 v[180:183], v205 offset:38912
	ds_read_b128 v[184:187], v205 offset:39936
	global_load_lds_dwordx4 v[232:233], off
	v_lshl_add_u64 v[232:233], s[22:23], 0, v[144:145]
	s_mov_b32 m0, s77
	s_nop 0
	global_load_lds_dwordx4 v[232:233], off
	s_waitcnt lgkmcnt(11)
	s_add_i32 s48, 0, 0x1c000
	s_add_i32 s22, s60, s71
	v_add_u32_e32 v214, s48, v203
	v_lshl_add_u64 v[200:201], v[200:201], 0, s[92:93]
	s_mov_b32 m0, s22
	ds_read_b128 v[188:191], v214
	ds_read_b128 v[192:195], v214 offset:1024
	ds_read_b128 v[196:199], v214 offset:2048
	ds_read_b128 v[220:223], v214 offset:3072
	s_waitcnt vmcnt(8) lgkmcnt(0)
	s_barrier
	v_mfma_f32_16x16x32_f16 v[122:125], v[130:133], v[156:159], v[122:125]
	v_mfma_f32_16x16x32_f16 v[126:129], v[138:141], v[156:159], v[126:129]
	v_mfma_f32_16x16x32_f16 v[110:113], v[130:133], v[164:167], v[110:113]
	v_mfma_f32_16x16x32_f16 v[106:109], v[138:141], v[164:167], v[106:109]
	v_mfma_f32_16x16x32_f16 v[94:97], v[130:133], v[172:175], v[94:97]
	v_mfma_f32_16x16x32_f16 v[90:93], v[138:141], v[172:175], v[90:93]
	v_mfma_f32_16x16x32_f16 v[78:81], v[130:133], v[180:183], v[78:81]
	v_mfma_f32_16x16x32_f16 v[74:77], v[138:141], v[180:183], v[74:77]
	v_mfma_f32_16x16x32_f16 v[122:125], v[134:137], v[160:163], v[122:125]
	v_mfma_f32_16x16x32_f16 v[126:129], v[152:155], v[160:163], v[126:129]
	v_mfma_f32_16x16x32_f16 v[110:113], v[134:137], v[168:171], v[110:113]
	v_mfma_f32_16x16x32_f16 v[106:109], v[152:155], v[168:171], v[106:109]
	v_mfma_f32_16x16x32_f16 v[94:97], v[134:137], v[176:179], v[94:97]
	v_mfma_f32_16x16x32_f16 v[90:93], v[152:155], v[176:179], v[90:93]
	v_mfma_f32_16x16x32_f16 v[78:81], v[134:137], v[184:187], v[78:81]
	v_mfma_f32_16x16x32_f16 v[74:77], v[152:155], v[184:187], v[74:77]
	v_mfma_f32_16x16x32_f16 v[118:121], v[188:191], v[156:159], v[118:121]
	v_mfma_f32_16x16x32_f16 v[114:117], v[196:199], v[156:159], v[114:117]
	v_mfma_f32_16x16x32_f16 v[102:105], v[188:191], v[164:167], v[102:105]
	v_mfma_f32_16x16x32_f16 v[98:101], v[196:199], v[164:167], v[98:101]
	v_mfma_f32_16x16x32_f16 v[86:89], v[188:191], v[172:175], v[86:89]
	v_mfma_f32_16x16x32_f16 v[82:85], v[196:199], v[172:175], v[82:85]
	v_mfma_f32_16x16x32_f16 v[70:73], v[188:191], v[180:183], v[70:73]
	v_mfma_f32_16x16x32_f16 v[66:69], v[196:199], v[180:183], v[66:69]
	v_mfma_f32_16x16x32_f16 v[118:121], v[192:195], v[160:163], v[118:121]
	v_mfma_f32_16x16x32_f16 v[114:117], v[220:223], v[160:163], v[114:117]
	v_mfma_f32_16x16x32_f16 v[102:105], v[192:195], v[168:171], v[102:105]
	v_mfma_f32_16x16x32_f16 v[98:101], v[220:223], v[168:171], v[98:101]
	v_mfma_f32_16x16x32_f16 v[86:89], v[192:195], v[176:179], v[86:89]
	v_mfma_f32_16x16x32_f16 v[82:85], v[220:223], v[176:179], v[82:85]
	v_mfma_f32_16x16x32_f16 v[70:73], v[192:195], v[184:187], v[70:73]
	v_mfma_f32_16x16x32_f16 v[66:69], v[220:223], v[184:187], v[66:69]
	s_barrier
; #define PG8_STAGE(bufoff, gbase, voff) do { _Pragma("unroll") for (int _i = 0; _i < 2; ++_i) \
;         __builtin_amdgcn_global_load_lds((const unsigned*)((const char*)(gbase) + (voff)[_i]), (LAS unsigned*)(lds + (bufoff) + ldsw + _i * 8192), 16, 0, 0); } while (0)
; #define PG8_LDA(dst, b, h) do { _Pragma("unroll") for (int m = 0; m < 4; ++m) _Pragma("unroll") for (int k = 0; k < 2; ++k) dst[m][k] = *(const LAS h16x8*)(lds + PG8_SA(b, h) + aoff + m * 2048 + k * 1024); } while (0)
; #define PG8_MMA(ai, bj, At, Bt_) do { __builtin_amdgcn_s_setprio(1); _Pragma("unroll") for (int m = 0; m < 4; ++m) _Pragma("unroll") for (int n = 0; n < 2; ++n) _Pragma("unroll") for (int k = 0; k < 2; ++k) \
;         acc[ai][bj][m][n] = __builtin_amdgcn_mfma_f32_16x16x32_f16(Bt_[n][k], At[m][k], acc[ai][bj][m][n], 0, 0, 0); __builtin_amdgcn_s_setprio(0); } while (0)
; #define PG8_WAIT_V(n) asm volatile("s_waitcnt vmcnt(" #n ")" ::: "memory")
; #define PG8_WAIT_L(n) asm volatile("s_waitcnt lgkmcnt(" #n ")" ::: "memory")
; #define PG8_BAR __builtin_amdgcn_s_barrier()
; #define PG8_SCHED __builtin_amdgcn_sched_barrier(0)
; template <class Epi, class AMap>
; __device__ __forceinline__ void gemm_phase(LAS unsigned char* lds, const AMap am, const int lda, const h16* Bt, const int ldb, const int M, const int N, const int K, const Epi& E) {
;     ...
;             PG8_LDA(At, 1, 1); PG8_STAGE(PG8_SA(1, 0), a3, voffA);
;             PG8_BAR; PG8_WAIT_L(0); PG8_MMA(1, 0, At, B0); PG8_BAR; PG8_SCHED;
;             PG8_STAGE(PG8_SB(1, 1), b3 + hstepB, voffB);
;             PG8_WAIT_V(6); PG8_BAR; PG8_MMA(1, 1, At, B1); PG8_BAR;
;         }
	global_load_lds_dwordx4 v[200:201], off
	v_lshl_add_u64 v[200:201], v[206:207], 0, s[92:93]
	s_add_i32 m0, s22, 0x2000
	s_nop 0
	global_load_lds_dwordx4 v[200:201], off
	s_mov_b32 m0, s78
	v_lshl_add_u64 v[200:201], v[212:213], 0, s[92:93]
	ds_read_b128 v[156:159], v205 offset:49152
	ds_read_b128 v[160:163], v205 offset:50176
	ds_read_b128 v[164:167], v205 offset:51200
	ds_read_b128 v[168:171], v205 offset:52224
	ds_read_b128 v[172:175], v205 offset:53248
	ds_read_b128 v[176:179], v205 offset:54272
	ds_read_b128 v[180:183], v205 offset:55296
	ds_read_b128 v[184:187], v205 offset:56320
	global_load_lds_dwordx4 v[200:201], off
	v_lshl_add_u64 v[200:201], v[224:225], 0, s[92:93]
	s_mov_b32 m0, s79
	s_nop 0
	global_load_lds_dwordx4 v[200:201], off
	s_add_u32 s22, s26, 0x10080
	s_addc_u32 s23, s27, 0
	s_add_i32 s26, s48, s71
	v_lshl_add_u64 v[232:233], s[22:23], 0, v[0:1]
	s_mov_b32 m0, s26
	s_nop 0
	global_load_lds_dwordx4 v[232:233], off
	v_lshl_add_u64 v[232:233], s[22:23], 0, v[146:147]
	s_add_i32 m0, s26, 0x2000
	s_nop 0
	global_load_lds_dwordx4 v[232:233], off
	s_waitcnt vmcnt(8) lgkmcnt(0)
	s_barrier
	v_mfma_f32_16x16x32_f16 v[62:65], v[130:133], v[156:159], v[62:65]
	v_mfma_f32_16x16x32_f16 v[58:61], v[138:141], v[156:159], v[58:61]
	v_mfma_f32_16x16x32_f16 v[46:49], v[130:133], v[164:167], v[46:49]
	v_mfma_f32_16x16x32_f16 v[42:45], v[138:141], v[164:167], v[42:45]
	v_mfma_f32_16x16x32_f16 v[30:33], v[130:133], v[172:175], v[30:33]
	v_mfma_f32_16x16x32_f16 v[26:29], v[138:141], v[172:175], v[26:29]
	v_mfma_f32_16x16x32_f16 v[14:17], v[130:133], v[180:183], v[14:17]
	v_mfma_f32_16x16x32_f16 v[10:13], v[138:141], v[180:183], v[10:13]
	v_mfma_f32_16x16x32_f16 v[62:65], v[134:137], v[160:163], v[62:65]
	v_mfma_f32_16x16x32_f16 v[58:61], v[152:155], v[160:163], v[58:61]
	v_mfma_f32_16x16x32_f16 v[46:49], v[134:137], v[168:171], v[46:49]
	v_mfma_f32_16x16x32_f16 v[42:45], v[152:155], v[168:171], v[42:45]
	v_mfma_f32_16x16x32_f16 v[30:33], v[134:137], v[176:179], v[30:33]
	v_mfma_f32_16x16x32_f16 v[26:29], v[152:155], v[176:179], v[26:29]
	v_mfma_f32_16x16x32_f16 v[14:17], v[134:137], v[184:187], v[14:17]
	v_mfma_f32_16x16x32_f16 v[10:13], v[152:155], v[184:187], v[10:13]
	v_mfma_f32_16x16x32_f16 v[54:57], v[188:191], v[156:159], v[54:57]
	v_mfma_f32_16x16x32_f16 v[50:53], v[196:199], v[156:159], v[50:53]
	v_mfma_f32_16x16x32_f16 v[38:41], v[188:191], v[164:167], v[38:41]
	v_mfma_f32_16x16x32_f16 v[34:37], v[196:199], v[164:167], v[34:37]
	v_mfma_f32_16x16x32_f16 v[22:25], v[188:191], v[172:175], v[22:25]
	v_mfma_f32_16x16x32_f16 v[18:21], v[196:199], v[172:175], v[18:21]
	v_mfma_f32_16x16x32_f16 v[6:9], v[188:191], v[180:183], v[6:9]
	v_mfma_f32_16x16x32_f16 v[2:5], v[196:199], v[180:183], v[2:5]
	v_mfma_f32_16x16x32_f16 v[54:57], v[192:195], v[160:163], v[54:57]
	v_mfma_f32_16x16x32_f16 v[50:53], v[220:223], v[160:163], v[50:53]
	v_mfma_f32_16x16x32_f16 v[38:41], v[192:195], v[168:171], v[38:41]
	v_mfma_f32_16x16x32_f16 v[34:37], v[220:223], v[168:171], v[34:37]
	v_mfma_f32_16x16x32_f16 v[22:25], v[192:195], v[176:179], v[22:25]
	v_mfma_f32_16x16x32_f16 v[18:21], v[220:223], v[176:179], v[18:21]
	v_mfma_f32_16x16x32_f16 v[6:9], v[192:195], v[184:187], v[6:9]
	v_mfma_f32_16x16x32_f16 v[2:5], v[220:223], v[184:187], v[2:5]
	s_add_u32 s29, s29, 0x100
	s_addc_u32 s45, s45, 0
	s_cmp_ge_i32 s51, s24
	s_mov_b64 s[22:23], s[0:1]
	s_mov_b32 s26, s51
	s_barrier
	s_cbranch_scc0 .LBB0_644
	s_branch .LBB0_633

; #define PG8_STAGE(bufoff, gbase, voff) do { _Pragma("unroll") for (int _i = 0; _i < 2; ++_i) \
;         __builtin_amdgcn_global_load_lds((const unsigned*)((const char*)(gbase) + (voff)[_i]), (LAS unsigned*)(lds + (bufoff) + ldsw + _i * 8192), 16, 0, 0); } while (0)
; #define PG8_LDA(dst, b, h) do { _Pragma("unroll") for (int m = 0; m < 4; ++m) _Pragma("unroll") for (int k = 0; k < 2; ++k) dst[m][k] = *(const LAS h16x8*)(lds + PG8_SA(b, h) + aoff + m * 2048 + k * 1024); } while (0)
; #define PG8_LDB(dst, b, h) do { _Pragma("unroll") for (int n = 0; n < 2; ++n) _Pragma("unroll") for (int k = 0; k < 2; ++k) dst[n][k] = *(const LAS h16x8*)(lds + PG8_SB(b, h) + boff + n * 2048 + k * 1024); } while (0)
; #define PG8_MMA(ai, bj, At, Bt_) do { __builtin_amdgcn_s_setprio(1); _Pragma("unroll") for (int m = 0; m < 4; ++m) _Pragma("unroll") for (int n = 0; n < 2; ++n) _Pragma("unroll") for (int k = 0; k < 2; ++k) \
;         acc[ai][bj][m][n] = __builtin_amdgcn_mfma_f32_16x16x32_f16(Bt_[n][k], At[m][k], acc[ai][bj][m][n], 0, 0, 0); __builtin_amdgcn_s_setprio(0); } while (0)
; #define PG8_WAIT_V(n) asm volatile("s_waitcnt vmcnt(" #n ")" ::: "memory")
; #define PG8_WAIT_L(n) asm volatile("s_waitcnt lgkmcnt(" #n ")" ::: "memory")
; template <class Epi, class AMap>
; __device__ __forceinline__ void gemm_phase(LAS unsigned char* lds, const AMap am, const int lda, const h16* Bt, const int ldb, const int M, const int N, const int K, const Epi& E) {
;     ...
;             const bool last = (t == nt - 2);
;             const char* a1 = cA + (size_t)(t + 1) * kstep;
;             const char* a2 = last ? nA : cA + (size_t)(t + 2) * kstep; const char* b2 = last ? nB : cB + (size_t)(t + 2) * kstep;
;             const char* a3 = a2 + kstep; const char* b3 = b2 + kstep;
;             PG8_LDB(B0, 0, 0); PG8_SCHED; PG8_LDA(At, 0, 0); PG8_STAGE(PG8_SA(1, 1), a1 + hstepA, voffA);
;             PG8_WAIT_L(8); PG8_BAR; PG8_WAIT_L(0); PG8_MMA(0, 0, At, B0); PG8_BAR; PG8_SCHED;
;             PG8_LDB(B1, 0, 1); PG8_STAGE(PG8_SB(0, 0), b2, voffB);
;             PG8_BAR; PG8_WAIT_L(0); PG8_MMA(0, 1, At, B1); PG8_BAR;
;             PG8_LDA(At, 0, 1); PG8_STAGE(PG8_SA(0, 0), a2, voffA);
;             PG8_BAR; PG8_WAIT_L(0); PG8_MMA(1, 0, At, B0); PG8_BAR; PG8_SCHED;
;             PG8_STAGE(PG8_SB(0, 1), b2 + hstepB, voffB);
;             PG8_WAIT_V(6); PG8_BAR; PG8_MMA(1, 1, At, B1); PG8_BAR;
.LBB0_667:
	s_add_i32 s60, s46, 2
	s_add_u32 s0, s44, 0x100
	s_addc_u32 s1, s45, 0
	s_add_i32 s66, 0, 0x10000
	v_add_u32_e32 v234, s66, v161
	ds_read_b128 v[140:143], v234
	ds_read_b128 v[144:147], v234 offset:1024
	ds_read_b128 v[148:151], v234 offset:2048
	ds_read_b128 v[152:155], v234 offset:3072
	s_cmp_eq_u32 s73, s46
	s_cselect_b32 s46, s21, s27
	s_cselect_b32 s49, s41, s1
	s_cselect_b32 s48, s40, s0
	s_cselect_b32 s47, s20, s29
	v_lshl_add_u64 v[232:233], s[44:45], 0, v[136:137]
	s_add_i32 m0, s65, 0xc000
	ds_read_b128 v[156:159], v163
	ds_read_b128 v[164:167], v163 offset:1024
	ds_read_b128 v[168:171], v163 offset:2048
	ds_read_b128 v[172:175], v163 offset:3072
	ds_read_b128 v[176:179], v163 offset:4096
	ds_read_b128 v[180:183], v163 offset:5120
	ds_read_b128 v[184:187], v163 offset:6144
	ds_read_b128 v[188:191], v163 offset:7168
	global_load_lds_dwordx4 v[232:233], off
	v_lshl_add_u64 v[232:233], s[44:45], 0, v[138:139]
	s_add_i32 m0, s65, 0xe000
	s_nop 0
	global_load_lds_dwordx4 v[232:233], off
	s_waitcnt lgkmcnt(11)
	s_add_i32 s78, 0, 0x14000
	s_add_i32 s44, s66, s62
	v_add_u32_e32 v234, s78, v161
	v_lshl_add_u64 v[212:213], s[46:47], 0, v[0:1]
	s_mov_b32 m0, s44
	ds_read_b128 v[192:195], v234
	ds_read_b128 v[196:199], v234 offset:1024
	ds_read_b128 v[200:203], v234 offset:2048
	ds_read_b128 v[204:207], v234 offset:3072
	s_waitcnt vmcnt(8) lgkmcnt(0)
	s_barrier
	v_mfma_f32_16x16x32_f16 v[126:129], v[140:143], v[156:159], v[126:129]
	v_mfma_f32_16x16x32_f16 v[122:125], v[148:151], v[156:159], v[122:125]
	v_mfma_f32_16x16x32_f16 v[118:121], v[140:143], v[168:171], v[118:121]
	v_mfma_f32_16x16x32_f16 v[114:117], v[148:151], v[168:171], v[114:117]
	v_mfma_f32_16x16x32_f16 v[110:113], v[140:143], v[176:179], v[110:113]
	v_mfma_f32_16x16x32_f16 v[106:109], v[148:151], v[176:179], v[106:109]
	v_mfma_f32_16x16x32_f16 v[102:105], v[140:143], v[184:187], v[102:105]
	v_mfma_f32_16x16x32_f16 v[98:101], v[148:151], v[184:187], v[98:101]
	v_mfma_f32_16x16x32_f16 v[126:129], v[144:147], v[164:167], v[126:129]
	v_mfma_f32_16x16x32_f16 v[122:125], v[152:155], v[164:167], v[122:125]
	v_mfma_f32_16x16x32_f16 v[118:121], v[144:147], v[172:175], v[118:121]
	v_mfma_f32_16x16x32_f16 v[114:117], v[152:155], v[172:175], v[114:117]
	v_mfma_f32_16x16x32_f16 v[110:113], v[144:147], v[180:183], v[110:113]
	v_mfma_f32_16x16x32_f16 v[106:109], v[152:155], v[180:183], v[106:109]
	v_mfma_f32_16x16x32_f16 v[102:105], v[144:147], v[188:191], v[102:105]
	v_mfma_f32_16x16x32_f16 v[98:101], v[152:155], v[188:191], v[98:101]
	v_mfma_f32_16x16x32_f16 v[94:97], v[192:195], v[156:159], v[94:97]
	v_mfma_f32_16x16x32_f16 v[86:89], v[200:203], v[156:159], v[86:89]
	v_mfma_f32_16x16x32_f16 v[78:81], v[192:195], v[168:171], v[78:81]
	v_mfma_f32_16x16x32_f16 v[70:73], v[200:203], v[168:171], v[70:73]
	v_mfma_f32_16x16x32_f16 v[62:65], v[192:195], v[176:179], v[62:65]
	v_mfma_f32_16x16x32_f16 v[54:57], v[200:203], v[176:179], v[54:57]
	v_mfma_f32_16x16x32_f16 v[46:49], v[192:195], v[184:187], v[46:49]
	v_mfma_f32_16x16x32_f16 v[38:41], v[200:203], v[184:187], v[38:41]
	v_mfma_f32_16x16x32_f16 v[94:97], v[196:199], v[164:167], v[94:97]
	v_mfma_f32_16x16x32_f16 v[86:89], v[204:207], v[164:167], v[86:89]
	v_mfma_f32_16x16x32_f16 v[78:81], v[196:199], v[172:175], v[78:81]
	v_mfma_f32_16x16x32_f16 v[70:73], v[204:207], v[172:175], v[70:73]
	v_mfma_f32_16x16x32_f16 v[62:65], v[196:199], v[180:183], v[62:65]
	v_mfma_f32_16x16x32_f16 v[54:57], v[204:207], v[180:183], v[54:57]
	v_mfma_f32_16x16x32_f16 v[46:49], v[196:199], v[188:191], v[46:49]
	v_mfma_f32_16x16x32_f16 v[38:41], v[204:207], v[188:191], v[38:41]
	s_barrier
	global_load_lds_dwordx4 v[212:213], off
	v_lshl_add_u64 v[220:221], s[46:47], 0, v[134:135]
	s_add_i32 m0, s44, 0x2000
	s_nop 0
	global_load_lds_dwordx4 v[220:221], off
	s_mov_b32 m0, s65
	v_lshl_add_u64 v[222:223], s[48:49], 0, v[130:131]
	ds_read_b128 v[156:159], v163 offset:16384
	ds_read_b128 v[164:167], v163 offset:17408
	ds_read_b128 v[168:171], v163 offset:18432
	ds_read_b128 v[172:175], v163 offset:19456
	ds_read_b128 v[176:179], v163 offset:20480
	ds_read_b128 v[180:183], v163 offset:21504
	ds_read_b128 v[184:187], v163 offset:22528
	ds_read_b128 v[188:191], v163 offset:23552
	global_load_lds_dwordx4 v[222:223], off
	v_lshl_add_u64 v[224:225], s[48:49], 0, v[132:133]
	s_mov_b32 m0, s68
	s_nop 0
	global_load_lds_dwordx4 v[224:225], off
	s_add_u32 s44, s46, 0x10000
	s_addc_u32 s45, s47, 0
	s_add_i32 s66, s78, s62
	v_lshl_add_u64 v[232:233], s[44:45], 0, v[0:1]
	s_mov_b32 m0, s66
	s_nop 0
	global_load_lds_dwordx4 v[232:233], off
	v_lshl_add_u64 v[232:233], s[44:45], 0, v[134:135]
	s_add_i32 m0, s66, 0x2000
	s_nop 0
	global_load_lds_dwordx4 v[232:233], off
	s_waitcnt vmcnt(8) lgkmcnt(0)
	s_barrier
; #define PG8_STAGE(bufoff, gbase, voff) do { _Pragma("unroll") for (int _i = 0; _i < 2; ++_i) \
;         __builtin_amdgcn_global_load_lds((const unsigned*)((const char*)(gbase) + (voff)[_i]), (LAS unsigned*)(lds + (bufoff) + ldsw + _i * 8192), 16, 0, 0); } while (0)
; #define PG8_LDA(dst, b, h) do { _Pragma("unroll") for (int m = 0; m < 4; ++m) _Pragma("unroll") for (int k = 0; k < 2; ++k) dst[m][k] = *(const LAS h16x8*)(lds + PG8_SA(b, h) + aoff + m * 2048 + k * 1024); } while (0)
; #define PG8_LDB(dst, b, h) do { _Pragma("unroll") for (int n = 0; n < 2; ++n) _Pragma("unroll") for (int k = 0; k < 2; ++k) dst[n][k] = *(const LAS h16x8*)(lds + PG8_SB(b, h) + boff + n * 2048 + k * 1024); } while (0)
; #define PG8_MMA(ai, bj, At, Bt_) do { __builtin_amdgcn_s_setprio(1); _Pragma("unroll") for (int m = 0; m < 4; ++m) _Pragma("unroll") for (int n = 0; n < 2; ++n) _Pragma("unroll") for (int k = 0; k < 2; ++k) \
;         acc[ai][bj][m][n] = __builtin_amdgcn_mfma_f32_16x16x32_f16(Bt_[n][k], At[m][k], acc[ai][bj][m][n], 0, 0, 0); __builtin_amdgcn_s_setprio(0); } while (0)
; #define PG8_WAIT_V(n) asm volatile("s_waitcnt vmcnt(" #n ")" ::: "memory")
; #define PG8_WAIT_L(n) asm volatile("s_waitcnt lgkmcnt(" #n ")" ::: "memory")
; #define PG8_BAR __builtin_amdgcn_s_barrier()
; #define PG8_SCHED __builtin_amdgcn_sched_barrier(0)
; template <class Epi, class AMap>
; __device__ __forceinline__ void gemm_phase(LAS unsigned char* lds, const AMap am, const int lda, const h16* Bt, const int ldb, const int M, const int N, const int K, const Epi& E) {
;     ...
;             PG8_BAR; PG8_WAIT_L(0); PG8_MMA(1, 0, At, B0); PG8_BAR; PG8_SCHED;
;             PG8_STAGE(PG8_SB(0, 1), b2 + hstepB, voffB);
;             PG8_WAIT_V(6); PG8_BAR; PG8_MMA(1, 1, At, B1); PG8_BAR;
;             PG8_LDB(B0, 1, 0); PG8_SCHED; PG8_LDA(At, 1, 0); PG8_STAGE(PG8_SA(0, 1), a2 + hstepA, voffA);
;             PG8_WAIT_L(8); PG8_BAR; PG8_WAIT_L(0); PG8_MMA(0, 0, At, B0); PG8_BAR; PG8_SCHED;
;             PG8_LDB(B1, 1, 1); PG8_STAGE(PG8_SB(1, 0), b3, voffB);
;             PG8_BAR; PG8_WAIT_L(0); PG8_MMA(0, 1, At, B1); PG8_BAR;
	v_mfma_f32_16x16x32_f16 v[90:93], v[140:143], v[156:159], v[90:93]
	v_mfma_f32_16x16x32_f16 v[82:85], v[148:151], v[156:159], v[82:85]
	v_mfma_f32_16x16x32_f16 v[74:77], v[140:143], v[168:171], v[74:77]
	v_mfma_f32_16x16x32_f16 v[66:69], v[148:151], v[168:171], v[66:69]
	v_mfma_f32_16x16x32_f16 v[58:61], v[140:143], v[176:179], v[58:61]
	v_mfma_f32_16x16x32_f16 v[50:53], v[148:151], v[176:179], v[50:53]
	v_mfma_f32_16x16x32_f16 v[42:45], v[140:143], v[184:187], v[42:45]
	v_mfma_f32_16x16x32_f16 v[34:37], v[148:151], v[184:187], v[34:37]
	v_mfma_f32_16x16x32_f16 v[90:93], v[144:147], v[164:167], v[90:93]
	v_mfma_f32_16x16x32_f16 v[82:85], v[152:155], v[164:167], v[82:85]
	v_mfma_f32_16x16x32_f16 v[74:77], v[144:147], v[172:175], v[74:77]
	v_mfma_f32_16x16x32_f16 v[66:69], v[152:155], v[172:175], v[66:69]
	v_mfma_f32_16x16x32_f16 v[58:61], v[144:147], v[180:183], v[58:61]
	v_mfma_f32_16x16x32_f16 v[50:53], v[152:155], v[180:183], v[50:53]
	v_mfma_f32_16x16x32_f16 v[42:45], v[144:147], v[188:191], v[42:45]
	v_mfma_f32_16x16x32_f16 v[34:37], v[152:155], v[188:191], v[34:37]
	v_mfma_f32_16x16x32_f16 v[30:33], v[192:195], v[156:159], v[30:33]
	v_mfma_f32_16x16x32_f16 v[26:29], v[200:203], v[156:159], v[26:29]
	v_mfma_f32_16x16x32_f16 v[22:25], v[192:195], v[168:171], v[22:25]
	v_mfma_f32_16x16x32_f16 v[18:21], v[200:203], v[168:171], v[18:21]
	v_mfma_f32_16x16x32_f16 v[14:17], v[192:195], v[176:179], v[14:17]
	v_mfma_f32_16x16x32_f16 v[10:13], v[200:203], v[176:179], v[10:13]
	v_mfma_f32_16x16x32_f16 v[6:9], v[192:195], v[184:187], v[6:9]
	v_mfma_f32_16x16x32_f16 v[2:5], v[200:203], v[184:187], v[2:5]
	v_mfma_f32_16x16x32_f16 v[30:33], v[196:199], v[164:167], v[30:33]
	v_mfma_f32_16x16x32_f16 v[26:29], v[204:207], v[164:167], v[26:29]
	v_mfma_f32_16x16x32_f16 v[22:25], v[196:199], v[172:175], v[22:25]
	v_mfma_f32_16x16x32_f16 v[18:21], v[204:207], v[172:175], v[18:21]
	v_mfma_f32_16x16x32_f16 v[14:17], v[196:199], v[180:183], v[14:17]
	v_mfma_f32_16x16x32_f16 v[10:13], v[204:207], v[180:183], v[10:13]
	v_mfma_f32_16x16x32_f16 v[6:9], v[196:199], v[188:191], v[6:9]
	v_mfma_f32_16x16x32_f16 v[2:5], v[204:207], v[188:191], v[2:5]
	s_barrier
	s_add_i32 s66, 0, 0x18000
	v_add_u32_e32 v234, s66, v161
	ds_read_b128 v[140:143], v234
	ds_read_b128 v[144:147], v234 offset:1024
	ds_read_b128 v[148:151], v234 offset:2048
	ds_read_b128 v[152:155], v234 offset:3072
	s_add_u32 s44, s48, 0x1c0000
	s_addc_u32 s45, s49, 0
	s_mov_b32 m0, s69
	v_lshl_add_u64 v[232:233], s[44:45], 0, v[130:131]
	ds_read_b128 v[156:159], v163 offset:32768
	ds_read_b128 v[164:167], v163 offset:33792
	ds_read_b128 v[168:171], v163 offset:34816
	ds_read_b128 v[172:175], v163 offset:35840
	ds_read_b128 v[176:179], v163 offset:36864
	ds_read_b128 v[180:183], v163 offset:37888
	ds_read_b128 v[184:187], v163 offset:38912
	ds_read_b128 v[188:191], v163 offset:39936
	global_load_lds_dwordx4 v[232:233], off
	v_lshl_add_u64 v[232:233], s[44:45], 0, v[132:133]
	s_mov_b32 m0, s70
	s_nop 0
	global_load_lds_dwordx4 v[232:233], off
	s_waitcnt lgkmcnt(11)
	s_add_i32 s48, 0, 0x1c000
	s_add_i32 s44, s66, s62
	v_add_u32_e32 v234, s48, v161
	v_lshl_add_u64 v[212:213], v[212:213], 0, s[92:93]
	s_mov_b32 m0, s44
	ds_read_b128 v[192:195], v234
	ds_read_b128 v[196:199], v234 offset:1024
	ds_read_b128 v[200:203], v234 offset:2048
	ds_read_b128 v[204:207], v234 offset:3072
	s_waitcnt vmcnt(8) lgkmcnt(0)
	s_barrier
	v_mfma_f32_16x16x32_f16 v[126:129], v[140:143], v[156:159], v[126:129]
	v_mfma_f32_16x16x32_f16 v[122:125], v[148:151], v[156:159], v[122:125]
	v_mfma_f32_16x16x32_f16 v[118:121], v[140:143], v[168:171], v[118:121]
	v_mfma_f32_16x16x32_f16 v[114:117], v[148:151], v[168:171], v[114:117]
	v_mfma_f32_16x16x32_f16 v[110:113], v[140:143], v[176:179], v[110:113]
	v_mfma_f32_16x16x32_f16 v[106:109], v[148:151], v[176:179], v[106:109]
	v_mfma_f32_16x16x32_f16 v[102:105], v[140:143], v[184:187], v[102:105]
	v_mfma_f32_16x16x32_f16 v[98:101], v[148:151], v[184:187], v[98:101]
	v_mfma_f32_16x16x32_f16 v[126:129], v[144:147], v[164:167], v[126:129]
	v_mfma_f32_16x16x32_f16 v[122:125], v[152:155], v[164:167], v[122:125]
	v_mfma_f32_16x16x32_f16 v[118:121], v[144:147], v[172:175], v[118:121]
	v_mfma_f32_16x16x32_f16 v[114:117], v[152:155], v[172:175], v[114:117]
	v_mfma_f32_16x16x32_f16 v[110:113], v[144:147], v[180:183], v[110:113]
	v_mfma_f32_16x16x32_f16 v[106:109], v[152:155], v[180:183], v[106:109]
	v_mfma_f32_16x16x32_f16 v[102:105], v[144:147], v[188:191], v[102:105]
	v_mfma_f32_16x16x32_f16 v[98:101], v[152:155], v[188:191], v[98:101]
	v_mfma_f32_16x16x32_f16 v[94:97], v[192:195], v[156:159], v[94:97]
	v_mfma_f32_16x16x32_f16 v[86:89], v[200:203], v[156:159], v[86:89]
	v_mfma_f32_16x16x32_f16 v[78:81], v[192:195], v[168:171], v[78:81]
	v_mfma_f32_16x16x32_f16 v[70:73], v[200:203], v[168:171], v[70:73]
	v_mfma_f32_16x16x32_f16 v[62:65], v[192:195], v[176:179], v[62:65]
	v_mfma_f32_16x16x32_f16 v[54:57], v[200:203], v[176:179], v[54:57]
	v_mfma_f32_16x16x32_f16 v[46:49], v[192:195], v[184:187], v[46:49]
	v_mfma_f32_16x16x32_f16 v[38:41], v[200:203], v[184:187], v[38:41]
	v_mfma_f32_16x16x32_f16 v[94:97], v[196:199], v[164:167], v[94:97]
	v_mfma_f32_16x16x32_f16 v[86:89], v[204:207], v[164:167], v[86:89]
	v_mfma_f32_16x16x32_f16 v[78:81], v[196:199], v[172:175], v[78:81]
	v_mfma_f32_16x16x32_f16 v[70:73], v[204:207], v[172:175], v[70:73]
	v_mfma_f32_16x16x32_f16 v[62:65], v[196:199], v[180:183], v[62:65]
	v_mfma_f32_16x16x32_f16 v[54:57], v[204:207], v[180:183], v[54:57]
	v_mfma_f32_16x16x32_f16 v[46:49], v[196:199], v[188:191], v[46:49]
	v_mfma_f32_16x16x32_f16 v[38:41], v[204:207], v[188:191], v[38:41]
	s_barrier
; #define PG8_STAGE(bufoff, gbase, voff) do { _Pragma("unroll") for (int _i = 0; _i < 2; ++_i) \
;         __builtin_amdgcn_global_load_lds((const unsigned*)((const char*)(gbase) + (voff)[_i]), (LAS unsigned*)(lds + (bufoff) + ldsw + _i * 8192), 16, 0, 0); } while (0)
; #define PG8_LDA(dst, b, h) do { _Pragma("unroll") for (int m = 0; m < 4; ++m) _Pragma("unroll") for (int k = 0; k < 2; ++k) dst[m][k] = *(const LAS h16x8*)(lds + PG8_SA(b, h) + aoff + m * 2048 + k * 1024); } while (0)
; #define PG8_MMA(ai, bj, At, Bt_) do { __builtin_amdgcn_s_setprio(1); _Pragma("unroll") for (int m = 0; m < 4; ++m) _Pragma("unroll") for (int n = 0; n < 2; ++n) _Pragma("unroll") for (int k = 0; k < 2; ++k) \
;         acc[ai][bj][m][n] = __builtin_amdgcn_mfma_f32_16x16x32_f16(Bt_[n][k], At[m][k], acc[ai][bj][m][n], 0, 0, 0); __builtin_amdgcn_s_setprio(0); } while (0)
; #define PG8_WAIT_V(n) asm volatile("s_waitcnt vmcnt(" #n ")" ::: "memory")
; #define PG8_WAIT_L(n) asm volatile("s_waitcnt lgkmcnt(" #n ")" ::: "memory")
; #define PG8_BAR __builtin_amdgcn_s_barrier()
; template <class Epi, class AMap>
; __device__ __forceinline__ void gemm_phase(LAS unsigned char* lds, const AMap am, const int lda, const h16* Bt, const int ldb, const int M, const int N, const int K, const Epi& E) {
;     ...
;             PG8_LDA(At, 1, 1); PG8_STAGE(PG8_SA(1, 0), a3, voffA);
;             PG8_BAR; PG8_WAIT_L(0); PG8_MMA(1, 0, At, B0); PG8_BAR; PG8_SCHED;
;             PG8_STAGE(PG8_SB(1, 1), b3 + hstepB, voffB);
;             PG8_WAIT_V(6); PG8_BAR; PG8_MMA(1, 1, At, B1); PG8_BAR;
;         }
;     template <int GI>
;     __device__ __forceinline__ void body(const f32x4 (&acc)[2][2][4][2], int row0, int colt) const {
;     ...
;             f32x4 b0 = (f32x4){0.f, 0.f, 0.f, 0.f}, b1 = b0;
;             if (GI == 0) { b0 = *(const f32x4*)(w0 + c); b1 = *(const f32x4*)(w0 + c + 4); }
;             else if (GI == 1) { b0 = *(const f32x4*)(a0 + c); b1 = *(const f32x4*)(a0 + c + 4); }
;             else if (GI == 3) { b0 = *(const f32x4*)(v0 + c); b1 = *(const f32x4*)(v0 + c + 4); }
; #pragma unroll
;             for (int ai = 0; ai < 2; ++ai)
; #pragma unroll
;                 for (int m = 0; m < 4; ++m) {
;                     const size_t row = (size_t)(row0 + ai * 128 + m * 16);
;                     f32x4 x0 = acc[ai][bj][m][0] + b0, x1 = acc[ai][bj][m][1] + b1;
	global_load_lds_dwordx4 v[212:213], off
	v_lshl_add_u64 v[212:213], v[220:221], 0, s[92:93]
	s_add_i32 m0, s44, 0x2000
	s_nop 0
	global_load_lds_dwordx4 v[212:213], off
	s_mov_b32 m0, s71
	v_lshl_add_u64 v[212:213], v[222:223], 0, s[92:93]
	ds_read_b128 v[156:159], v163 offset:49152
	ds_read_b128 v[164:167], v163 offset:50176
	ds_read_b128 v[168:171], v163 offset:51200
	ds_read_b128 v[172:175], v163 offset:52224
	ds_read_b128 v[176:179], v163 offset:53248
	ds_read_b128 v[180:183], v163 offset:54272
	ds_read_b128 v[184:187], v163 offset:55296
	ds_read_b128 v[188:191], v163 offset:56320
	global_load_lds_dwordx4 v[212:213], off
	v_lshl_add_u64 v[212:213], v[224:225], 0, s[92:93]
	s_mov_b32 m0, s72
	s_nop 0
	global_load_lds_dwordx4 v[212:213], off
	s_add_u32 s44, s46, 0x10080
	s_addc_u32 s45, s47, 0
	s_add_i32 s46, s48, s62
	v_lshl_add_u64 v[232:233], s[44:45], 0, v[0:1]
	s_mov_b32 m0, s46
	s_nop 0
	global_load_lds_dwordx4 v[232:233], off
	v_lshl_add_u64 v[232:233], s[44:45], 0, v[134:135]
	s_add_i32 m0, s46, 0x2000
	s_nop 0
	global_load_lds_dwordx4 v[232:233], off
	s_waitcnt vmcnt(8) lgkmcnt(0)
	s_barrier
	v_mfma_f32_16x16x32_f16 v[90:93], v[140:143], v[156:159], v[90:93]
	v_mfma_f32_16x16x32_f16 v[82:85], v[148:151], v[156:159], v[82:85]
	v_mfma_f32_16x16x32_f16 v[74:77], v[140:143], v[168:171], v[74:77]
	v_mfma_f32_16x16x32_f16 v[66:69], v[148:151], v[168:171], v[66:69]
	v_mfma_f32_16x16x32_f16 v[58:61], v[140:143], v[176:179], v[58:61]
	v_mfma_f32_16x16x32_f16 v[50:53], v[148:151], v[176:179], v[50:53]
	v_mfma_f32_16x16x32_f16 v[42:45], v[140:143], v[184:187], v[42:45]
	v_mfma_f32_16x16x32_f16 v[34:37], v[148:151], v[184:187], v[34:37]
	v_mfma_f32_16x16x32_f16 v[90:93], v[144:147], v[164:167], v[90:93]
	v_mfma_f32_16x16x32_f16 v[82:85], v[152:155], v[164:167], v[82:85]
	v_mfma_f32_16x16x32_f16 v[74:77], v[144:147], v[172:175], v[74:77]
	v_mfma_f32_16x16x32_f16 v[66:69], v[152:155], v[172:175], v[66:69]
	v_mfma_f32_16x16x32_f16 v[58:61], v[144:147], v[180:183], v[58:61]
	v_mfma_f32_16x16x32_f16 v[50:53], v[152:155], v[180:183], v[50:53]
	v_mfma_f32_16x16x32_f16 v[42:45], v[144:147], v[188:191], v[42:45]
	v_mfma_f32_16x16x32_f16 v[34:37], v[152:155], v[188:191], v[34:37]
	v_mfma_f32_16x16x32_f16 v[30:33], v[192:195], v[156:159], v[30:33]
	v_mfma_f32_16x16x32_f16 v[26:29], v[200:203], v[156:159], v[26:29]
	v_mfma_f32_16x16x32_f16 v[22:25], v[192:195], v[168:171], v[22:25]
	v_mfma_f32_16x16x32_f16 v[18:21], v[200:203], v[168:171], v[18:21]
	v_mfma_f32_16x16x32_f16 v[14:17], v[192:195], v[176:179], v[14:17]
	v_mfma_f32_16x16x32_f16 v[10:13], v[200:203], v[176:179], v[10:13]
	v_mfma_f32_16x16x32_f16 v[6:9], v[192:195], v[184:187], v[6:9]
	v_mfma_f32_16x16x32_f16 v[2:5], v[200:203], v[184:187], v[2:5]
	v_mfma_f32_16x16x32_f16 v[30:33], v[196:199], v[164:167], v[30:33]
	v_mfma_f32_16x16x32_f16 v[26:29], v[204:207], v[164:167], v[26:29]
	v_mfma_f32_16x16x32_f16 v[22:25], v[196:199], v[172:175], v[22:25]
	v_mfma_f32_16x16x32_f16 v[18:21], v[204:207], v[172:175], v[18:21]
	v_mfma_f32_16x16x32_f16 v[14:17], v[196:199], v[180:183], v[14:17]
	v_mfma_f32_16x16x32_f16 v[10:13], v[204:207], v[180:183], v[10:13]
	v_mfma_f32_16x16x32_f16 v[6:9], v[196:199], v[188:191], v[6:9]
	v_mfma_f32_16x16x32_f16 v[2:5], v[204:207], v[188:191], v[2:5]
	s_add_u32 s27, s27, 0x100
	s_addc_u32 s29, s29, 0
	s_cmp_ge_i32 s60, s24
	s_mov_b64 s[44:45], s[0:1]
	s_mov_b32 s46, s60
	s_barrier
	s_cbranch_scc0 .LBB0_667
	v_pk_add_f32 v[128:129], v[128:129], 0 op_sel_hi:[1,0]
	v_pk_add_f32 v[126:127], v[126:127], 0 op_sel_hi:[1,0]
	v_pk_add_f32 v[124:125], v[124:125], 0 op_sel_hi:[1,0]
	v_pk_add_f32 v[122:123], v[122:123], 0 op_sel_hi:[1,0]
	v_pk_add_f32 v[120:121], v[120:121], 0 op_sel_hi:[1,0]
	v_pk_add_f32 v[118:119], v[118:119], 0 op_sel_hi:[1,0]
	v_pk_add_f32 v[116:117], v[116:117], 0 op_sel_hi:[1,0]
	v_pk_add_f32 v[114:115], v[114:115], 0 op_sel_hi:[1,0]
	v_pk_add_f32 v[112:113], v[112:113], 0 op_sel_hi:[1,0]
	v_pk_add_f32 v[110:111], v[110:111], 0 op_sel_hi:[1,0]
	v_pk_add_f32 v[108:109], v[108:109], 0 op_sel_hi:[1,0]
	v_pk_add_f32 v[106:107], v[106:107], 0 op_sel_hi:[1,0]
	v_pk_add_f32 v[104:105], v[104:105], 0 op_sel_hi:[1,0]
	v_pk_add_f32 v[102:103], v[102:103], 0 op_sel_hi:[1,0]
	v_pk_add_f32 v[100:101], v[100:101], 0 op_sel_hi:[1,0]
	v_pk_add_f32 v[98:99], v[98:99], 0 op_sel_hi:[1,0]
	v_pk_add_f32 v[92:93], v[92:93], 0 op_sel_hi:[1,0]
	v_pk_add_f32 v[90:91], v[90:91], 0 op_sel_hi:[1,0]
	v_pk_add_f32 v[144:145], v[84:85], 0 op_sel_hi:[1,0]
	v_pk_add_f32 v[152:153], v[82:83], 0 op_sel_hi:[1,0]
	v_pk_add_f32 v[76:77], v[76:77], 0 op_sel_hi:[1,0]
	v_pk_add_f32 v[84:85], v[74:75], 0 op_sel_hi:[1,0]
	v_pk_add_f32 v[146:147], v[68:69], 0 op_sel_hi:[1,0]
	v_pk_add_f32 v[154:155], v[66:67], 0 op_sel_hi:[1,0]
	v_pk_add_f32 v[74:75], v[60:61], 0 op_sel_hi:[1,0]
	v_pk_add_f32 v[140:141], v[58:59], 0 op_sel_hi:[1,0]
	v_pk_add_f32 v[148:149], v[52:53], 0 op_sel_hi:[1,0]
	v_pk_add_f32 v[156:157], v[50:51], 0 op_sel_hi:[1,0]
	v_pk_add_f32 v[82:83], v[44:45], 0 op_sel_hi:[1,0]
	v_pk_add_f32 v[142:143], v[42:43], 0 op_sel_hi:[1,0]
	v_pk_add_f32 v[150:151], v[36:37], 0 op_sel_hi:[1,0]
	v_pk_add_f32 v[158:159], v[34:35], 0 op_sel_hi:[1,0]
	v_pk_add_f32 v[34:35], v[96:97], 0 op_sel_hi:[1,0]
	v_pk_add_f32 v[36:37], v[94:95], 0 op_sel_hi:[1,0]
	v_pk_add_f32 v[50:51], v[88:89], 0 op_sel_hi:[1,0]
	v_pk_add_f32 v[52:53], v[86:87], 0 op_sel_hi:[1,0]
	v_pk_add_f32 v[42:43], v[80:81], 0 op_sel_hi:[1,0]
	v_pk_add_f32 v[44:45], v[78:79], 0 op_sel_hi:[1,0]
	v_pk_add_f32 v[66:67], v[72:73], 0 op_sel_hi:[1,0]
	v_pk_add_f32 v[68:69], v[70:71], 0 op_sel_hi:[1,0]
	v_pk_add_f32 v[58:59], v[64:65], 0 op_sel_hi:[1,0]
	v_pk_add_f32 v[60:61], v[62:63], 0 op_sel_hi:[1,0]
	v_pk_add_f32 v[56:57], v[56:57], 0 op_sel_hi:[1,0]
	v_pk_add_f32 v[54:55], v[54:55], 0 op_sel_hi:[1,0]
	v_pk_add_f32 v[48:49], v[48:49], 0 op_sel_hi:[1,0]
	v_pk_add_f32 v[46:47], v[46:47], 0 op_sel_hi:[1,0]
	v_pk_add_f32 v[40:41], v[40:41], 0 op_sel_hi:[1,0]
	v_pk_add_f32 v[38:39], v[38:39], 0 op_sel_hi:[1,0]
	v_pk_add_f32 v[32:33], v[32:33], 0 op_sel_hi:[1,0]
	v_pk_add_f32 v[30:31], v[30:31], 0 op_sel_hi:[1,0]
	v_pk_add_f32 v[28:29], v[28:29], 0 op_sel_hi:[1,0]
	v_pk_add_f32 v[26:27], v[26:27], 0 op_sel_hi:[1,0]
	v_pk_add_f32 v[24:25], v[24:25], 0 op_sel_hi:[1,0]
	v_pk_add_f32 v[22:23], v[22:23], 0 op_sel_hi:[1,0]
	v_pk_add_f32 v[20:21], v[20:21], 0 op_sel_hi:[1,0]
	v_pk_add_f32 v[18:19], v[18:19], 0 op_sel_hi:[1,0]
	v_pk_add_f32 v[16:17], v[16:17], 0 op_sel_hi:[1,0]
	v_pk_add_f32 v[14:15], v[14:15], 0 op_sel_hi:[1,0]
	v_pk_add_f32 v[12:13], v[12:13], 0 op_sel_hi:[1,0]
	v_pk_add_f32 v[10:11], v[10:11], 0 op_sel_hi:[1,0]
	v_pk_add_f32 v[8:9], v[8:9], 0 op_sel_hi:[1,0]
	v_pk_add_f32 v[6:7], v[6:7], 0 op_sel_hi:[1,0]
	v_pk_add_f32 v[4:5], v[4:5], 0 op_sel_hi:[1,0]
	v_pk_add_f32 v[2:3], v[2:3], 0 op_sel_hi:[1,0]
	s_movk_i32 s66, 0x80
	s_branch .LBB0_656

; #define PG8_STAGE(bufoff, gbase, voff) do { _Pragma("unroll") for (int _i = 0; _i < 2; ++_i) \
;         __builtin_amdgcn_global_load_lds((const unsigned*)((const char*)(gbase) + (voff)[_i]), (LAS unsigned*)(lds + (bufoff) + ldsw + _i * 8192), 16, 0, 0); } while (0)
; #define PG8_LDA(dst, b, h) do { _Pragma("unroll") for (int m = 0; m < 4; ++m) _Pragma("unroll") for (int k = 0; k < 2; ++k) dst[m][k] = *(const LAS h16x8*)(lds + PG8_SA(b, h) + aoff + m * 2048 + k * 1024); } while (0)
; #define PG8_LDB(dst, b, h) do { _Pragma("unroll") for (int n = 0; n < 2; ++n) _Pragma("unroll") for (int k = 0; k < 2; ++k) dst[n][k] = *(const LAS h16x8*)(lds + PG8_SB(b, h) + boff + n * 2048 + k * 1024); } while (0)
; #define PG8_MMA(ai, bj, At, Bt_) do { __builtin_amdgcn_s_setprio(1); _Pragma("unroll") for (int m = 0; m < 4; ++m) _Pragma("unroll") for (int n = 0; n < 2; ++n) _Pragma("unroll") for (int k = 0; k < 2; ++k) \
;         acc[ai][bj][m][n] = __builtin_amdgcn_mfma_f32_16x16x32_f16(Bt_[n][k], At[m][k], acc[ai][bj][m][n], 0, 0, 0); __builtin_amdgcn_s_setprio(0); } while (0)
; #define PG8_WAIT_V(n) asm volatile("s_waitcnt vmcnt(" #n ")" ::: "memory")
; #define PG8_WAIT_L(n) asm volatile("s_waitcnt lgkmcnt(" #n ")" ::: "memory")
; template <class Epi, class AMap>
; __device__ __forceinline__ void gemm_phase(LAS unsigned char* lds, const AMap am, const int lda, const h16* Bt, const int ldb, const int M, const int N, const int K, const Epi& E) {
;     ...
;             const bool last = (t == nt - 2);
;             const char* a1 = cA + (size_t)(t + 1) * kstep;
;             const char* a2 = last ? nA : cA + (size_t)(t + 2) * kstep; const char* b2 = last ? nB : cB + (size_t)(t + 2) * kstep;
;             const char* a3 = a2 + kstep; const char* b3 = b2 + kstep;
;             PG8_LDB(B0, 0, 0); PG8_SCHED; PG8_LDA(At, 0, 0); PG8_STAGE(PG8_SA(1, 1), a1 + hstepA, voffA);
;             PG8_WAIT_L(8); PG8_BAR; PG8_WAIT_L(0); PG8_MMA(0, 0, At, B0); PG8_BAR; PG8_SCHED;
;             PG8_LDB(B1, 0, 1); PG8_STAGE(PG8_SB(0, 0), b2, voffB);
;             PG8_BAR; PG8_WAIT_L(0); PG8_MMA(0, 1, At, B1); PG8_BAR;
;             PG8_LDA(At, 0, 1); PG8_STAGE(PG8_SA(0, 0), a2, voffA);
;             PG8_BAR; PG8_WAIT_L(0); PG8_MMA(1, 0, At, B0); PG8_BAR; PG8_SCHED;
;             PG8_STAGE(PG8_SB(0, 1), b2 + hstepB, voffB);
;             PG8_WAIT_V(6); PG8_BAR; PG8_MMA(1, 1, At, B1); PG8_BAR;
.LBB0_692:
	s_add_i32 s51, s26, 2
	s_add_u32 s0, s22, 0x100
	s_addc_u32 s1, s23, 0
	s_add_i32 s60, 0, 0x10000
	v_add_u32_e32 v234, s60, v175
	ds_read_b128 v[82:85], v234
	ds_read_b128 v[86:89], v234 offset:1024
	ds_read_b128 v[138:141], v234 offset:2048
	ds_read_b128 v[142:145], v234 offset:3072
	s_cmp_eq_u32 s61, s26
	s_cselect_b32 s26, s21, s29
	s_cselect_b32 s49, s47, s1
	s_cselect_b32 s48, s46, s0
	s_cselect_b32 s27, s20, s45
	v_lshl_add_u64 v[172:173], s[22:23], 0, v[152:153]
	s_add_i32 m0, s74, 0xc000
	ds_read_b128 v[156:159], v177
	ds_read_b128 v[160:163], v177 offset:1024
	ds_read_b128 v[164:167], v177 offset:2048
	ds_read_b128 v[168:171], v177 offset:3072
	ds_read_b128 v[178:181], v177 offset:4096
	ds_read_b128 v[182:185], v177 offset:5120
	ds_read_b128 v[186:189], v177 offset:6144
	ds_read_b128 v[190:193], v177 offset:7168
	global_load_lds_dwordx4 v[172:173], off
	v_lshl_add_u64 v[172:173], s[22:23], 0, v[154:155]
	s_add_i32 m0, s74, 0xe000
	s_nop 0
	global_load_lds_dwordx4 v[172:173], off
	s_waitcnt lgkmcnt(11)
	s_add_i32 s62, 0, 0x14000
	v_add_u32_e32 v172, s62, v175
	s_add_i32 s22, s60, s71
	ds_read_b128 v[194:197], v172
	ds_read_b128 v[198:201], v172 offset:1024
	ds_read_b128 v[202:205], v172 offset:2048
	ds_read_b128 v[220:223], v172 offset:3072
	s_waitcnt vmcnt(8) lgkmcnt(0)
	s_barrier
	v_mfma_f32_16x16x32_f16 v[134:137], v[82:85], v[156:159], v[134:137]
	v_mfma_f32_16x16x32_f16 v[130:133], v[138:141], v[156:159], v[130:133]
	v_mfma_f32_16x16x32_f16 v[126:129], v[82:85], v[164:167], v[126:129]
	v_mfma_f32_16x16x32_f16 v[122:125], v[138:141], v[164:167], v[122:125]
	v_mfma_f32_16x16x32_f16 v[118:121], v[82:85], v[178:181], v[118:121]
	v_mfma_f32_16x16x32_f16 v[114:117], v[138:141], v[178:181], v[114:117]
	v_mfma_f32_16x16x32_f16 v[110:113], v[82:85], v[186:189], v[110:113]
	v_mfma_f32_16x16x32_f16 v[106:109], v[138:141], v[186:189], v[106:109]
	v_mfma_f32_16x16x32_f16 v[134:137], v[86:89], v[160:163], v[134:137]
	v_mfma_f32_16x16x32_f16 v[130:133], v[142:145], v[160:163], v[130:133]
	v_mfma_f32_16x16x32_f16 v[126:129], v[86:89], v[168:171], v[126:129]
	v_mfma_f32_16x16x32_f16 v[122:125], v[142:145], v[168:171], v[122:125]
	v_mfma_f32_16x16x32_f16 v[118:121], v[86:89], v[182:185], v[118:121]
	v_mfma_f32_16x16x32_f16 v[114:117], v[142:145], v[182:185], v[114:117]
	v_mfma_f32_16x16x32_f16 v[110:113], v[86:89], v[190:193], v[110:113]
	v_mfma_f32_16x16x32_f16 v[106:109], v[142:145], v[190:193], v[106:109]
	v_mfma_f32_16x16x32_f16 v[62:65], v[194:197], v[156:159], v[62:65]
	v_mfma_f32_16x16x32_f16 v[58:61], v[202:205], v[156:159], v[58:61]
	v_mfma_f32_16x16x32_f16 v[54:57], v[194:197], v[164:167], v[54:57]
	v_mfma_f32_16x16x32_f16 v[50:53], v[202:205], v[164:167], v[50:53]
	v_mfma_f32_16x16x32_f16 v[46:49], v[194:197], v[178:181], v[46:49]
	v_mfma_f32_16x16x32_f16 v[42:45], v[202:205], v[178:181], v[42:45]
	v_mfma_f32_16x16x32_f16 v[38:41], v[194:197], v[186:189], v[38:41]
	v_mfma_f32_16x16x32_f16 v[34:37], v[202:205], v[186:189], v[34:37]
	v_mfma_f32_16x16x32_f16 v[62:65], v[198:201], v[160:163], v[62:65]
	v_mfma_f32_16x16x32_f16 v[58:61], v[220:223], v[160:163], v[58:61]
	v_mfma_f32_16x16x32_f16 v[54:57], v[198:201], v[168:171], v[54:57]
	v_mfma_f32_16x16x32_f16 v[50:53], v[220:223], v[168:171], v[50:53]
	v_mfma_f32_16x16x32_f16 v[46:49], v[198:201], v[182:185], v[46:49]
	v_mfma_f32_16x16x32_f16 v[42:45], v[220:223], v[182:185], v[42:45]
	v_mfma_f32_16x16x32_f16 v[38:41], v[198:201], v[190:193], v[38:41]
	v_mfma_f32_16x16x32_f16 v[34:37], v[220:223], v[190:193], v[34:37]
	s_barrier
	v_lshl_add_u64 v[172:173], s[26:27], 0, v[0:1]
	s_mov_b32 m0, s22
	v_lshl_add_u64 v[206:207], s[26:27], 0, v[150:151]
	global_load_lds_dwordx4 v[172:173], off
	s_add_i32 m0, s22, 0x2000
	s_nop 0
	global_load_lds_dwordx4 v[206:207], off
	s_mov_b32 m0, s74
	v_lshl_add_u64 v[212:213], s[48:49], 0, v[146:147]
	ds_read_b128 v[156:159], v177 offset:16384
	ds_read_b128 v[160:163], v177 offset:17408
	ds_read_b128 v[164:167], v177 offset:18432
	ds_read_b128 v[168:171], v177 offset:19456
	ds_read_b128 v[178:181], v177 offset:20480
	ds_read_b128 v[182:185], v177 offset:21504
	ds_read_b128 v[186:189], v177 offset:22528
	ds_read_b128 v[190:193], v177 offset:23552
	global_load_lds_dwordx4 v[212:213], off
	v_lshl_add_u64 v[224:225], s[48:49], 0, v[148:149]
	s_mov_b32 m0, s75
	s_nop 0
	global_load_lds_dwordx4 v[224:225], off
	s_add_u32 s22, s26, 0x10000
	s_addc_u32 s23, s27, 0
	s_add_i32 s60, s62, s71
	v_lshl_add_u64 v[232:233], s[22:23], 0, v[0:1]
	s_mov_b32 m0, s60
	s_nop 0
	global_load_lds_dwordx4 v[232:233], off
	v_lshl_add_u64 v[232:233], s[22:23], 0, v[150:151]
	s_add_i32 m0, s60, 0x2000
	s_nop 0
	global_load_lds_dwordx4 v[232:233], off
	s_waitcnt vmcnt(8) lgkmcnt(0)
	s_barrier
; #define PG8_STAGE(bufoff, gbase, voff) do { _Pragma("unroll") for (int _i = 0; _i < 2; ++_i) \
;         __builtin_amdgcn_global_load_lds((const unsigned*)((const char*)(gbase) + (voff)[_i]), (LAS unsigned*)(lds + (bufoff) + ldsw + _i * 8192), 16, 0, 0); } while (0)
; #define PG8_LDA(dst, b, h) do { _Pragma("unroll") for (int m = 0; m < 4; ++m) _Pragma("unroll") for (int k = 0; k < 2; ++k) dst[m][k] = *(const LAS h16x8*)(lds + PG8_SA(b, h) + aoff + m * 2048 + k * 1024); } while (0)
; #define PG8_LDB(dst, b, h) do { _Pragma("unroll") for (int n = 0; n < 2; ++n) _Pragma("unroll") for (int k = 0; k < 2; ++k) dst[n][k] = *(const LAS h16x8*)(lds + PG8_SB(b, h) + boff + n * 2048 + k * 1024); } while (0)
; #define PG8_MMA(ai, bj, At, Bt_) do { __builtin_amdgcn_s_setprio(1); _Pragma("unroll") for (int m = 0; m < 4; ++m) _Pragma("unroll") for (int n = 0; n < 2; ++n) _Pragma("unroll") for (int k = 0; k < 2; ++k) \
;         acc[ai][bj][m][n] = __builtin_amdgcn_mfma_f32_16x16x32_f16(Bt_[n][k], At[m][k], acc[ai][bj][m][n], 0, 0, 0); __builtin_amdgcn_s_setprio(0); } while (0)
; #define PG8_WAIT_V(n) asm volatile("s_waitcnt vmcnt(" #n ")" ::: "memory")
; #define PG8_WAIT_L(n) asm volatile("s_waitcnt lgkmcnt(" #n ")" ::: "memory")
; #define PG8_BAR __builtin_amdgcn_s_barrier()
; #define PG8_SCHED __builtin_amdgcn_sched_barrier(0)
; template <class Epi, class AMap>
; __device__ __forceinline__ void gemm_phase(LAS unsigned char* lds, const AMap am, const int lda, const h16* Bt, const int ldb, const int M, const int N, const int K, const Epi& E) {
;     ...
;             PG8_BAR; PG8_WAIT_L(0); PG8_MMA(1, 0, At, B0); PG8_BAR; PG8_SCHED;
;             PG8_STAGE(PG8_SB(0, 1), b2 + hstepB, voffB);
;             PG8_WAIT_V(6); PG8_BAR; PG8_MMA(1, 1, At, B1); PG8_BAR;
;             PG8_LDB(B0, 1, 0); PG8_SCHED; PG8_LDA(At, 1, 0); PG8_STAGE(PG8_SA(0, 1), a2 + hstepA, voffA);
;             PG8_WAIT_L(8); PG8_BAR; PG8_WAIT_L(0); PG8_MMA(0, 0, At, B0); PG8_BAR; PG8_SCHED;
;             PG8_LDB(B1, 1, 1); PG8_STAGE(PG8_SB(1, 0), b3, voffB);
;             PG8_BAR; PG8_WAIT_L(0); PG8_MMA(0, 1, At, B1); PG8_BAR;
	v_mfma_f32_16x16x32_f16 v[102:105], v[82:85], v[156:159], v[102:105]
	v_mfma_f32_16x16x32_f16 v[98:101], v[138:141], v[156:159], v[98:101]
	v_mfma_f32_16x16x32_f16 v[94:97], v[82:85], v[164:167], v[94:97]
	v_mfma_f32_16x16x32_f16 v[90:93], v[138:141], v[164:167], v[90:93]
	v_mfma_f32_16x16x32_f16 v[78:81], v[82:85], v[178:181], v[78:81]
	v_mfma_f32_16x16x32_f16 v[74:77], v[138:141], v[178:181], v[74:77]
	v_mfma_f32_16x16x32_f16 v[70:73], v[82:85], v[186:189], v[70:73]
	v_mfma_f32_16x16x32_f16 v[66:69], v[138:141], v[186:189], v[66:69]
	v_mfma_f32_16x16x32_f16 v[102:105], v[86:89], v[160:163], v[102:105]
	v_mfma_f32_16x16x32_f16 v[98:101], v[142:145], v[160:163], v[98:101]
	v_mfma_f32_16x16x32_f16 v[94:97], v[86:89], v[168:171], v[94:97]
	v_mfma_f32_16x16x32_f16 v[90:93], v[142:145], v[168:171], v[90:93]
	v_mfma_f32_16x16x32_f16 v[78:81], v[86:89], v[182:185], v[78:81]
	v_mfma_f32_16x16x32_f16 v[74:77], v[142:145], v[182:185], v[74:77]
	v_mfma_f32_16x16x32_f16 v[70:73], v[86:89], v[190:193], v[70:73]
	v_mfma_f32_16x16x32_f16 v[66:69], v[142:145], v[190:193], v[66:69]
	v_mfma_f32_16x16x32_f16 v[30:33], v[194:197], v[156:159], v[30:33]
	v_mfma_f32_16x16x32_f16 v[26:29], v[202:205], v[156:159], v[26:29]
	v_mfma_f32_16x16x32_f16 v[22:25], v[194:197], v[164:167], v[22:25]
	v_mfma_f32_16x16x32_f16 v[18:21], v[202:205], v[164:167], v[18:21]
	v_mfma_f32_16x16x32_f16 v[14:17], v[194:197], v[178:181], v[14:17]
	v_mfma_f32_16x16x32_f16 v[10:13], v[202:205], v[178:181], v[10:13]
	v_mfma_f32_16x16x32_f16 v[6:9], v[194:197], v[186:189], v[6:9]
	v_mfma_f32_16x16x32_f16 v[2:5], v[202:205], v[186:189], v[2:5]
	v_mfma_f32_16x16x32_f16 v[30:33], v[198:201], v[160:163], v[30:33]
	v_mfma_f32_16x16x32_f16 v[26:29], v[220:223], v[160:163], v[26:29]
	v_mfma_f32_16x16x32_f16 v[22:25], v[198:201], v[168:171], v[22:25]
	v_mfma_f32_16x16x32_f16 v[18:21], v[220:223], v[168:171], v[18:21]
	v_mfma_f32_16x16x32_f16 v[14:17], v[198:201], v[182:185], v[14:17]
	v_mfma_f32_16x16x32_f16 v[10:13], v[220:223], v[182:185], v[10:13]
	v_mfma_f32_16x16x32_f16 v[6:9], v[198:201], v[190:193], v[6:9]
	v_mfma_f32_16x16x32_f16 v[2:5], v[220:223], v[190:193], v[2:5]
	s_barrier
	s_add_i32 s60, 0, 0x18000
	v_add_u32_e32 v234, s60, v175
	ds_read_b128 v[82:85], v234
	ds_read_b128 v[86:89], v234 offset:1024
	ds_read_b128 v[138:141], v234 offset:2048
	ds_read_b128 v[142:145], v234 offset:3072
	s_add_u32 s22, s48, 0x1c0000
	s_addc_u32 s23, s49, 0
	s_mov_b32 m0, s76
	v_lshl_add_u64 v[232:233], s[22:23], 0, v[146:147]
	ds_read_b128 v[156:159], v177 offset:32768
	ds_read_b128 v[160:163], v177 offset:33792
	ds_read_b128 v[164:167], v177 offset:34816
	ds_read_b128 v[168:171], v177 offset:35840
	ds_read_b128 v[178:181], v177 offset:36864
	ds_read_b128 v[182:185], v177 offset:37888
	ds_read_b128 v[186:189], v177 offset:38912
	ds_read_b128 v[190:193], v177 offset:39936
	global_load_lds_dwordx4 v[232:233], off
	v_lshl_add_u64 v[232:233], s[22:23], 0, v[148:149]
	s_mov_b32 m0, s77
	s_nop 0
	global_load_lds_dwordx4 v[232:233], off
	s_waitcnt lgkmcnt(11)
	s_add_i32 s48, 0, 0x1c000
	s_add_i32 s22, s60, s71
	v_add_u32_e32 v214, s48, v175
	v_lshl_add_u64 v[172:173], v[172:173], 0, s[92:93]
	s_mov_b32 m0, s22
	ds_read_b128 v[194:197], v214
	ds_read_b128 v[198:201], v214 offset:1024
	ds_read_b128 v[202:205], v214 offset:2048
	ds_read_b128 v[220:223], v214 offset:3072
	s_waitcnt vmcnt(8) lgkmcnt(0)
	s_barrier
	v_mfma_f32_16x16x32_f16 v[134:137], v[82:85], v[156:159], v[134:137]
	v_mfma_f32_16x16x32_f16 v[130:133], v[138:141], v[156:159], v[130:133]
	v_mfma_f32_16x16x32_f16 v[126:129], v[82:85], v[164:167], v[126:129]
	v_mfma_f32_16x16x32_f16 v[122:125], v[138:141], v[164:167], v[122:125]
	v_mfma_f32_16x16x32_f16 v[118:121], v[82:85], v[178:181], v[118:121]
	v_mfma_f32_16x16x32_f16 v[114:117], v[138:141], v[178:181], v[114:117]
	v_mfma_f32_16x16x32_f16 v[110:113], v[82:85], v[186:189], v[110:113]
	v_mfma_f32_16x16x32_f16 v[106:109], v[138:141], v[186:189], v[106:109]
	v_mfma_f32_16x16x32_f16 v[134:137], v[86:89], v[160:163], v[134:137]
	v_mfma_f32_16x16x32_f16 v[130:133], v[142:145], v[160:163], v[130:133]
	v_mfma_f32_16x16x32_f16 v[126:129], v[86:89], v[168:171], v[126:129]
	v_mfma_f32_16x16x32_f16 v[122:125], v[142:145], v[168:171], v[122:125]
	v_mfma_f32_16x16x32_f16 v[118:121], v[86:89], v[182:185], v[118:121]
	v_mfma_f32_16x16x32_f16 v[114:117], v[142:145], v[182:185], v[114:117]
	v_mfma_f32_16x16x32_f16 v[110:113], v[86:89], v[190:193], v[110:113]
	v_mfma_f32_16x16x32_f16 v[106:109], v[142:145], v[190:193], v[106:109]
	v_mfma_f32_16x16x32_f16 v[62:65], v[194:197], v[156:159], v[62:65]
	v_mfma_f32_16x16x32_f16 v[58:61], v[202:205], v[156:159], v[58:61]
	v_mfma_f32_16x16x32_f16 v[54:57], v[194:197], v[164:167], v[54:57]
	v_mfma_f32_16x16x32_f16 v[50:53], v[202:205], v[164:167], v[50:53]
	v_mfma_f32_16x16x32_f16 v[46:49], v[194:197], v[178:181], v[46:49]
	v_mfma_f32_16x16x32_f16 v[42:45], v[202:205], v[178:181], v[42:45]
	v_mfma_f32_16x16x32_f16 v[38:41], v[194:197], v[186:189], v[38:41]
	v_mfma_f32_16x16x32_f16 v[34:37], v[202:205], v[186:189], v[34:37]
	v_mfma_f32_16x16x32_f16 v[62:65], v[198:201], v[160:163], v[62:65]
	v_mfma_f32_16x16x32_f16 v[58:61], v[220:223], v[160:163], v[58:61]
	v_mfma_f32_16x16x32_f16 v[54:57], v[198:201], v[168:171], v[54:57]
	v_mfma_f32_16x16x32_f16 v[50:53], v[220:223], v[168:171], v[50:53]
	v_mfma_f32_16x16x32_f16 v[46:49], v[198:201], v[182:185], v[46:49]
	v_mfma_f32_16x16x32_f16 v[42:45], v[220:223], v[182:185], v[42:45]
	v_mfma_f32_16x16x32_f16 v[38:41], v[198:201], v[190:193], v[38:41]
	v_mfma_f32_16x16x32_f16 v[34:37], v[220:223], v[190:193], v[34:37]
	s_barrier
; #define PG8_STAGE(bufoff, gbase, voff) do { _Pragma("unroll") for (int _i = 0; _i < 2; ++_i) \
;         __builtin_amdgcn_global_load_lds((const unsigned*)((const char*)(gbase) + (voff)[_i]), (LAS unsigned*)(lds + (bufoff) + ldsw + _i * 8192), 16, 0, 0); } while (0)
; #define PG8_LDA(dst, b, h) do { _Pragma("unroll") for (int m = 0; m < 4; ++m) _Pragma("unroll") for (int k = 0; k < 2; ++k) dst[m][k] = *(const LAS h16x8*)(lds + PG8_SA(b, h) + aoff + m * 2048 + k * 1024); } while (0)
; #define PG8_MMA(ai, bj, At, Bt_) do { __builtin_amdgcn_s_setprio(1); _Pragma("unroll") for (int m = 0; m < 4; ++m) _Pragma("unroll") for (int n = 0; n < 2; ++n) _Pragma("unroll") for (int k = 0; k < 2; ++k) \
;         acc[ai][bj][m][n] = __builtin_amdgcn_mfma_f32_16x16x32_f16(Bt_[n][k], At[m][k], acc[ai][bj][m][n], 0, 0, 0); __builtin_amdgcn_s_setprio(0); } while (0)
; #define PG8_WAIT_V(n) asm volatile("s_waitcnt vmcnt(" #n ")" ::: "memory")
; #define PG8_WAIT_L(n) asm volatile("s_waitcnt lgkmcnt(" #n ")" ::: "memory")
; #define PG8_BAR __builtin_amdgcn_s_barrier()
; #define PG8_SCHED __builtin_amdgcn_sched_barrier(0)
; template <class Epi, class AMap>
; __device__ __forceinline__ void gemm_phase(LAS unsigned char* lds, const AMap am, const int lda, const h16* Bt, const int ldb, const int M, const int N, const int K, const Epi& E) {
;     ...
;             PG8_LDA(At, 1, 1); PG8_STAGE(PG8_SA(1, 0), a3, voffA);
;             PG8_BAR; PG8_WAIT_L(0); PG8_MMA(1, 0, At, B0); PG8_BAR; PG8_SCHED;
;             PG8_STAGE(PG8_SB(1, 1), b3 + hstepB, voffB);
;             PG8_WAIT_V(6); PG8_BAR; PG8_MMA(1, 1, At, B1); PG8_BAR;
;         }
	global_load_lds_dwordx4 v[172:173], off
	v_lshl_add_u64 v[172:173], v[206:207], 0, s[92:93]
	s_add_i32 m0, s22, 0x2000
	s_nop 0
	global_load_lds_dwordx4 v[172:173], off
	s_mov_b32 m0, s79
	v_lshl_add_u64 v[172:173], v[212:213], 0, s[92:93]
	ds_read_b128 v[156:159], v177 offset:49152
	ds_read_b128 v[160:163], v177 offset:50176
	ds_read_b128 v[164:167], v177 offset:51200
	ds_read_b128 v[168:171], v177 offset:52224
	ds_read_b128 v[178:181], v177 offset:53248
	ds_read_b128 v[182:185], v177 offset:54272
	ds_read_b128 v[186:189], v177 offset:55296
	ds_read_b128 v[190:193], v177 offset:56320
	global_load_lds_dwordx4 v[172:173], off
	v_lshl_add_u64 v[172:173], v[224:225], 0, s[92:93]
	s_mov_b32 m0, s80
	s_nop 0
	global_load_lds_dwordx4 v[172:173], off
	s_add_u32 s22, s26, 0x10080
	s_addc_u32 s23, s27, 0
	s_add_i32 s26, s48, s71
	v_lshl_add_u64 v[232:233], s[22:23], 0, v[0:1]
	s_mov_b32 m0, s26
	s_nop 0
	global_load_lds_dwordx4 v[232:233], off
	v_lshl_add_u64 v[232:233], s[22:23], 0, v[150:151]
	s_add_i32 m0, s26, 0x2000
	s_nop 0
	global_load_lds_dwordx4 v[232:233], off
	s_waitcnt vmcnt(8) lgkmcnt(0)
	s_barrier
	v_mfma_f32_16x16x32_f16 v[102:105], v[82:85], v[156:159], v[102:105]
	v_mfma_f32_16x16x32_f16 v[98:101], v[138:141], v[156:159], v[98:101]
	v_mfma_f32_16x16x32_f16 v[94:97], v[82:85], v[164:167], v[94:97]
	v_mfma_f32_16x16x32_f16 v[90:93], v[138:141], v[164:167], v[90:93]
	v_mfma_f32_16x16x32_f16 v[78:81], v[82:85], v[178:181], v[78:81]
	v_mfma_f32_16x16x32_f16 v[74:77], v[138:141], v[178:181], v[74:77]
	v_mfma_f32_16x16x32_f16 v[70:73], v[82:85], v[186:189], v[70:73]
	v_mfma_f32_16x16x32_f16 v[66:69], v[138:141], v[186:189], v[66:69]
	v_mfma_f32_16x16x32_f16 v[102:105], v[86:89], v[160:163], v[102:105]
	v_mfma_f32_16x16x32_f16 v[98:101], v[142:145], v[160:163], v[98:101]
	v_mfma_f32_16x16x32_f16 v[94:97], v[86:89], v[168:171], v[94:97]
	v_mfma_f32_16x16x32_f16 v[90:93], v[142:145], v[168:171], v[90:93]
	v_mfma_f32_16x16x32_f16 v[78:81], v[86:89], v[182:185], v[78:81]
	v_mfma_f32_16x16x32_f16 v[74:77], v[142:145], v[182:185], v[74:77]
	v_mfma_f32_16x16x32_f16 v[70:73], v[86:89], v[190:193], v[70:73]
	v_mfma_f32_16x16x32_f16 v[66:69], v[142:145], v[190:193], v[66:69]
	v_mfma_f32_16x16x32_f16 v[30:33], v[194:197], v[156:159], v[30:33]
	v_mfma_f32_16x16x32_f16 v[26:29], v[202:205], v[156:159], v[26:29]
	v_mfma_f32_16x16x32_f16 v[22:25], v[194:197], v[164:167], v[22:25]
	v_mfma_f32_16x16x32_f16 v[18:21], v[202:205], v[164:167], v[18:21]
	v_mfma_f32_16x16x32_f16 v[14:17], v[194:197], v[178:181], v[14:17]
	v_mfma_f32_16x16x32_f16 v[10:13], v[202:205], v[178:181], v[10:13]
	v_mfma_f32_16x16x32_f16 v[6:9], v[194:197], v[186:189], v[6:9]
	v_mfma_f32_16x16x32_f16 v[2:5], v[202:205], v[186:189], v[2:5]
	v_mfma_f32_16x16x32_f16 v[30:33], v[198:201], v[160:163], v[30:33]
	v_mfma_f32_16x16x32_f16 v[26:29], v[220:223], v[160:163], v[26:29]
	v_mfma_f32_16x16x32_f16 v[22:25], v[198:201], v[168:171], v[22:25]
	v_mfma_f32_16x16x32_f16 v[18:21], v[220:223], v[168:171], v[18:21]
	v_mfma_f32_16x16x32_f16 v[14:17], v[198:201], v[182:185], v[14:17]
	v_mfma_f32_16x16x32_f16 v[10:13], v[220:223], v[182:185], v[10:13]
	v_mfma_f32_16x16x32_f16 v[6:9], v[198:201], v[190:193], v[6:9]
	v_mfma_f32_16x16x32_f16 v[2:5], v[220:223], v[190:193], v[2:5]
	s_add_u32 s29, s29, 0x100
	s_addc_u32 s45, s45, 0
	s_cmp_ge_i32 s51, s24
	s_mov_b64 s[22:23], s[0:1]
	s_mov_b32 s26, s51
	s_barrier
	s_cbranch_scc0 .LBB0_692
	s_branch .LBB0_681

; #define PG8_STAGE(bufoff, gbase, voff) do { _Pragma("unroll") for (int _i = 0; _i < 2; ++_i) \
;         __builtin_amdgcn_global_load_lds((const unsigned*)((const char*)(gbase) + (voff)[_i]), (LAS unsigned*)(lds + (bufoff) + ldsw + _i * 8192), 16, 0, 0); } while (0)
; #define PG8_LDA(dst, b, h) do { _Pragma("unroll") for (int m = 0; m < 4; ++m) _Pragma("unroll") for (int k = 0; k < 2; ++k) dst[m][k] = *(const LAS h16x8*)(lds + PG8_SA(b, h) + aoff + m * 2048 + k * 1024); } while (0)
; #define PG8_LDB(dst, b, h) do { _Pragma("unroll") for (int n = 0; n < 2; ++n) _Pragma("unroll") for (int k = 0; k < 2; ++k) dst[n][k] = *(const LAS h16x8*)(lds + PG8_SB(b, h) + boff + n * 2048 + k * 1024); } while (0)
; #define PG8_MMA(ai, bj, At, Bt_) do { __builtin_amdgcn_s_setprio(1); _Pragma("unroll") for (int m = 0; m < 4; ++m) _Pragma("unroll") for (int n = 0; n < 2; ++n) _Pragma("unroll") for (int k = 0; k < 2; ++k) \
;         acc[ai][bj][m][n] = __builtin_amdgcn_mfma_f32_16x16x32_f16(Bt_[n][k], At[m][k], acc[ai][bj][m][n], 0, 0, 0); __builtin_amdgcn_s_setprio(0); } while (0)
; #define PG8_WAIT_V(n) asm volatile("s_waitcnt vmcnt(" #n ")" ::: "memory")
; template <class Epi, class AMap>
; __device__ __forceinline__ void gemm_phase(LAS unsigned char* lds, const AMap am, const int lda, const h16* Bt, const int ldb, const int M, const int N, const int K, const Epi& E) {
;     ...
;         for (int t = 0; t < nt; t += 2) {
;             const bool last = (t == nt - 2);
;             const char* a1 = cA + (size_t)(t + 1) * kstep;
;             const char* a2 = last ? nA : cA + (size_t)(t + 2) * kstep; const char* b2 = last ? nB : cB + (size_t)(t + 2) * kstep;
;             const char* a3 = a2 + kstep; const char* b3 = b2 + kstep;
;             PG8_LDB(B0, 0, 0); PG8_SCHED; PG8_LDA(At, 0, 0); PG8_STAGE(PG8_SA(1, 1), a1 + hstepA, voffA);
;             PG8_WAIT_L(8); PG8_BAR; PG8_WAIT_L(0); PG8_MMA(0, 0, At, B0); PG8_BAR; PG8_SCHED;
;             PG8_LDB(B1, 0, 1); PG8_STAGE(PG8_SB(0, 0), b2, voffB);
;             PG8_BAR; PG8_WAIT_L(0); PG8_MMA(0, 1, At, B1); PG8_BAR;
;             PG8_LDA(At, 0, 1); PG8_STAGE(PG8_SA(0, 0), a2, voffA);
;             PG8_BAR; PG8_WAIT_L(0); PG8_MMA(1, 0, At, B0); PG8_BAR; PG8_SCHED;
;             PG8_STAGE(PG8_SB(0, 1), b2 + hstepB, voffB);
;             PG8_WAIT_V(6); PG8_BAR; PG8_MMA(1, 1, At, B1); PG8_BAR;
.LBB0_799:
	s_add_u32 s40, s0, 0xfff80080
	s_addc_u32 s41, s1, -1
	s_add_i32 s45, 0, 0x10000
	v_add_u32_e32 v152, s45, v155
	ds_read_b128 v[130:133], v152
	ds_read_b128 v[134:137], v152 offset:1024
	ds_read_b128 v[148:151], v152 offset:2048
	ds_read_b128 v[158:161], v152 offset:3072
	s_cmp_eq_u32 s43, 28
	s_cselect_b32 s49, s47, s41
	s_cselect_b32 s48, s46, s40
	s_cselect_b32 s41, s29, s35
	s_cselect_b32 s40, s20, s21
	v_lshl_add_u64 v[152:153], s[0:1], 0, v[144:145]
	s_add_i32 m0, s23, 0xc000
	ds_read_b128 v[162:165], v157
	ds_read_b128 v[166:169], v157 offset:1024
	ds_read_b128 v[170:173], v157 offset:2048
	ds_read_b128 v[174:177], v157 offset:3072
	ds_read_b128 v[178:181], v157 offset:4096
	ds_read_b128 v[182:185], v157 offset:5120
	ds_read_b128 v[186:189], v157 offset:6144
	ds_read_b128 v[190:193], v157 offset:7168
	global_load_lds_dwordx4 v[152:153], off
	v_lshl_add_u64 v[152:153], s[0:1], 0, v[146:147]
	s_add_i32 m0, s23, 0xe000
	s_nop 0
	global_load_lds_dwordx4 v[152:153], off
	s_waitcnt lgkmcnt(11)
	s_add_i32 s60, 0, 0x14000
	v_add_u32_e32 v152, s60, v155
	s_add_i32 s45, s45, s72
	ds_read_b128 v[194:197], v152
	ds_read_b128 v[198:201], v152 offset:1024
	ds_read_b128 v[202:205], v152 offset:2048
	ds_read_b128 v[220:223], v152 offset:3072
	s_waitcnt vmcnt(8) lgkmcnt(0)
	s_barrier
	v_mfma_f32_16x16x32_f16 v[126:129], v[130:133], v[162:165], v[126:129]
	v_mfma_f32_16x16x32_f16 v[122:125], v[148:151], v[162:165], v[122:125]
	v_mfma_f32_16x16x32_f16 v[110:113], v[130:133], v[170:173], v[110:113]
	v_mfma_f32_16x16x32_f16 v[106:109], v[148:151], v[170:173], v[106:109]
	v_mfma_f32_16x16x32_f16 v[94:97], v[130:133], v[178:181], v[94:97]
	v_mfma_f32_16x16x32_f16 v[90:93], v[148:151], v[178:181], v[90:93]
	v_mfma_f32_16x16x32_f16 v[78:81], v[130:133], v[186:189], v[78:81]
	v_mfma_f32_16x16x32_f16 v[74:77], v[148:151], v[186:189], v[74:77]
	v_mfma_f32_16x16x32_f16 v[126:129], v[134:137], v[166:169], v[126:129]
	v_mfma_f32_16x16x32_f16 v[122:125], v[158:161], v[166:169], v[122:125]
	v_mfma_f32_16x16x32_f16 v[110:113], v[134:137], v[174:177], v[110:113]
	v_mfma_f32_16x16x32_f16 v[106:109], v[158:161], v[174:177], v[106:109]
	v_mfma_f32_16x16x32_f16 v[94:97], v[134:137], v[182:185], v[94:97]
	v_mfma_f32_16x16x32_f16 v[90:93], v[158:161], v[182:185], v[90:93]
	v_mfma_f32_16x16x32_f16 v[78:81], v[134:137], v[190:193], v[78:81]
	v_mfma_f32_16x16x32_f16 v[74:77], v[158:161], v[190:193], v[74:77]
	v_mfma_f32_16x16x32_f16 v[118:121], v[194:197], v[162:165], v[118:121]
	v_mfma_f32_16x16x32_f16 v[114:117], v[202:205], v[162:165], v[114:117]
	v_mfma_f32_16x16x32_f16 v[102:105], v[194:197], v[170:173], v[102:105]
	v_mfma_f32_16x16x32_f16 v[98:101], v[202:205], v[170:173], v[98:101]
	v_mfma_f32_16x16x32_f16 v[86:89], v[194:197], v[178:181], v[86:89]
	v_mfma_f32_16x16x32_f16 v[82:85], v[202:205], v[178:181], v[82:85]
	v_mfma_f32_16x16x32_f16 v[70:73], v[194:197], v[186:189], v[70:73]
	v_mfma_f32_16x16x32_f16 v[66:69], v[202:205], v[186:189], v[66:69]
	v_mfma_f32_16x16x32_f16 v[118:121], v[198:201], v[166:169], v[118:121]
	v_mfma_f32_16x16x32_f16 v[114:117], v[220:223], v[166:169], v[114:117]
	v_mfma_f32_16x16x32_f16 v[102:105], v[198:201], v[174:177], v[102:105]
	v_mfma_f32_16x16x32_f16 v[98:101], v[220:223], v[174:177], v[98:101]
	v_mfma_f32_16x16x32_f16 v[86:89], v[198:201], v[182:185], v[86:89]
	v_mfma_f32_16x16x32_f16 v[82:85], v[220:223], v[182:185], v[82:85]
	v_mfma_f32_16x16x32_f16 v[70:73], v[198:201], v[190:193], v[70:73]
	v_mfma_f32_16x16x32_f16 v[66:69], v[220:223], v[190:193], v[66:69]
	s_barrier
	v_lshl_add_u64 v[152:153], s[40:41], 0, v[0:1]
	s_mov_b32 m0, s45
	v_lshl_add_u64 v[206:207], s[40:41], 0, v[142:143]
	global_load_lds_dwordx4 v[152:153], off
	s_add_i32 m0, s45, 0x2000
	s_nop 0
	global_load_lds_dwordx4 v[206:207], off
	s_mov_b32 m0, s23
	v_lshl_add_u64 v[212:213], s[48:49], 0, v[138:139]
	ds_read_b128 v[162:165], v157 offset:16384
	ds_read_b128 v[166:169], v157 offset:17408
	ds_read_b128 v[170:173], v157 offset:18432
	ds_read_b128 v[174:177], v157 offset:19456
	ds_read_b128 v[178:181], v157 offset:20480
	ds_read_b128 v[182:185], v157 offset:21504
	ds_read_b128 v[186:189], v157 offset:22528
	ds_read_b128 v[190:193], v157 offset:23552
	global_load_lds_dwordx4 v[212:213], off
	v_lshl_add_u64 v[224:225], s[48:49], 0, v[140:141]
	s_mov_b32 m0, s27
	s_nop 0
	global_load_lds_dwordx4 v[224:225], off
	s_add_u32 s50, s40, 0x80000
	s_addc_u32 s51, s41, 0
	s_add_i32 s45, s60, s72
	v_lshl_add_u64 v[232:233], s[50:51], 0, v[0:1]
	s_mov_b32 m0, s45
	s_nop 0
	global_load_lds_dwordx4 v[232:233], off
	v_lshl_add_u64 v[232:233], s[50:51], 0, v[142:143]
	s_add_i32 m0, s45, 0x2000
	s_nop 0
	global_load_lds_dwordx4 v[232:233], off
	s_waitcnt vmcnt(8) lgkmcnt(0)
	s_barrier
; #define PG8_STAGE(bufoff, gbase, voff) do { _Pragma("unroll") for (int _i = 0; _i < 2; ++_i) \
;         __builtin_amdgcn_global_load_lds((const unsigned*)((const char*)(gbase) + (voff)[_i]), (LAS unsigned*)(lds + (bufoff) + ldsw + _i * 8192), 16, 0, 0); } while (0)
; #define PG8_LDA(dst, b, h) do { _Pragma("unroll") for (int m = 0; m < 4; ++m) _Pragma("unroll") for (int k = 0; k < 2; ++k) dst[m][k] = *(const LAS h16x8*)(lds + PG8_SA(b, h) + aoff + m * 2048 + k * 1024); } while (0)
; #define PG8_LDB(dst, b, h) do { _Pragma("unroll") for (int n = 0; n < 2; ++n) _Pragma("unroll") for (int k = 0; k < 2; ++k) dst[n][k] = *(const LAS h16x8*)(lds + PG8_SB(b, h) + boff + n * 2048 + k * 1024); } while (0)
; #define PG8_WAIT_V(n) asm volatile("s_waitcnt vmcnt(" #n ")" ::: "memory")
; #define PG8_WAIT_L(n) asm volatile("s_waitcnt lgkmcnt(" #n ")" ::: "memory")
; #define PG8_BAR __builtin_amdgcn_s_barrier()
; #define PG8_SCHED __builtin_amdgcn_sched_barrier(0)
; template <class Epi, class AMap>
; __device__ __forceinline__ void gemm_phase(LAS unsigned char* lds, const AMap am, const int lda, const h16* Bt, const int ldb, const int M, const int N, const int K, const Epi& E) {
;     ...
;             PG8_LDB(B0, 0, 0); PG8_SCHED; PG8_LDA(At, 0, 0); PG8_STAGE(PG8_SA(1, 1), a1 + hstepA, voffA);
;             PG8_WAIT_L(8); PG8_BAR; PG8_WAIT_L(0); PG8_MMA(0, 0, At, B0); PG8_BAR; PG8_SCHED;
;             PG8_LDB(B1, 0, 1); PG8_STAGE(PG8_SB(0, 0), b2, voffB);
;             PG8_BAR; PG8_WAIT_L(0); PG8_MMA(0, 1, At, B1); PG8_BAR;
;             PG8_LDA(At, 0, 1); PG8_STAGE(PG8_SA(0, 0), a2, voffA);
;             PG8_BAR; PG8_WAIT_L(0); PG8_MMA(1, 0, At, B0); PG8_BAR; PG8_SCHED;
;             PG8_STAGE(PG8_SB(0, 1), b2 + hstepB, voffB);
;             PG8_WAIT_V(6); PG8_BAR; PG8_MMA(1, 1, At, B1); PG8_BAR;
;             PG8_LDB(B0, 1, 0); PG8_SCHED; PG8_LDA(At, 1, 0); PG8_STAGE(PG8_SA(0, 1), a2 + hstepA, voffA);
;             PG8_WAIT_L(8); PG8_BAR; PG8_WAIT_L(0); PG8_MMA(0, 0, At, B0); PG8_BAR; PG8_SCHED;
;             PG8_LDB(B1, 1, 1); PG8_STAGE(PG8_SB(1, 0), b3, voffB);
;             PG8_BAR; PG8_WAIT_L(0); PG8_MMA(0, 1, At, B1); PG8_BAR;
;             PG8_LDA(At, 1, 1); PG8_STAGE(PG8_SA(1, 0), a3, voffA);
;             PG8_BAR; PG8_WAIT_L(0); PG8_MMA(1, 0, At, B0); PG8_BAR; PG8_SCHED;
	v_mfma_f32_16x16x32_f16 v[62:65], v[130:133], v[162:165], v[62:65]
	v_mfma_f32_16x16x32_f16 v[58:61], v[148:151], v[162:165], v[58:61]
	v_mfma_f32_16x16x32_f16 v[46:49], v[130:133], v[170:173], v[46:49]
	v_mfma_f32_16x16x32_f16 v[42:45], v[148:151], v[170:173], v[42:45]
	v_mfma_f32_16x16x32_f16 v[30:33], v[130:133], v[178:181], v[30:33]
	v_mfma_f32_16x16x32_f16 v[26:29], v[148:151], v[178:181], v[26:29]
	v_mfma_f32_16x16x32_f16 v[14:17], v[130:133], v[186:189], v[14:17]
	v_mfma_f32_16x16x32_f16 v[10:13], v[148:151], v[186:189], v[10:13]
	v_mfma_f32_16x16x32_f16 v[62:65], v[134:137], v[166:169], v[62:65]
	v_mfma_f32_16x16x32_f16 v[58:61], v[158:161], v[166:169], v[58:61]
	v_mfma_f32_16x16x32_f16 v[46:49], v[134:137], v[174:177], v[46:49]
	v_mfma_f32_16x16x32_f16 v[42:45], v[158:161], v[174:177], v[42:45]
	v_mfma_f32_16x16x32_f16 v[30:33], v[134:137], v[182:185], v[30:33]
	v_mfma_f32_16x16x32_f16 v[26:29], v[158:161], v[182:185], v[26:29]
	v_mfma_f32_16x16x32_f16 v[14:17], v[134:137], v[190:193], v[14:17]
	v_mfma_f32_16x16x32_f16 v[10:13], v[158:161], v[190:193], v[10:13]
	v_mfma_f32_16x16x32_f16 v[54:57], v[194:197], v[162:165], v[54:57]
	v_mfma_f32_16x16x32_f16 v[50:53], v[202:205], v[162:165], v[50:53]
	v_mfma_f32_16x16x32_f16 v[38:41], v[194:197], v[170:173], v[38:41]
	v_mfma_f32_16x16x32_f16 v[34:37], v[202:205], v[170:173], v[34:37]
	v_mfma_f32_16x16x32_f16 v[22:25], v[194:197], v[178:181], v[22:25]
	v_mfma_f32_16x16x32_f16 v[18:21], v[202:205], v[178:181], v[18:21]
	v_mfma_f32_16x16x32_f16 v[6:9], v[194:197], v[186:189], v[6:9]
	v_mfma_f32_16x16x32_f16 v[2:5], v[202:205], v[186:189], v[2:5]
	v_mfma_f32_16x16x32_f16 v[54:57], v[198:201], v[166:169], v[54:57]
	v_mfma_f32_16x16x32_f16 v[50:53], v[220:223], v[166:169], v[50:53]
	v_mfma_f32_16x16x32_f16 v[38:41], v[198:201], v[174:177], v[38:41]
	v_mfma_f32_16x16x32_f16 v[34:37], v[220:223], v[174:177], v[34:37]
	v_mfma_f32_16x16x32_f16 v[22:25], v[198:201], v[182:185], v[22:25]
	v_mfma_f32_16x16x32_f16 v[18:21], v[220:223], v[182:185], v[18:21]
	v_mfma_f32_16x16x32_f16 v[6:9], v[198:201], v[190:193], v[6:9]
	v_mfma_f32_16x16x32_f16 v[2:5], v[220:223], v[190:193], v[2:5]
	s_barrier
	s_add_i32 s45, 0, 0x18000
	v_add_u32_e32 v234, s45, v155
	ds_read_b128 v[130:133], v234
	ds_read_b128 v[134:137], v234 offset:1024
	ds_read_b128 v[148:151], v234 offset:2048
	ds_read_b128 v[158:161], v234 offset:3072
	s_add_u32 s48, s48, 0x80000
	s_addc_u32 s49, s49, 0
	s_mov_b32 m0, s73
	v_lshl_add_u64 v[232:233], s[48:49], 0, v[138:139]
	ds_read_b128 v[162:165], v157 offset:32768
	ds_read_b128 v[166:169], v157 offset:33792
	ds_read_b128 v[170:173], v157 offset:34816
	ds_read_b128 v[174:177], v157 offset:35840
	ds_read_b128 v[178:181], v157 offset:36864
	ds_read_b128 v[182:185], v157 offset:37888
	ds_read_b128 v[186:189], v157 offset:38912
	ds_read_b128 v[190:193], v157 offset:39936
	global_load_lds_dwordx4 v[232:233], off
	v_lshl_add_u64 v[232:233], s[48:49], 0, v[140:141]
	s_mov_b32 m0, s74
	s_nop 0
	global_load_lds_dwordx4 v[232:233], off
	s_waitcnt lgkmcnt(11)
	s_add_i32 s48, 0, 0x1c000
	s_add_i32 s45, s45, s72
	v_add_u32_e32 v214, s48, v155
	v_lshl_add_u64 v[152:153], v[152:153], 0, s[92:93]
	s_mov_b32 m0, s45
	ds_read_b128 v[194:197], v214
	ds_read_b128 v[198:201], v214 offset:1024
	ds_read_b128 v[202:205], v214 offset:2048
	ds_read_b128 v[220:223], v214 offset:3072
	s_waitcnt vmcnt(8) lgkmcnt(0)
	s_barrier
	v_mfma_f32_16x16x32_f16 v[126:129], v[130:133], v[162:165], v[126:129]
	v_mfma_f32_16x16x32_f16 v[122:125], v[148:151], v[162:165], v[122:125]
	v_mfma_f32_16x16x32_f16 v[110:113], v[130:133], v[170:173], v[110:113]
	v_mfma_f32_16x16x32_f16 v[106:109], v[148:151], v[170:173], v[106:109]
	v_mfma_f32_16x16x32_f16 v[94:97], v[130:133], v[178:181], v[94:97]
	v_mfma_f32_16x16x32_f16 v[90:93], v[148:151], v[178:181], v[90:93]
	v_mfma_f32_16x16x32_f16 v[78:81], v[130:133], v[186:189], v[78:81]
	v_mfma_f32_16x16x32_f16 v[74:77], v[148:151], v[186:189], v[74:77]
	v_mfma_f32_16x16x32_f16 v[126:129], v[134:137], v[166:169], v[126:129]
	v_mfma_f32_16x16x32_f16 v[122:125], v[158:161], v[166:169], v[122:125]
	v_mfma_f32_16x16x32_f16 v[110:113], v[134:137], v[174:177], v[110:113]
	v_mfma_f32_16x16x32_f16 v[106:109], v[158:161], v[174:177], v[106:109]
	v_mfma_f32_16x16x32_f16 v[94:97], v[134:137], v[182:185], v[94:97]
	v_mfma_f32_16x16x32_f16 v[90:93], v[158:161], v[182:185], v[90:93]
	v_mfma_f32_16x16x32_f16 v[78:81], v[134:137], v[190:193], v[78:81]
	v_mfma_f32_16x16x32_f16 v[74:77], v[158:161], v[190:193], v[74:77]
	v_mfma_f32_16x16x32_f16 v[118:121], v[194:197], v[162:165], v[118:121]
	v_mfma_f32_16x16x32_f16 v[114:117], v[202:205], v[162:165], v[114:117]
	v_mfma_f32_16x16x32_f16 v[102:105], v[194:197], v[170:173], v[102:105]
	v_mfma_f32_16x16x32_f16 v[98:101], v[202:205], v[170:173], v[98:101]
	v_mfma_f32_16x16x32_f16 v[86:89], v[194:197], v[178:181], v[86:89]
	v_mfma_f32_16x16x32_f16 v[82:85], v[202:205], v[178:181], v[82:85]
	v_mfma_f32_16x16x32_f16 v[70:73], v[194:197], v[186:189], v[70:73]
	v_mfma_f32_16x16x32_f16 v[66:69], v[202:205], v[186:189], v[66:69]
	v_mfma_f32_16x16x32_f16 v[118:121], v[198:201], v[166:169], v[118:121]
	v_mfma_f32_16x16x32_f16 v[114:117], v[220:223], v[166:169], v[114:117]
	v_mfma_f32_16x16x32_f16 v[102:105], v[198:201], v[174:177], v[102:105]
	v_mfma_f32_16x16x32_f16 v[98:101], v[220:223], v[174:177], v[98:101]
	v_mfma_f32_16x16x32_f16 v[86:89], v[198:201], v[182:185], v[86:89]
	v_mfma_f32_16x16x32_f16 v[82:85], v[220:223], v[182:185], v[82:85]
	v_mfma_f32_16x16x32_f16 v[70:73], v[198:201], v[190:193], v[70:73]
	v_mfma_f32_16x16x32_f16 v[66:69], v[220:223], v[190:193], v[66:69]
	s_barrier
; #define PG8_STAGE(bufoff, gbase, voff) do { _Pragma("unroll") for (int _i = 0; _i < 2; ++_i) \
;         __builtin_amdgcn_global_load_lds((const unsigned*)((const char*)(gbase) + (voff)[_i]), (LAS unsigned*)(lds + (bufoff) + ldsw + _i * 8192), 16, 0, 0); } while (0)
; #define PG8_LDA(dst, b, h) do { _Pragma("unroll") for (int m = 0; m < 4; ++m) _Pragma("unroll") for (int k = 0; k < 2; ++k) dst[m][k] = *(const LAS h16x8*)(lds + PG8_SA(b, h) + aoff + m * 2048 + k * 1024); } while (0)
; #define PG8_LDB(dst, b, h) do { _Pragma("unroll") for (int n = 0; n < 2; ++n) _Pragma("unroll") for (int k = 0; k < 2; ++k) dst[n][k] = *(const LAS h16x8*)(lds + PG8_SB(b, h) + boff + n * 2048 + k * 1024); } while (0)
; #define PG8_MMA(ai, bj, At, Bt_) do { __builtin_amdgcn_s_setprio(1); _Pragma("unroll") for (int m = 0; m < 4; ++m) _Pragma("unroll") for (int n = 0; n < 2; ++n) _Pragma("unroll") for (int k = 0; k < 2; ++k) \
;         acc[ai][bj][m][n] = __builtin_amdgcn_mfma_f32_16x16x32_f16(Bt_[n][k], At[m][k], acc[ai][bj][m][n], 0, 0, 0); __builtin_amdgcn_s_setprio(0); } while (0)
; #define PG8_WAIT_V(n) asm volatile("s_waitcnt vmcnt(" #n ")" ::: "memory")
; #define PG8_WAIT_L(n) asm volatile("s_waitcnt lgkmcnt(" #n ")" ::: "memory")
; #define PG8_BAR __builtin_amdgcn_s_barrier()
; #define PG8_SCHED __builtin_amdgcn_sched_barrier(0)
; template <class Epi, class AMap>
; __device__ __forceinline__ void gemm_phase(LAS unsigned char* lds, const AMap am, const int lda, const h16* Bt, const int ldb, const int M, const int N, const int K, const Epi& E) {
;     ...
;             PG8_LDB(B1, 1, 1); PG8_STAGE(PG8_SB(1, 0), b3, voffB);
;             PG8_BAR; PG8_WAIT_L(0); PG8_MMA(0, 1, At, B1); PG8_BAR;
;             PG8_LDA(At, 1, 1); PG8_STAGE(PG8_SA(1, 0), a3, voffA);
;             PG8_BAR; PG8_WAIT_L(0); PG8_MMA(1, 0, At, B0); PG8_BAR; PG8_SCHED;
;             PG8_STAGE(PG8_SB(1, 1), b3 + hstepB, voffB);
;             PG8_WAIT_V(6); PG8_BAR; PG8_MMA(1, 1, At, B1); PG8_BAR;
;         }
;         E(acc, cur, wr, wc, fr, fq);
;         if (!has_next) break;
;     __device__ __forceinline__ void operator()(const f32x4 (&acc)[2][2][4][2], const Unit& u, int wr, int wc, int fr, int fq) const {
;     ...
;         const int mode = u.pn == 24 ? 1 : (u.pn == 26 ? 2 : 0);
	global_load_lds_dwordx4 v[152:153], off
	v_lshl_add_u64 v[152:153], v[206:207], 0, s[92:93]
	s_add_i32 m0, s45, 0x2000
	s_nop 0
	global_load_lds_dwordx4 v[152:153], off
	s_mov_b32 m0, s75
	v_lshl_add_u64 v[152:153], v[212:213], 0, s[92:93]
	ds_read_b128 v[162:165], v157 offset:49152
	ds_read_b128 v[166:169], v157 offset:50176
	ds_read_b128 v[170:173], v157 offset:51200
	ds_read_b128 v[174:177], v157 offset:52224
	ds_read_b128 v[178:181], v157 offset:53248
	ds_read_b128 v[182:185], v157 offset:54272
	ds_read_b128 v[186:189], v157 offset:55296
	ds_read_b128 v[190:193], v157 offset:56320
	global_load_lds_dwordx4 v[152:153], off
	v_lshl_add_u64 v[152:153], v[224:225], 0, s[92:93]
	s_mov_b32 m0, s76
	s_nop 0
	global_load_lds_dwordx4 v[152:153], off
	s_add_u32 s40, s40, 0x80080
	s_addc_u32 s41, s41, 0
	s_add_i32 s45, s48, s72
	v_lshl_add_u64 v[232:233], s[40:41], 0, v[0:1]
	s_mov_b32 m0, s45
	s_nop 0
	global_load_lds_dwordx4 v[232:233], off
	v_lshl_add_u64 v[232:233], s[40:41], 0, v[142:143]
	s_add_i32 m0, s45, 0x2000
	s_nop 0
	global_load_lds_dwordx4 v[232:233], off
	s_waitcnt vmcnt(8) lgkmcnt(0)
	s_barrier
	v_mfma_f32_16x16x32_f16 v[62:65], v[130:133], v[162:165], v[62:65]
	v_mfma_f32_16x16x32_f16 v[58:61], v[148:151], v[162:165], v[58:61]
	v_mfma_f32_16x16x32_f16 v[46:49], v[130:133], v[170:173], v[46:49]
	v_mfma_f32_16x16x32_f16 v[42:45], v[148:151], v[170:173], v[42:45]
	v_mfma_f32_16x16x32_f16 v[30:33], v[130:133], v[178:181], v[30:33]
	v_mfma_f32_16x16x32_f16 v[26:29], v[148:151], v[178:181], v[26:29]
	v_mfma_f32_16x16x32_f16 v[14:17], v[130:133], v[186:189], v[14:17]
	v_mfma_f32_16x16x32_f16 v[10:13], v[148:151], v[186:189], v[10:13]
	v_mfma_f32_16x16x32_f16 v[62:65], v[134:137], v[166:169], v[62:65]
	v_mfma_f32_16x16x32_f16 v[58:61], v[158:161], v[166:169], v[58:61]
	v_mfma_f32_16x16x32_f16 v[46:49], v[134:137], v[174:177], v[46:49]
	v_mfma_f32_16x16x32_f16 v[42:45], v[158:161], v[174:177], v[42:45]
	v_mfma_f32_16x16x32_f16 v[30:33], v[134:137], v[182:185], v[30:33]
	v_mfma_f32_16x16x32_f16 v[26:29], v[158:161], v[182:185], v[26:29]
	v_mfma_f32_16x16x32_f16 v[14:17], v[134:137], v[190:193], v[14:17]
	v_mfma_f32_16x16x32_f16 v[10:13], v[158:161], v[190:193], v[10:13]
	v_mfma_f32_16x16x32_f16 v[54:57], v[194:197], v[162:165], v[54:57]
	v_mfma_f32_16x16x32_f16 v[50:53], v[202:205], v[162:165], v[50:53]
	v_mfma_f32_16x16x32_f16 v[38:41], v[194:197], v[170:173], v[38:41]
	v_mfma_f32_16x16x32_f16 v[34:37], v[202:205], v[170:173], v[34:37]
	v_mfma_f32_16x16x32_f16 v[22:25], v[194:197], v[178:181], v[22:25]
	v_mfma_f32_16x16x32_f16 v[18:21], v[202:205], v[178:181], v[18:21]
	v_mfma_f32_16x16x32_f16 v[6:9], v[194:197], v[186:189], v[6:9]
	v_mfma_f32_16x16x32_f16 v[2:5], v[202:205], v[186:189], v[2:5]
	v_mfma_f32_16x16x32_f16 v[54:57], v[198:201], v[166:169], v[54:57]
	v_mfma_f32_16x16x32_f16 v[50:53], v[220:223], v[166:169], v[50:53]
	v_mfma_f32_16x16x32_f16 v[38:41], v[198:201], v[174:177], v[38:41]
	v_mfma_f32_16x16x32_f16 v[34:37], v[220:223], v[174:177], v[34:37]
	v_mfma_f32_16x16x32_f16 v[22:25], v[198:201], v[182:185], v[22:25]
	v_mfma_f32_16x16x32_f16 v[18:21], v[220:223], v[182:185], v[18:21]
	v_mfma_f32_16x16x32_f16 v[6:9], v[198:201], v[190:193], v[6:9]
	v_mfma_f32_16x16x32_f16 v[2:5], v[220:223], v[190:193], v[2:5]
	s_add_i32 s43, s43, 2
	s_add_u32 s0, s0, 0x100
	s_addc_u32 s1, s1, 0
	s_add_u32 s21, s21, 0x100
	s_addc_u32 s35, s35, 0
	s_cmp_gt_u32 s43, 29
	s_barrier
	s_cbranch_scc0 .LBB0_799
	s_cmp_eq_u32 s22, 26
	s_cselect_b32 s0, 2, 0
	s_cmp_lg_u32 s22, 24
	s_cselect_b32 s43, s0, 1
	s_cmp_gt_i32 s43, 1
	s_mov_b64 s[0:1], -1
	s_cbranch_scc0 .LBB0_802
; __device__ __forceinline__ float sigmoidf_(float x) { return 1.0f / (1.0f + __expf(-x)); }
;     __device__ __forceinline__ void operator()(const f32x4 (&acc)[2][2][4][2], const Unit& u, int wr, int wc, int fr, int fq) const {
;     ...
;                     if (mode == 1) {
; #pragma unroll
;                         for (int j = 0; j < 4; ++j) { v0[j] = 1.0f - 2.0f / (1.0f + __expf(2.0f * v0[j])); v1[j] = 1.0f - 2.0f / (1.0f + __expf(2.0f * v1[j])); } }
;                     else if (mode == 2) {
; #pragma unroll
;                         for (int j = 0; j < 4; ++j) { v0[j] = sigmoidf_(v0[j]); v1[j] = sigmoidf_(v1[j]); } }
;                     const u32x4 pk = pack8(v0, v1);
	v_mul_f32_e32 v132, 0xbfb8aa3b, v123
	v_mul_f32_e32 v133, 0xbfb8aa3b, v124
	v_exp_f32_e32 v135, v132
	v_mul_f32_e32 v132, 0xbfb8aa3b, v128
	v_exp_f32_e32 v136, v133
	v_mul_f32_e32 v133, 0xbfb8aa3b, v129
	v_exp_f32_e32 v132, v132
	v_exp_f32_e32 v133, v133
	v_mul_f32_e32 v131, 0xbfb8aa3b, v122
	v_mul_f32_e32 v130, 0xbfb8aa3b, v126
	v_exp_f32_e32 v134, v131
	v_pk_add_f32 v[132:133], v[132:133], 1.0 op_sel_hi:[1,0]
	v_mul_f32_e32 v131, 0xbfb8aa3b, v127
	v_div_scale_f32 v137, s[0:1], v133, v133, 1.0
	v_rcp_f32_e32 v148, v137
	v_exp_f32_e32 v130, v130
	v_exp_f32_e32 v131, v131
	v_pk_add_f32 v[134:135], v[134:135], 1.0 op_sel_hi:[1,0]
	v_fma_f32 v149, -v137, v148, 1.0
	v_fmac_f32_e32 v148, v149, v148
	v_div_scale_f32 v149, vcc, 1.0, v133, 1.0
	v_mul_f32_e32 v150, v149, v148
	v_fma_f32 v151, -v137, v150, v149
	v_fmac_f32_e32 v150, v151, v148
	v_fma_f32 v137, -v137, v150, v149
	v_div_fmas_f32 v137, v137, v148, v150
	v_div_fixup_f32 v133, v137, v133, 1.0
	v_div_scale_f32 v137, s[0:1], v132, v132, 1.0
	v_rcp_f32_e32 v148, v137
	v_pk_add_f32 v[130:131], v[130:131], 1.0 op_sel_hi:[1,0]
	v_fma_f32 v149, -v137, v148, 1.0
	v_fmac_f32_e32 v148, v149, v148
	v_div_scale_f32 v149, vcc, 1.0, v132, 1.0
	v_mul_f32_e32 v150, v149, v148
	v_fma_f32 v151, -v137, v150, v149
	v_fmac_f32_e32 v150, v151, v148
	v_fma_f32 v137, -v137, v150, v149
	v_div_fmas_f32 v137, v137, v148, v150
	v_div_fixup_f32 v132, v137, v132, 1.0
	v_div_scale_f32 v137, s[0:1], v131, v131, 1.0
	v_rcp_f32_e32 v148, v137
	s_nop 0
	v_fma_f32 v149, -v137, v148, 1.0
	v_fmac_f32_e32 v148, v149, v148
	v_div_scale_f32 v149, vcc, 1.0, v131, 1.0
	v_mul_f32_e32 v150, v149, v148
	v_fma_f32 v151, -v137, v150, v149
	v_fmac_f32_e32 v150, v151, v148
	v_fma_f32 v137, -v137, v150, v149
	v_div_fmas_f32 v137, v137, v148, v150
	v_div_fixup_f32 v131, v137, v131, 1.0
	v_div_scale_f32 v137, s[0:1], v130, v130, 1.0
	v_rcp_f32_e32 v148, v137
	s_nop 0
	v_fma_f32 v149, -v137, v148, 1.0
	v_fmac_f32_e32 v148, v149, v148
	v_div_scale_f32 v149, vcc, 1.0, v130, 1.0
	v_mul_f32_e32 v150, v149, v148
	v_fma_f32 v151, -v137, v150, v149
	v_fmac_f32_e32 v150, v151, v148
	v_fma_f32 v137, -v137, v150, v149
	v_div_fmas_f32 v137, v137, v148, v150
	v_div_fixup_f32 v130, v137, v130, 1.0
	v_mul_f32_e32 v137, 0xbfb8aa3b, v125
	v_exp_f32_e32 v137, v137
	s_nop 0
	v_pk_add_f32 v[136:137], v[136:137], 1.0 op_sel_hi:[1,0]
	s_nop 0
	v_div_scale_f32 v148, s[0:1], v137, v137, 1.0
	v_rcp_f32_e32 v149, v148
	s_nop 0
	v_fma_f32 v150, -v148, v149, 1.0
	v_fmac_f32_e32 v149, v150, v149
	v_div_scale_f32 v150, vcc, 1.0, v137, 1.0
	v_mul_f32_e32 v151, v150, v149
	v_fma_f32 v152, -v148, v151, v150
	v_fmac_f32_e32 v151, v152, v149
	v_fma_f32 v148, -v148, v151, v150
	v_div_fmas_f32 v148, v148, v149, v151
	v_div_fixup_f32 v137, v148, v137, 1.0
	v_div_scale_f32 v148, s[0:1], v136, v136, 1.0
	v_rcp_f32_e32 v149, v148
	s_nop 0
	v_fma_f32 v150, -v148, v149, 1.0
	v_fmac_f32_e32 v149, v150, v149
	v_div_scale_f32 v150, vcc, 1.0, v136, 1.0
	v_mul_f32_e32 v151, v150, v149
	v_fma_f32 v152, -v148, v151, v150
	v_fmac_f32_e32 v151, v152, v149
	v_fma_f32 v148, -v148, v151, v150
	v_div_fmas_f32 v148, v148, v149, v151
	v_div_fixup_f32 v136, v148, v136, 1.0
	v_div_scale_f32 v148, s[0:1], v135, v135, 1.0
	v_rcp_f32_e32 v149, v148
	s_nop 0
	v_fma_f32 v150, -v148, v149, 1.0
	v_fmac_f32_e32 v149, v150, v149
	v_div_scale_f32 v150, vcc, 1.0, v135, 1.0
	v_mul_f32_e32 v151, v150, v149
	v_fma_f32 v152, -v148, v151, v150
	v_fmac_f32_e32 v151, v152, v149
	v_fma_f32 v148, -v148, v151, v150
	v_div_fmas_f32 v148, v148, v149, v151
	v_div_fixup_f32 v135, v148, v135, 1.0
	v_div_scale_f32 v148, s[0:1], v134, v134, 1.0
	v_rcp_f32_e32 v149, v148
	s_mov_b64 s[0:1], 0
	v_fma_f32 v150, -v148, v149, 1.0
	v_fmac_f32_e32 v149, v150, v149
	v_div_scale_f32 v150, vcc, 1.0, v134, 1.0
	v_mul_f32_e32 v151, v150, v149
	v_fma_f32 v152, -v148, v151, v150
	v_fmac_f32_e32 v151, v152, v149
	v_fma_f32 v148, -v148, v151, v150
	v_div_fmas_f32 v148, v148, v149, v151
	v_div_fixup_f32 v134, v148, v134, 1.0
